# GEMM A operands (hidden, h2, normed H) also stored K32-blocked by their producers (FFN-in / out-proj / FFN-out epilogues, RMSNorm) so A-tile DMAs fetch full 128-byte lines
# speedup vs baseline: 1.1215x; 1.0259x over previous
; DI int tid_() { int t = threadIdx.x; asm volatile("" : "+v"(t)); return t; }
; DI unsigned pk2(float lo, float hi) { f32x2 v = {lo, hi}; bf16x2_t r = __builtin_convertvector(v, bf16x2_t); return __builtin_bit_cast(unsigned, r); }
; DI void phase_rmsnorm(const float* X, const float* g, bf16_t* H) {
;     const int lane = tid_() & 63, wave = __builtin_amdgcn_readfirstlane(tid_() >> 6);
;     for (int row = blockIdx.x * 4 + wave; row < NTOK; row += gridDim.x * 4) {
;         const float* xr = X + (size_t)row * DM;
;         f32x4 v[4]; float ss = 0.f;
; #pragma unroll
;         for (int i = 0; i < 4; ++i) { v[i] = *(const f32x4*)(xr + i * 256 + lane * 4); ss += v[i][0] * v[i][0] + v[i][1] * v[i][1] + v[i][2] * v[i][2] + v[i][3] * v[i][3]; }
; #pragma unroll
;         for (int o = 32; o >= 1; o >>= 1) ss += __shfl_xor(ss, o);
;         const float r = rsqrtf(ss * (1.f / DM) + 1e-6f);
; #pragma unroll
;         for (int i = 0; i < 4; ++i) {
;             const f32x4 gg = *(const f32x4*)(g + i * 256 + lane * 4);
;             u32x2 o2; o2[0] = pk2(v[i][0] * r * gg[0], v[i][1] * r * gg[1]); o2[1] = pk2(v[i][2] * r * gg[2], v[i][3] * r * gg[3]);
;             *(u32x2*)(H + (size_t)row * DM + i * 256 + lane * 4) = o2;
;         }
;     }
; }
.LBB0_139:
	v_mov_b32_e32 v2, v210
	v_mov_b32_e32 v1, v210
	s_lshl_b32 s1, s2, 2
	v_readfirstlane_b32 s0, v1
	s_ashr_i32 s0, s0, 6
	s_add_i32 s0, s0, s1
	s_cmpk_gt_i32 s0, 0x7fff
	v_mbcnt_lo_u32_b32 v1, -1, 0
	s_cbranch_scc1 .LBB0_142
	v_lshlrev_b32_e32 v2, 2, v2
	v_and_b32_e32 v8, 0xfc, v2
	v_readlane_b32 s8, v251, 18
	v_mbcnt_hi_u32_b32 v13, -1, v1
	v_lshlrev_b32_e32 v6, 2, v8
	v_mov_b32_e32 v7, 0
	v_readlane_b32 s9, v251, 19
	v_readlane_b32 s10, v251, 20
	v_readlane_b32 s11, v251, 21
	v_and_b32_e32 v4, 64, v13
	v_lshl_add_u64 v[2:3], s[8:9], 0, v[6:7]
	v_add_u32_e32 v14, 64, v4
	v_lshl_add_u64 v[4:5], s[10:11], 0, v[6:7]
	v_lshrrev_b32_e32 v6, 5, v8
	v_lshlrev_b32_e32 v6, 21, v6
	v_and_b32_e32 v36, 0x1c, v8
	v_lshl_or_b32 v6, v36, 1, v6
	s_mov_b32 s98, 0x1000000
	s_mov_b32 s99, 0
	v_xor_b32_e32 v8, 32, v13
	v_cmp_lt_i32_e32 vcc, v8, v14
	v_xor_b32_e32 v9, 16, v13
	v_xor_b32_e32 v10, 8, v13
	v_cndmask_b32_e32 v8, v13, v8, vcc
	v_cmp_lt_i32_e32 vcc, v9, v14
	v_xor_b32_e32 v11, 4, v13
	v_xor_b32_e32 v12, 2, v13
	v_cndmask_b32_e32 v9, v13, v9, vcc
	v_cmp_lt_i32_e32 vcc, v10, v14
	v_xor_b32_e32 v15, 1, v13
	v_lshl_add_u64 v[6:7], s[78:79], 0, v[6:7]
	v_cndmask_b32_e32 v10, v13, v10, vcc
	v_cmp_lt_i32_e32 vcc, v11, v14
	s_lshl_b32 s6, s42, 2
	v_lshlrev_b32_e32 v8, 2, v8
	v_cndmask_b32_e32 v11, v13, v11, vcc
	v_cmp_lt_i32_e32 vcc, v12, v14
	v_lshlrev_b32_e32 v9, 2, v9
	v_lshlrev_b32_e32 v10, 2, v10
	v_cndmask_b32_e32 v12, v13, v12, vcc
	v_cmp_lt_i32_e32 vcc, v15, v14
	v_lshlrev_b32_e32 v11, 2, v11
	v_lshlrev_b32_e32 v12, 2, v12
	v_cndmask_b32_e32 v13, v13, v15, vcc
	v_lshlrev_b32_e32 v13, 2, v13
	v_mov_b32_e32 v14, 0x358637bd
	s_mov_b32 s7, 0x800000
	v_readlane_b32 s12, v251, 22
	v_readlane_b32 s13, v251, 23
	v_readlane_b32 s14, v251, 24
	v_readlane_b32 s15, v251, 25
	v_readlane_b32 s16, v251, 26
	v_readlane_b32 s17, v251, 27
	v_readlane_b32 s18, v251, 28
	v_readlane_b32 s19, v251, 29
	v_readlane_b32 s20, v251, 30
	v_readlane_b32 s21, v251, 31
	v_readlane_b32 s22, v251, 32
	v_readlane_b32 s23, v251, 33
.LBB0_141:
	s_ashr_i32 s1, s0, 31
	s_lshl_b64 s[8:9], s[0:1], 12
	v_lshl_add_u64 v[28:29], v[2:3], 0, s[8:9]
	global_load_dwordx4 v[16:19], v[28:29], off
	global_load_dwordx4 v[20:23], v[28:29], off offset:1024
	global_load_dwordx4 v[24:27], v[28:29], off offset:2048
	s_nop 0
	global_load_dwordx4 v[28:31], v[28:29], off offset:3072
	s_nop 0
	global_load_dwordx4 v[32:35], v[4:5], off
	s_lshl_b64 s[8:9], s[0:1], 6
	s_add_i32 s0, s0, s6
	s_cmp_lt_i32 s0, 0x8000
	s_waitcnt vmcnt(4)
	v_mov_b32_e32 v38, v17
	s_waitcnt vmcnt(3)
	v_mov_b32_e32 v39, v21
	v_mov_b32_e32 v36, v16
	v_mov_b32_e32 v37, v20
	s_waitcnt vmcnt(2)
	v_mov_b32_e32 v46, v25
	s_waitcnt vmcnt(1)
	v_mov_b32_e32 v47, v29
	v_pk_mul_f32 v[38:39], v[38:39], v[38:39]
	v_mov_b32_e32 v40, v18
	v_mov_b32_e32 v41, v22
	v_mov_b32_e32 v44, v24
	v_mov_b32_e32 v45, v28
	v_pk_mul_f32 v[46:47], v[46:47], v[46:47]
	v_pk_fma_f32 v[36:37], v[36:37], v[36:37], v[38:39]
	v_mov_b32_e32 v42, v19
	v_mov_b32_e32 v43, v23
	v_mov_b32_e32 v48, v26
	v_mov_b32_e32 v49, v30
	v_pk_fma_f32 v[38:39], v[44:45], v[44:45], v[46:47]
	v_pk_fma_f32 v[36:37], v[40:41], v[40:41], v[36:37]
	v_mov_b32_e32 v50, v27
	v_mov_b32_e32 v51, v31
	v_pk_fma_f32 v[38:39], v[48:49], v[48:49], v[38:39]
	v_pk_fma_f32 v[36:37], v[42:43], v[42:43], v[36:37]
	v_pk_fma_f32 v[38:39], v[50:51], v[50:51], v[38:39]
	v_add_f32_e32 v15, v36, v37
	v_add_f32_e32 v15, v15, v38
	v_add_f32_e32 v15, v15, v39
	ds_bpermute_b32 v36, v8, v15
	s_waitcnt lgkmcnt(0)
	v_add_f32_e32 v15, v15, v36
	ds_bpermute_b32 v36, v9, v15
	s_waitcnt lgkmcnt(0)
	v_add_f32_e32 v15, v15, v36
	ds_bpermute_b32 v36, v10, v15
	s_waitcnt lgkmcnt(0)
	v_add_f32_e32 v15, v15, v36
	ds_bpermute_b32 v36, v11, v15
	s_waitcnt lgkmcnt(0)
	v_add_f32_e32 v15, v15, v36
	ds_bpermute_b32 v36, v12, v15
	s_waitcnt lgkmcnt(0)
	v_add_f32_e32 v15, v15, v36
	ds_bpermute_b32 v36, v13, v15
	s_waitcnt lgkmcnt(0)
	v_add_f32_e32 v15, v15, v36
	v_fmamk_f32 v15, v15, 0x3a800000, v14
	v_mul_f32_e32 v36, 0x4b800000, v15
	v_cmp_gt_f32_e32 vcc, s7, v15
	s_nop 1
	v_cndmask_b32_e32 v15, v15, v36, vcc
	v_rsq_f32_e32 v15, v15
	v_lshl_add_u64 v[36:37], v[6:7], 0, s[8:9]
	v_mul_f32_e32 v38, 0x45800000, v15
	v_cndmask_b32_e32 v38, v15, v38, vcc
	v_pk_mul_f32 v[16:17], v[16:17], v[38:39] op_sel_hi:[1,0]
	v_pk_mul_f32 v[18:19], v[18:19], v[38:39] op_sel_hi:[1,0]
	s_waitcnt vmcnt(0)
	v_pk_mul_f32 v[16:17], v[32:33], v[16:17]
	v_pk_mul_f32 v[18:19], v[34:35], v[18:19]
	v_cvt_pk_bf16_f32 v16, v16, v17
	v_cvt_pk_bf16_f32 v17, v18, v19
	global_store_dwordx2 v[36:37], v[16:17], off
	global_load_dwordx4 v[16:19], v[4:5], off offset:1024
	v_pk_mul_f32 v[20:21], v[20:21], v[38:39] op_sel_hi:[1,0]
	v_pk_mul_f32 v[22:23], v[22:23], v[38:39] op_sel_hi:[1,0]
	s_waitcnt vmcnt(0)
	v_pk_mul_f32 v[16:17], v[16:17], v[20:21]
	v_pk_mul_f32 v[18:19], v[18:19], v[22:23]
	v_cvt_pk_bf16_f32 v16, v16, v17
	v_cvt_pk_bf16_f32 v17, v18, v19
	v_lshl_add_u64 v[36:37], v[36:37], 0, s[98:99]
	global_store_dwordx2 v[36:37], v[16:17], off
	global_load_dwordx4 v[16:19], v[4:5], off offset:2048
	v_pk_mul_f32 v[20:21], v[24:25], v[38:39] op_sel_hi:[1,0]
	v_pk_mul_f32 v[22:23], v[26:27], v[38:39] op_sel_hi:[1,0]
	s_waitcnt vmcnt(0)
	v_pk_mul_f32 v[16:17], v[16:17], v[20:21]
	v_pk_mul_f32 v[18:19], v[18:19], v[22:23]
	v_cvt_pk_bf16_f32 v16, v16, v17
	v_cvt_pk_bf16_f32 v17, v18, v19
	v_lshl_add_u64 v[36:37], v[36:37], 0, s[98:99]
	global_store_dwordx2 v[36:37], v[16:17], off
	global_load_dwordx4 v[16:19], v[4:5], off offset:3072
	v_pk_mul_f32 v[20:21], v[28:29], v[38:39] op_sel_hi:[1,0]
	v_pk_mul_f32 v[22:23], v[30:31], v[38:39] op_sel_hi:[1,0]
	s_waitcnt vmcnt(0)
	v_pk_mul_f32 v[16:17], v[16:17], v[20:21]
	v_pk_mul_f32 v[18:19], v[18:19], v[22:23]
	v_cvt_pk_bf16_f32 v16, v16, v17
	v_cvt_pk_bf16_f32 v17, v18, v19
	v_lshl_add_u64 v[36:37], v[36:37], 0, s[98:99]
	global_store_dwordx2 v[36:37], v[16:17], off
	s_cbranch_scc1 .LBB0_141

; DI f32x4 mfma(bf16x8 a, bf16x8 b, f32x4 c) { return __builtin_amdgcn_mfma_f32_16x16x32_bf16(a, b, c, 0, 0, 0); }
; #define G_LOAD(PA, PB, STEP) do { _Pragma("unroll") for (int i_ = 0; i_ < 2; ++i_) ra[i_] = *(const u32x4*)((PA) + (size_t)(64 * i_) * K + (STEP) * 32); \
;         _Pragma("unroll") for (int i_ = 0; i_ < 4; ++i_) rb[i_] = *(const u32x4*)((PB) + (size_t)(64 * i_) * K + (STEP) * 32); } while (0)
; #define G_STORE(BUF) do { _Pragma("unroll") for (int i_ = 0; i_ < 2; ++i_) *(u32x4*)(sA + (BUF) * 128 * 40 + (lrow + 64 * i_) * 40 + lcc * 8) = ra[i_]; \
;         _Pragma("unroll") for (int i_ = 0; i_ < 4; ++i_) *(u32x4*)(sB + (BUF) * 256 * 40 + (lrow + 64 * i_) * 40 + lcc * 8) = rb[i_]; } while (0)
; template <int EPI> ...
;     ...
;     const int idx0 = blockIdx.x >> 3;
;     if (idx0 < perX) {
;         int mt0, nt0; tile_of(idx0, mt0, nt0);
;         const bf16_t* A0 = A + (size_t)(mt0 * 128 + lrow) * K + lcc * 8;
;         const bf16_t* B0 = Bt + (size_t)(nt0 * 256 + lrowp) * K + lcc * 8;
;         G_LOAD(A0, B0, 0);
;         G_STORE(0);
;         G_LOAD(A0, B0, 1);
;         __syncthreads();
;     }
;     ...
;         for (int kt = 0; kt < nk; ++kt) {
;             const int buf = kt & 1;
;             const bf16_t* a_ = sA + buf * 128 * 40 + (wr * 64 + fr) * 40 + fq * 8;
;             const bf16_t* b_ = sB + buf * 256 * 40 + (wc * 128 + fr) * 40 + fq * 8;
;             bf16x8 af[4];
; #pragma unroll
;             for (int i = 0; i < 4; ++i) af[i] = *(const bf16x8*)(a_ + i * 16 * 40);
; #pragma unroll
;             for (int jh = 0; jh < 2; ++jh) {
;                 bf16x8 bfr[4];
; #pragma unroll
;                 for (int j = 0; j < 4; ++j) bfr[j] = *(const bf16x8*)(b_ + (jh * 4 + j) * 16 * 40);
; #pragma unroll
;                 for (int i = 0; i < 4; ++i)
; #pragma unroll
;                     for (int j = 0; j < 4; ++j) acc[i][jh * 4 + j] = mfma(bfr[j], af[i], acc[i][jh * 4 + j]);
;             }
;             G_STORE(buf ^ 1);
;             {
;                 const bool cur = kt + 2 < nk;
;                 const bf16_t* pa = cur ? Ag : An; const bf16_t* pb = cur ? Bg : Bn;
;                 const int st = cur ? kt + 2 : kt + 2 - nk;
;                 G_LOAD(pa, pb, st);
;             }
.LBB0_162:
	v_readlane_b32 s9, v253, 4
	v_readlane_b32 s12, v253, 6
	v_readlane_b32 s13, v253, 5
	s_nop 3
	s_cmp_eq_u32 s13, 0
	s_cbranch_scc1 .Lg162_entry
	v_and_b32_e32 v8, 63, v210
	v_lshrrev_b32_e32 v9, 6, v210
	s_nop 0
	v_readfirstlane_b32 s13, v9
	v_lshrrev_b32_e32 v9, 4, v8
	v_sub_u32_e32 v10, 0, v9
	v_and_b32_e32 v10, 3, v10
	v_and_b32_e32 v11, 3, v8
	v_xor_b32_e32 v11, v11, v10
	v_lshrrev_b32_e32 v12, 2, v8
	v_lshlrev_b32_e32 v0, 6, v12
	v_lshl_add_u32 v0, v11, 4, v0
	s_lshl_b32 vcc_lo, s13, 11
	v_add_u32_e32 v0, vcc_lo, v0
	v_add_u32_e32 v0, 0x1000, v0
	v_add_u32_e32 v1, 0x0, v0
	v_and_b32_e32 v13, 3, v12
	v_lshl_add_u32 v13, v9, 3, v13
	v_lshlrev_b32_e32 v2, 6, v13
	v_lshl_add_u32 v2, v11, 4, v2
	s_lshl_b32 vcc_lo, s13, 12
	v_add_u32_e32 v2, vcc_lo, v2
	v_add_u32_e32 v2, 0x800, v2
	v_add_u32_e32 v3, 0xfffffd00, v2
	v_add_u32_e32 v4, 0x1000, v2
	v_add_u32_e32 v5, 0xd00, v2
	v_and_b32_e32 v10, 15, v8
	v_lshrrev_b32_e32 v11, 2, v10
	v_sub_u32_e32 v11, 0, v11
	v_and_b32_e32 v11, 3, v11
	v_xor_b32_e32 v11, v9, v11
	v_lshlrev_b32_e32 v6, 6, v10
	v_lshl_add_u32 v6, v11, 4, v6
	s_lshr_b32 vcc_lo, s13, 1
	s_mul_i32 vcc_lo, vcc_lo, 0x3000
	s_and_b32 vcc_hi, s13, 1
	s_mul_i32 vcc_hi, vcc_hi, 0x3000
	s_add_u32 vcc_hi, vcc_hi, 0x800
	v_add_u32_e32 v7, vcc_hi, v6
	v_add_u32_e32 v6, vcc_lo, v6
	s_mul_i32 s12, s13, 0x1800
	v_writelane_b32 v253, s12, 6
	v_writelane_b32 v253, 0, 5
	v_readlane_b32 vcc_lo, v253, 0
	v_readlane_b32 vcc_hi, v253, 1
	s_lshl_b32 s13, s6, 13
	s_nop 1
	s_add_u32 s98, vcc_lo, s13
	s_addc_u32 s99, vcc_hi, 0
	s_sub_u32 s98, s98, 0x1000
	s_subb_u32 s99, s99, 0
	v_readlane_b32 vcc_lo, v253, 2
	v_readlane_b32 vcc_hi, v253, 3
	s_lshl_b32 s13, s5, 14
	s_nop 1
	s_add_u32 s100, vcc_lo, s13
	s_addc_u32 s101, vcc_hi, 0
	s_sub_u32 s100, s100, 0x1000
	s_subb_u32 s101, s101, 0
	s_add_u32 m0, s9, s12
	s_nop 0
	global_load_lds_dwordx4 v0, s[98:99]
	global_load_lds_dwordx4 v1, s[98:99] offset:1024
	global_load_lds_dwordx4 v2, s[100:101] offset:2048
	global_load_lds_dwordx4 v3, s[100:101] offset:3072
	s_add_u32 m0, m0, 0x1000
	s_nop 0
	global_load_lds_dwordx4 v4, s[100:101]
	global_load_lds_dwordx4 v5, s[100:101] offset:1024
	s_add_u32 s98, s98, 0x200000
	s_addc_u32 s99, s99, 0
	s_add_u32 s100, s100, 0x30000
	s_addc_u32 s101, s101, 0
	s_add_u32 s13, s9, 0x6000
	s_cmp_eq_u32 s13, 0x12000
	s_cselect_b32 s13, 0, s13
	s_add_u32 m0, s13, s12
	s_nop 0
	global_load_lds_dwordx4 v0, s[98:99]
	global_load_lds_dwordx4 v1, s[98:99] offset:1024
	global_load_lds_dwordx4 v2, s[100:101] offset:2048
	global_load_lds_dwordx4 v3, s[100:101] offset:3072
	s_add_u32 m0, m0, 0x1000
	s_nop 0
	global_load_lds_dwordx4 v4, s[100:101]
	global_load_lds_dwordx4 v5, s[100:101] offset:1024
	s_add_u32 s98, s98, 0x200000
	s_addc_u32 s99, s99, 0
	s_add_u32 s100, s100, 0x30000
	s_addc_u32 s101, s101, 0
	s_add_u32 s13, s13, 0x6000
	s_cmp_eq_u32 s13, 0x12000
	s_cselect_b32 s13, 0, s13
	s_add_u32 m0, s13, s12
	s_nop 0
	global_load_lds_dwordx4 v0, s[98:99]
	global_load_lds_dwordx4 v1, s[98:99] offset:1024
	global_load_lds_dwordx4 v2, s[100:101] offset:2048
	global_load_lds_dwordx4 v3, s[100:101] offset:3072
	s_add_u32 m0, m0, 0x1000
	s_nop 0
	global_load_lds_dwordx4 v4, s[100:101]
	global_load_lds_dwordx4 v5, s[100:101] offset:1024
	s_add_u32 s98, s98, 0x200000
	s_addc_u32 s99, s99, 0
	s_add_u32 s100, s100, 0x30000
	s_addc_u32 s101, s101, 0

; DI f32x4 mfma(bf16x8 a, bf16x8 b, f32x4 c) { return __builtin_amdgcn_mfma_f32_16x16x32_bf16(a, b, c, 0, 0, 0); }
; #define G_LOAD(PA, PB, STEP) do { _Pragma("unroll") for (int i_ = 0; i_ < 2; ++i_) ra[i_] = *(const u32x4*)((PA) + (size_t)(64 * i_) * K + (STEP) * 32); \
;         _Pragma("unroll") for (int i_ = 0; i_ < 4; ++i_) rb[i_] = *(const u32x4*)((PB) + (size_t)(64 * i_) * K + (STEP) * 32); } while (0)
; #define G_STORE(BUF) do { _Pragma("unroll") for (int i_ = 0; i_ < 2; ++i_) *(u32x4*)(sA + (BUF) * 128 * 40 + (lrow + 64 * i_) * 40 + lcc * 8) = ra[i_]; \
;         _Pragma("unroll") for (int i_ = 0; i_ < 4; ++i_) *(u32x4*)(sB + (BUF) * 256 * 40 + (lrow + 64 * i_) * 40 + lcc * 8) = rb[i_]; } while (0)
; template <int EPI> ...
;     ...
;         for (int kt = 0; kt < nk; ++kt) {
;             const int buf = kt & 1;
;             const bf16_t* a_ = sA + buf * 128 * 40 + (wr * 64 + fr) * 40 + fq * 8;
;             const bf16_t* b_ = sB + buf * 256 * 40 + (wc * 128 + fr) * 40 + fq * 8;
;             bf16x8 af[4];
; #pragma unroll
;             for (int i = 0; i < 4; ++i) af[i] = *(const bf16x8*)(a_ + i * 16 * 40);
; #pragma unroll
;             for (int jh = 0; jh < 2; ++jh) {
;                 bf16x8 bfr[4];
; #pragma unroll
;                 for (int j = 0; j < 4; ++j) bfr[j] = *(const bf16x8*)(b_ + (jh * 4 + j) * 16 * 40);
; #pragma unroll
;                 for (int i = 0; i < 4; ++i)
; #pragma unroll
;                     for (int j = 0; j < 4; ++j) acc[i][jh * 4 + j] = mfma(bfr[j], af[i], acc[i][jh * 4 + j]);
;             }
;             G_STORE(buf ^ 1);
;             {
;                 const bool cur = kt + 2 < nk;
;                 const bf16_t* pa = cur ? Ag : An; const bf16_t* pb = cur ? Bg : Bn;
;                 const int st = cur ? kt + 2 : kt + 2 - nk;
;                 G_LOAD(pa, pb, st);
;             }
;             __syncthreads();
;         }
.Lg162_swret:
	s_add_u32 m0, s9, s12
	v_mfma_f32_16x16x32_bf16 v[132:135], v[192:195], v[10:13], v[132:135]
	global_load_lds_dwordx4 v0, s[98:99]
	v_mfma_f32_16x16x32_bf16 v[128:131], v[196:199], v[10:13], v[128:131]
	v_mfma_f32_16x16x32_bf16 v[124:127], v[200:203], v[10:13], v[124:127]
	global_load_lds_dwordx4 v1, s[98:99] offset:1024
	v_mfma_f32_16x16x32_bf16 v[120:123], v[204:207], v[10:13], v[120:123]
	ds_read_b128 v[10:13], v8
	v_mfma_f32_16x16x32_bf16 v[100:103], v[192:195], v[14:17], v[100:103]
	global_load_lds_dwordx4 v2, s[100:101] offset:2048
	v_mfma_f32_16x16x32_bf16 v[96:99], v[196:199], v[14:17], v[96:99]
	v_mfma_f32_16x16x32_bf16 v[92:95], v[200:203], v[14:17], v[92:95]
	global_load_lds_dwordx4 v3, s[100:101] offset:3072
	v_mfma_f32_16x16x32_bf16 v[88:91], v[204:207], v[14:17], v[88:91]
	ds_read_b128 v[14:17], v8 offset:1024
	v_mfma_f32_16x16x32_bf16 v[68:71], v[192:195], v[18:21], v[68:71]
	s_add_u32 m0, m0, 0x1000
	v_mfma_f32_16x16x32_bf16 v[64:67], v[196:199], v[18:21], v[64:67]
	global_load_lds_dwordx4 v4, s[100:101]
	v_mfma_f32_16x16x32_bf16 v[60:63], v[200:203], v[18:21], v[60:63]
	v_mfma_f32_16x16x32_bf16 v[56:59], v[204:207], v[18:21], v[56:59]
	ds_read_b128 v[18:21], v8 offset:6144
	v_mfma_f32_16x16x32_bf16 v[36:39], v[192:195], v[152:155], v[36:39]
	global_load_lds_dwordx4 v5, s[100:101] offset:1024
	v_mfma_f32_16x16x32_bf16 v[32:35], v[196:199], v[152:155], v[32:35]
	v_mfma_f32_16x16x32_bf16 v[28:31], v[200:203], v[152:155], v[28:31]
	v_mfma_f32_16x16x32_bf16 v[24:27], v[204:207], v[152:155], v[24:27]
	ds_read_b128 v[152:155], v8 offset:7168
	ds_read_b128 v[192:195], v9 offset:6144
	ds_read_b128 v[196:199], v9 offset:7168
	ds_read_b128 v[200:203], v9 offset:8192
	ds_read_b128 v[204:207], v9 offset:9216
	s_add_u32 s98, s98, 0x200000
	s_addc_u32 s99, s99, 0
	s_add_u32 s100, s100, 0x30000
	s_addc_u32 s101, s101, 0
	s_add_u32 s9, s9, 0x6000
	s_cmp_eq_u32 s9, 0x12000
	s_cselect_b32 s9, 0, s9
	s_add_u32 s4, s4, 1
	s_cmp_lt_u32 s4, 31
	s_cbranch_scc1 .Lg162_top
	s_waitcnt lgkmcnt(4)
	v_mfma_f32_16x16x32_bf16 v[148:151], v[160:163], v[10:13], v[148:151]
	v_mfma_f32_16x16x32_bf16 v[116:119], v[160:163], v[14:17], v[116:119]
	v_mfma_f32_16x16x32_bf16 v[84:87], v[160:163], v[18:21], v[84:87]
	v_mfma_f32_16x16x32_bf16 v[52:55], v[160:163], v[152:155], v[52:55]
	v_mfma_f32_16x16x32_bf16 v[144:147], v[174:177], v[10:13], v[144:147]
	v_mfma_f32_16x16x32_bf16 v[112:115], v[174:177], v[14:17], v[112:115]
	v_mfma_f32_16x16x32_bf16 v[80:83], v[174:177], v[18:21], v[80:83]
	v_mfma_f32_16x16x32_bf16 v[48:51], v[174:177], v[152:155], v[48:51]
	v_mfma_f32_16x16x32_bf16 v[140:143], v[178:181], v[10:13], v[140:143]
	v_mfma_f32_16x16x32_bf16 v[108:111], v[178:181], v[14:17], v[108:111]
	v_mfma_f32_16x16x32_bf16 v[76:79], v[178:181], v[18:21], v[76:79]
	v_mfma_f32_16x16x32_bf16 v[44:47], v[178:181], v[152:155], v[44:47]
	v_mfma_f32_16x16x32_bf16 v[136:139], v[182:185], v[10:13], v[136:139]
	v_mfma_f32_16x16x32_bf16 v[104:107], v[182:185], v[14:17], v[104:107]
	v_mfma_f32_16x16x32_bf16 v[72:75], v[182:185], v[18:21], v[72:75]
	v_mfma_f32_16x16x32_bf16 v[40:43], v[182:185], v[152:155], v[40:43]
	s_waitcnt vmcnt(6)
	s_waitcnt lgkmcnt(0)
	s_barrier
	s_add_u32 m0, s9, s12
	v_mfma_f32_16x16x32_bf16 v[132:135], v[192:195], v[10:13], v[132:135]
	global_load_lds_dwordx4 v0, s[98:99]
	v_mfma_f32_16x16x32_bf16 v[128:131], v[196:199], v[10:13], v[128:131]
	v_mfma_f32_16x16x32_bf16 v[124:127], v[200:203], v[10:13], v[124:127]
	global_load_lds_dwordx4 v1, s[98:99] offset:1024
	v_mfma_f32_16x16x32_bf16 v[120:123], v[204:207], v[10:13], v[120:123]
	v_mfma_f32_16x16x32_bf16 v[100:103], v[192:195], v[14:17], v[100:103]
	global_load_lds_dwordx4 v2, s[100:101] offset:2048
	v_mfma_f32_16x16x32_bf16 v[96:99], v[196:199], v[14:17], v[96:99]
	v_mfma_f32_16x16x32_bf16 v[92:95], v[200:203], v[14:17], v[92:95]
	global_load_lds_dwordx4 v3, s[100:101] offset:3072
	v_mfma_f32_16x16x32_bf16 v[88:91], v[204:207], v[14:17], v[88:91]
	v_mfma_f32_16x16x32_bf16 v[68:71], v[192:195], v[18:21], v[68:71]
	s_add_u32 m0, m0, 0x1000
	v_mfma_f32_16x16x32_bf16 v[64:67], v[196:199], v[18:21], v[64:67]
	global_load_lds_dwordx4 v4, s[100:101]
	v_mfma_f32_16x16x32_bf16 v[60:63], v[200:203], v[18:21], v[60:63]
	v_mfma_f32_16x16x32_bf16 v[56:59], v[204:207], v[18:21], v[56:59]
	v_mfma_f32_16x16x32_bf16 v[36:39], v[192:195], v[152:155], v[36:39]
	global_load_lds_dwordx4 v5, s[100:101] offset:1024
	v_mfma_f32_16x16x32_bf16 v[32:35], v[196:199], v[152:155], v[32:35]
	v_mfma_f32_16x16x32_bf16 v[28:31], v[200:203], v[152:155], v[28:31]
	v_mfma_f32_16x16x32_bf16 v[24:27], v[204:207], v[152:155], v[24:27]
	s_add_u32 s98, s98, 0x200000
	s_addc_u32 s99, s99, 0
	s_add_u32 s100, s100, 0x30000
	s_addc_u32 s101, s101, 0
	s_add_u32 s9, s9, 0x6000
	s_cmp_eq_u32 s9, 0x12000
	s_cselect_b32 s9, 0, s9
	s_add_u32 s4, s4, 1
	s_branch .Lg162_end
.Lg162_sw:
	v_readlane_b32 vcc_lo, v253, 0
	v_readlane_b32 vcc_hi, v253, 1
	s_lshl_b32 s13, s7, 13
	s_nop 1
	s_add_u32 s98, vcc_lo, s13
	s_addc_u32 s99, vcc_hi, 0
	s_sub_u32 s98, s98, 0x1000
	s_subb_u32 s99, s99, 0
	v_readlane_b32 vcc_lo, v253, 2
	v_readlane_b32 vcc_hi, v253, 3
	s_lshl_b32 s13, s8, 14
	s_nop 1
	s_add_u32 s100, vcc_lo, s13
	s_addc_u32 s101, vcc_hi, 0
	s_sub_u32 s100, s100, 0x1000
	s_subb_u32 s101, s101, 0
	s_branch .Lg162_swret

; DI f32x4 mfma(bf16x8 a, bf16x8 b, f32x4 c) { return __builtin_amdgcn_mfma_f32_16x16x32_bf16(a, b, c, 0, 0, 0); }
; #define G_LOAD(PA, PB, STEP) do { _Pragma("unroll") for (int i_ = 0; i_ < 2; ++i_) ra[i_] = *(const u32x4*)((PA) + (size_t)(64 * i_) * K + (STEP) * 32); \
;         _Pragma("unroll") for (int i_ = 0; i_ < 4; ++i_) rb[i_] = *(const u32x4*)((PB) + (size_t)(64 * i_) * K + (STEP) * 32); } while (0)
; #define G_STORE(BUF) do { _Pragma("unroll") for (int i_ = 0; i_ < 2; ++i_) *(u32x4*)(sA + (BUF) * 128 * 40 + (lrow + 64 * i_) * 40 + lcc * 8) = ra[i_]; \
;         _Pragma("unroll") for (int i_ = 0; i_ < 4; ++i_) *(u32x4*)(sB + (BUF) * 256 * 40 + (lrow + 64 * i_) * 40 + lcc * 8) = rb[i_]; } while (0)
; template <int EPI> ...
;     ...
;     const int idx0 = blockIdx.x >> 3;
;     if (idx0 < perX) {
;         int mt0, nt0; tile_of(idx0, mt0, nt0);
;         const bf16_t* A0 = A + (size_t)(mt0 * 128 + lrow) * K + lcc * 8;
;         const bf16_t* B0 = Bt + (size_t)(nt0 * 256 + lrowp) * K + lcc * 8;
;         G_LOAD(A0, B0, 0);
;         G_STORE(0);
;         G_LOAD(A0, B0, 1);
;         __syncthreads();
;     }
;     ...
;         for (int kt = 0; kt < nk; ++kt) {
;             const int buf = kt & 1;
;             const bf16_t* a_ = sA + buf * 128 * 40 + (wr * 64 + fr) * 40 + fq * 8;
;             const bf16_t* b_ = sB + buf * 256 * 40 + (wc * 128 + fr) * 40 + fq * 8;
;             bf16x8 af[4];
; #pragma unroll
;             for (int i = 0; i < 4; ++i) af[i] = *(const bf16x8*)(a_ + i * 16 * 40);
; #pragma unroll
;             for (int jh = 0; jh < 2; ++jh) {
;                 bf16x8 bfr[4];
; #pragma unroll
;                 for (int j = 0; j < 4; ++j) bfr[j] = *(const bf16x8*)(b_ + (jh * 4 + j) * 16 * 40);
; #pragma unroll
;                 for (int i = 0; i < 4; ++i)
; #pragma unroll
;                     for (int j = 0; j < 4; ++j) acc[i][jh * 4 + j] = mfma(bfr[j], af[i], acc[i][jh * 4 + j]);
;             }
;             G_STORE(buf ^ 1);
;             {
;                 const bool cur = kt + 2 < nk;
;                 const bf16_t* pa = cur ? Ag : An; const bf16_t* pb = cur ? Bg : Bn;
;                 const int st = cur ? kt + 2 : kt + 2 - nk;
;                 G_LOAD(pa, pb, st);
;             }
.LBB0_691:
	v_readlane_b32 s21, v253, 4
	v_readlane_b32 s22, v253, 6
	v_readlane_b32 s23, v253, 5
	s_nop 3
	s_cmp_eq_u32 s23, 0
	s_cbranch_scc1 .Lg691_entry
	v_and_b32_e32 v8, 63, v210
	v_lshrrev_b32_e32 v9, 6, v210
	s_nop 0
	v_readfirstlane_b32 s23, v9
	v_lshrrev_b32_e32 v9, 4, v8
	v_sub_u32_e32 v10, 0, v9
	v_and_b32_e32 v10, 3, v10
	v_and_b32_e32 v11, 3, v8
	v_xor_b32_e32 v11, v11, v10
	v_lshrrev_b32_e32 v12, 2, v8
	v_lshlrev_b32_e32 v0, 11, v12
	v_lshl_add_u32 v0, v11, 4, v0
	s_lshl_b32 vcc_lo, s23, 16
	v_add_u32_e32 v0, vcc_lo, v0
	v_add_u32_e32 v0, 0x1000, v0
	v_add_u32_e32 v1, 0x7c00, v0
	v_and_b32_e32 v13, 3, v12
	v_lshl_add_u32 v13, v9, 3, v13
	v_lshlrev_b32_e32 v2, 6, v13
	v_lshl_add_u32 v2, v11, 4, v2
	s_lshl_b32 vcc_lo, s23, 12
	v_add_u32_e32 v2, vcc_lo, v2
	v_add_u32_e32 v2, 0x800, v2
	v_add_u32_e32 v3, 0xfffffd00, v2
	v_add_u32_e32 v4, 0x1000, v2
	v_add_u32_e32 v5, 0xd00, v2
	v_and_b32_e32 v10, 15, v8
	v_lshrrev_b32_e32 v11, 2, v10
	v_sub_u32_e32 v11, 0, v11
	v_and_b32_e32 v11, 3, v11
	v_xor_b32_e32 v11, v9, v11
	v_lshlrev_b32_e32 v6, 6, v10
	v_lshl_add_u32 v6, v11, 4, v6
	s_lshr_b32 vcc_lo, s23, 1
	s_mul_i32 vcc_lo, vcc_lo, 0x3000
	s_and_b32 vcc_hi, s23, 1
	s_mul_i32 vcc_hi, vcc_hi, 0x3000
	s_add_u32 vcc_hi, vcc_hi, 0x800
	v_add_u32_e32 v7, vcc_hi, v6
	v_add_u32_e32 v6, vcc_lo, v6
	s_mul_i32 s22, s23, 0x1800
	v_writelane_b32 v253, s22, 6
	v_writelane_b32 v253, 0, 5
	v_readlane_b32 vcc_lo, v253, 0
	v_readlane_b32 vcc_hi, v253, 1
	s_lshl_b32 s23, s8, 18
	s_nop 1
	s_add_u32 s98, vcc_lo, s23
	s_addc_u32 s99, vcc_hi, 0
	s_sub_u32 s98, s98, 0x1000
	s_subb_u32 s99, s99, 0
	v_readlane_b32 vcc_lo, v253, 2
	v_readlane_b32 vcc_hi, v253, 3
	s_lshl_b32 s23, s9, 14
	s_nop 1
	s_add_u32 s100, vcc_lo, s23
	s_addc_u32 s101, vcc_hi, 0
	s_sub_u32 s100, s100, 0x1000
	s_subb_u32 s101, s101, 0
	s_add_u32 m0, s21, s22
	s_nop 0
	global_load_lds_dwordx4 v0, s[98:99]
	global_load_lds_dwordx4 v1, s[98:99] offset:1024
	global_load_lds_dwordx4 v2, s[100:101] offset:2048
	global_load_lds_dwordx4 v3, s[100:101] offset:3072
	s_add_u32 m0, m0, 0x1000
	s_nop 0
	global_load_lds_dwordx4 v4, s[100:101]
	global_load_lds_dwordx4 v5, s[100:101] offset:1024
	s_add_u32 s98, s98, 0x40
	s_addc_u32 s99, s99, 0
	s_add_u32 s100, s100, 0x10000
	s_addc_u32 s101, s101, 0
	s_add_u32 s23, s21, 0x6000
	s_cmp_eq_u32 s23, 0x12000
	s_cselect_b32 s23, 0, s23
	s_add_u32 m0, s23, s22
	s_nop 0
	global_load_lds_dwordx4 v0, s[98:99]
	global_load_lds_dwordx4 v1, s[98:99] offset:1024
	global_load_lds_dwordx4 v2, s[100:101] offset:2048
	global_load_lds_dwordx4 v3, s[100:101] offset:3072
	s_add_u32 m0, m0, 0x1000
	s_nop 0
	global_load_lds_dwordx4 v4, s[100:101]
	global_load_lds_dwordx4 v5, s[100:101] offset:1024
	s_add_u32 s98, s98, 0x40
	s_addc_u32 s99, s99, 0
	s_add_u32 s100, s100, 0x10000
	s_addc_u32 s101, s101, 0
	s_add_u32 s23, s23, 0x6000
	s_cmp_eq_u32 s23, 0x12000
	s_cselect_b32 s23, 0, s23
	s_add_u32 m0, s23, s22
	s_nop 0
	global_load_lds_dwordx4 v0, s[98:99]
	global_load_lds_dwordx4 v1, s[98:99] offset:1024
	global_load_lds_dwordx4 v2, s[100:101] offset:2048
	global_load_lds_dwordx4 v3, s[100:101] offset:3072
	s_add_u32 m0, m0, 0x1000
	s_nop 0
	global_load_lds_dwordx4 v4, s[100:101]
	global_load_lds_dwordx4 v5, s[100:101] offset:1024
	s_add_u32 s98, s98, 0x40
	s_addc_u32 s99, s99, 0
	s_add_u32 s100, s100, 0x10000
	s_addc_u32 s101, s101, 0
.Lg691_entry:
	v_mov_b32_e32 v254, 0x200000
	v_mov_b32_e32 v255, 0
	s_mov_b32 s20, 0
	s_waitcnt vmcnt(0)
	s_barrier
	v_add_u32_e32 v8, s21, v6
	v_add_u32_e32 v9, s21, v7
	ds_read_b128 v[174:177], v9
	ds_read_b128 v[192:195], v9 offset:1024
	ds_read_b128 v[196:199], v9 offset:2048
	ds_read_b128 v[200:203], v9 offset:3072
	ds_read_b128 v[10:13], v8
	ds_read_b128 v[14:17], v8 offset:1024
	ds_read_b128 v[18:21], v8 offset:6144
	ds_read_b128 v[154:157], v8 offset:7168
	ds_read_b128 v[204:207], v9 offset:6144
	ds_read_b128 v[232:235], v9 offset:7168
	ds_read_b128 v[236:239], v9 offset:8192
	ds_read_b128 v[240:243], v9 offset:9216

; DI f32x4 mfma(bf16x8 a, bf16x8 b, f32x4 c) { return __builtin_amdgcn_mfma_f32_16x16x32_bf16(a, b, c, 0, 0, 0); }
; #define G_LOAD(PA, PB, STEP) do { _Pragma("unroll") for (int i_ = 0; i_ < 2; ++i_) ra[i_] = *(const u32x4*)((PA) + (size_t)(64 * i_) * K + (STEP) * 32); \
;         _Pragma("unroll") for (int i_ = 0; i_ < 4; ++i_) rb[i_] = *(const u32x4*)((PB) + (size_t)(64 * i_) * K + (STEP) * 32); } while (0)
; #define G_STORE(BUF) do { _Pragma("unroll") for (int i_ = 0; i_ < 2; ++i_) *(u32x4*)(sA + (BUF) * 128 * 40 + (lrow + 64 * i_) * 40 + lcc * 8) = ra[i_]; \
;         _Pragma("unroll") for (int i_ = 0; i_ < 4; ++i_) *(u32x4*)(sB + (BUF) * 256 * 40 + (lrow + 64 * i_) * 40 + lcc * 8) = rb[i_]; } while (0)
; template <int EPI> ...
;     ...
;         for (int kt = 0; kt < nk; ++kt) {
;             const int buf = kt & 1;
;             const bf16_t* a_ = sA + buf * 128 * 40 + (wr * 64 + fr) * 40 + fq * 8;
;             const bf16_t* b_ = sB + buf * 256 * 40 + (wc * 128 + fr) * 40 + fq * 8;
;             bf16x8 af[4];
; #pragma unroll
;             for (int i = 0; i < 4; ++i) af[i] = *(const bf16x8*)(a_ + i * 16 * 40);
; #pragma unroll
;             for (int jh = 0; jh < 2; ++jh) {
;                 bf16x8 bfr[4];
; #pragma unroll
;                 for (int j = 0; j < 4; ++j) bfr[j] = *(const bf16x8*)(b_ + (jh * 4 + j) * 16 * 40);
; #pragma unroll
;                 for (int i = 0; i < 4; ++i)
; #pragma unroll
;                     for (int j = 0; j < 4; ++j) acc[i][jh * 4 + j] = mfma(bfr[j], af[i], acc[i][jh * 4 + j]);
;             }
;             G_STORE(buf ^ 1);
;             {
;                 const bool cur = kt + 2 < nk;
;                 const bf16_t* pa = cur ? Ag : An; const bf16_t* pb = cur ? Bg : Bn;
;                 const int st = cur ? kt + 2 : kt + 2 - nk;
;                 G_LOAD(pa, pb, st);
;             }
;             __syncthreads();
;         }
.Lg691_swret:
	s_add_u32 m0, s21, s22
	v_mfma_f32_16x16x32_bf16 v[132:135], v[204:207], v[10:13], v[132:135]
	global_load_lds_dwordx4 v0, s[98:99]
	v_mfma_f32_16x16x32_bf16 v[128:131], v[232:235], v[10:13], v[128:131]
	v_mfma_f32_16x16x32_bf16 v[124:127], v[236:239], v[10:13], v[124:127]
	global_load_lds_dwordx4 v1, s[98:99] offset:1024
	v_mfma_f32_16x16x32_bf16 v[120:123], v[240:243], v[10:13], v[120:123]
	ds_read_b128 v[10:13], v8
	v_mfma_f32_16x16x32_bf16 v[100:103], v[204:207], v[14:17], v[100:103]
	global_load_lds_dwordx4 v2, s[100:101] offset:2048
	v_mfma_f32_16x16x32_bf16 v[96:99], v[232:235], v[14:17], v[96:99]
	v_mfma_f32_16x16x32_bf16 v[92:95], v[236:239], v[14:17], v[92:95]
	global_load_lds_dwordx4 v3, s[100:101] offset:3072
	v_mfma_f32_16x16x32_bf16 v[88:91], v[240:243], v[14:17], v[88:91]
	ds_read_b128 v[14:17], v8 offset:1024
	v_mfma_f32_16x16x32_bf16 v[68:71], v[204:207], v[18:21], v[68:71]
	s_add_u32 m0, m0, 0x1000
	v_mfma_f32_16x16x32_bf16 v[64:67], v[232:235], v[18:21], v[64:67]
	global_load_lds_dwordx4 v4, s[100:101]
	v_mfma_f32_16x16x32_bf16 v[60:63], v[236:239], v[18:21], v[60:63]
	v_mfma_f32_16x16x32_bf16 v[56:59], v[240:243], v[18:21], v[56:59]
	ds_read_b128 v[18:21], v8 offset:6144
	v_mfma_f32_16x16x32_bf16 v[36:39], v[204:207], v[154:157], v[36:39]
	global_load_lds_dwordx4 v5, s[100:101] offset:1024
	v_mfma_f32_16x16x32_bf16 v[32:35], v[232:235], v[154:157], v[32:35]
	v_mfma_f32_16x16x32_bf16 v[28:31], v[236:239], v[154:157], v[28:31]
	v_mfma_f32_16x16x32_bf16 v[24:27], v[240:243], v[154:157], v[24:27]
	ds_read_b128 v[154:157], v8 offset:7168
	ds_read_b128 v[204:207], v9 offset:6144
	ds_read_b128 v[232:235], v9 offset:7168
	ds_read_b128 v[236:239], v9 offset:8192
	ds_read_b128 v[240:243], v9 offset:9216
	s_add_u32 s98, s98, 0x40
	s_addc_u32 s99, s99, 0
	s_add_u32 s100, s100, 0x10000
	s_addc_u32 s101, s101, 0
	s_add_u32 s21, s21, 0x6000
	s_cmp_eq_u32 s21, 0x12000
	s_cselect_b32 s21, 0, s21
	s_add_u32 s20, s20, 1
	s_cmp_lt_u32 s20, 31
	s_cbranch_scc1 .Lg691_top
	s_waitcnt lgkmcnt(4)
	v_mfma_f32_16x16x32_bf16 v[148:151], v[174:177], v[10:13], v[148:151]
	v_mfma_f32_16x16x32_bf16 v[116:119], v[174:177], v[14:17], v[116:119]
	v_mfma_f32_16x16x32_bf16 v[84:87], v[174:177], v[18:21], v[84:87]
	v_mfma_f32_16x16x32_bf16 v[52:55], v[174:177], v[154:157], v[52:55]
	v_mfma_f32_16x16x32_bf16 v[144:147], v[192:195], v[10:13], v[144:147]
	v_mfma_f32_16x16x32_bf16 v[112:115], v[192:195], v[14:17], v[112:115]
	v_mfma_f32_16x16x32_bf16 v[80:83], v[192:195], v[18:21], v[80:83]
	v_mfma_f32_16x16x32_bf16 v[48:51], v[192:195], v[154:157], v[48:51]
	v_mfma_f32_16x16x32_bf16 v[140:143], v[196:199], v[10:13], v[140:143]
	v_mfma_f32_16x16x32_bf16 v[108:111], v[196:199], v[14:17], v[108:111]
	v_mfma_f32_16x16x32_bf16 v[76:79], v[196:199], v[18:21], v[76:79]
	v_mfma_f32_16x16x32_bf16 v[44:47], v[196:199], v[154:157], v[44:47]
	v_mfma_f32_16x16x32_bf16 v[136:139], v[200:203], v[10:13], v[136:139]
	v_mfma_f32_16x16x32_bf16 v[104:107], v[200:203], v[14:17], v[104:107]
	v_mfma_f32_16x16x32_bf16 v[72:75], v[200:203], v[18:21], v[72:75]
	v_mfma_f32_16x16x32_bf16 v[40:43], v[200:203], v[154:157], v[40:43]
	s_waitcnt vmcnt(6)
	s_waitcnt lgkmcnt(0)
	s_barrier
	s_add_u32 m0, s21, s22
	v_mfma_f32_16x16x32_bf16 v[132:135], v[204:207], v[10:13], v[132:135]
	global_load_lds_dwordx4 v0, s[98:99]
	v_mfma_f32_16x16x32_bf16 v[128:131], v[232:235], v[10:13], v[128:131]
	v_mfma_f32_16x16x32_bf16 v[124:127], v[236:239], v[10:13], v[124:127]
	global_load_lds_dwordx4 v1, s[98:99] offset:1024
	v_mfma_f32_16x16x32_bf16 v[120:123], v[240:243], v[10:13], v[120:123]
	v_mfma_f32_16x16x32_bf16 v[100:103], v[204:207], v[14:17], v[100:103]
	global_load_lds_dwordx4 v2, s[100:101] offset:2048
	v_mfma_f32_16x16x32_bf16 v[96:99], v[232:235], v[14:17], v[96:99]
	v_mfma_f32_16x16x32_bf16 v[92:95], v[236:239], v[14:17], v[92:95]
	global_load_lds_dwordx4 v3, s[100:101] offset:3072
	v_mfma_f32_16x16x32_bf16 v[88:91], v[240:243], v[14:17], v[88:91]
	v_mfma_f32_16x16x32_bf16 v[68:71], v[204:207], v[18:21], v[68:71]
	s_add_u32 m0, m0, 0x1000
	v_mfma_f32_16x16x32_bf16 v[64:67], v[232:235], v[18:21], v[64:67]
	global_load_lds_dwordx4 v4, s[100:101]
	v_mfma_f32_16x16x32_bf16 v[60:63], v[236:239], v[18:21], v[60:63]
	v_mfma_f32_16x16x32_bf16 v[56:59], v[240:243], v[18:21], v[56:59]
	v_mfma_f32_16x16x32_bf16 v[36:39], v[204:207], v[154:157], v[36:39]
	global_load_lds_dwordx4 v5, s[100:101] offset:1024
	v_mfma_f32_16x16x32_bf16 v[32:35], v[232:235], v[154:157], v[32:35]
	v_mfma_f32_16x16x32_bf16 v[28:31], v[236:239], v[154:157], v[28:31]
	v_mfma_f32_16x16x32_bf16 v[24:27], v[240:243], v[154:157], v[24:27]
	s_add_u32 s98, s98, 0x40
	s_addc_u32 s99, s99, 0
	s_add_u32 s100, s100, 0x10000
	s_addc_u32 s101, s101, 0
	s_add_u32 s21, s21, 0x6000
	s_cmp_eq_u32 s21, 0x12000
	s_cselect_b32 s21, 0, s21
	s_add_u32 s20, s20, 1
	s_branch .Lg691_end

; DI unsigned pk2(float lo, float hi) { f32x2 v = {lo, hi}; bf16x2_t r = __builtin_convertvector(v, bf16x2_t); return __builtin_bit_cast(unsigned, r); }
; template <int EPI> ...
;     ...
;                 } else {
;                     *(f32x4*)(xout + (size_t)m * Nn + n0) = v0;
;                     *(f32x4*)(xout + (size_t)m * Nn + n0 + 4) = v1;
;                     if (hb) {
;                         const f32x4 g0 = *(const f32x4*)(gn + n0), g1 = *(const f32x4*)(gn + n0 + 4);
;                         u32x4 o4; o4[0] = pk2(v0[0] * g0[0], v0[1] * g0[1]); o4[1] = pk2(v0[2] * g0[2], v0[3] * g0[3]);
;                         o4[2] = pk2(v1[0] * g1[0], v1[1] * g1[1]); o4[3] = pk2(v1[2] * g1[2], v1[3] * g1[3]);
;                         *(u32x4*)(hb + (size_t)m * Nn + n0) = o4;
;                         sq += v0[0] * v0[0] + v0[1] * v0[1] + v0[2] * v0[2] + v0[3] * v0[3] + v1[0] * v1[0] + v1[1] * v1[1] + v1[2] * v1[2] + v1[3] * v1[3];
;                     }
.Lg691_end:
	s_setprio 0
	v_writelane_b32 v253, s21, 4
	v_readlane_b32 s52, v251, 34
	v_readlane_b32 s53, v251, 35
	v_readlane_b32 s54, v251, 36
	v_readlane_b32 s55, v251, 37
	v_readlane_b32 s56, v251, 38
	v_readlane_b32 s57, v251, 39
	v_readlane_b32 s58, v251, 40
	v_readlane_b32 s59, v251, 41
	v_readlane_b32 s60, v251, 42
	v_readlane_b32 s61, v251, 43
	v_readlane_b32 s62, v251, 44
	v_readlane_b32 s63, v251, 45
	v_readlane_b32 s64, v251, 46
	v_readlane_b32 s65, v251, 47
	v_readlane_b32 s66, v251, 48
	v_readlane_b32 s67, v251, 49
	v_or_b32_e32 v185, s16, v183
	v_lshl_add_u64 v[164:165], s[56:57], 0, v[164:165]
	v_readlane_b32 s52, v251, 0
	v_lshlrev_b64 v[174:175], 6, v[158:159]
	v_readlane_b32 s66, v251, 14
	v_readlane_b32 s67, v251, 15
	v_lshlrev_b32_e32 v188, 2, v185
	v_lshl_add_u64 v[176:177], v[164:165], 0, v[188:189]
	v_lshl_add_u64 v[174:175], s[66:67], 0, v[174:175]
	s_and_b64 vcc, exec, s[24:25]
	v_lshrrev_b32_e32 v164, 5, v185
	v_lshlrev_b32_e32 v164, 20, v164
	v_and_or_b32 v164, v185, 31, v164
	v_lshlrev_b32_e32 v164, 1, v164
	v_readlane_b32 s53, v251, 1
	v_readlane_b32 s54, v251, 2
	v_readlane_b32 s55, v251, 3
	v_readlane_b32 s56, v251, 4
	v_readlane_b32 s57, v251, 5
	v_readlane_b32 s58, v251, 6
	v_readlane_b32 s59, v251, 7
	v_readlane_b32 s60, v251, 8
	v_readlane_b32 s61, v251, 9
	v_readlane_b32 s62, v251, 10
	v_readlane_b32 s63, v251, 11
	v_readlane_b32 s64, v251, 12
	v_readlane_b32 s65, v251, 13
	global_store_dwordx4 v[176:177], v[148:151], off
	global_store_dwordx4 v[176:177], v[144:147], off offset:16
	s_cbranch_vccz .LBB0_694
	global_load_dwordx4 v[192:195], v188, s[12:13] offset:16
	global_load_dwordx4 v[196:199], v188, s[12:13]
	v_mov_b32_e32 v165, v189
	s_waitcnt vmcnt(1)
	v_pk_mul_f32 v[192:193], v[144:145], v[192:193]
	s_waitcnt vmcnt(0)
	v_pk_mul_f32 v[196:197], v[148:149], v[196:197]
	v_pk_mul_f32 v[148:149], v[148:149], v[148:149]
	v_pk_mul_f32 v[186:187], v[150:151], v[198:199]
	v_pk_mul_f32 v[150:151], v[150:151], v[150:151]
	v_add_f32_e32 v148, v148, v149
	v_add_f32_e32 v148, v150, v148
	v_pk_mul_f32 v[144:145], v[144:145], v[144:145]
	v_add_f32_e32 v148, v151, v148
	v_add_f32_e32 v144, v144, v148
	v_cvt_pk_bf16_f32 v196, v196, v197
	v_cvt_pk_bf16_f32 v197, v186, v187
	v_pk_mul_f32 v[186:187], v[146:147], v[194:195]
	v_pk_mul_f32 v[146:147], v[146:147], v[146:147]
	v_add_f32_e32 v144, v145, v144
	v_add_f32_e32 v144, v146, v144
	v_cvt_pk_bf16_f32 v198, v192, v193
	v_cvt_pk_bf16_f32 v199, v186, v187
	v_lshl_add_u64 v[186:187], v[174:175], 0, v[164:165]
	v_add_f32_e32 v144, v147, v144
	global_store_dwordx4 v[186:187], v[196:199], off
	s_branch .LBB0_695

; DI unsigned pk2(float lo, float hi) { f32x2 v = {lo, hi}; bf16x2_t r = __builtin_convertvector(v, bf16x2_t); return __builtin_bit_cast(unsigned, r); }
; template <int EPI> ...
;     ...
;                 } else {
;                     *(f32x4*)(xout + (size_t)m * Nn + n0) = v0;
;                     *(f32x4*)(xout + (size_t)m * Nn + n0 + 4) = v1;
;                     if (hb) {
;                         const f32x4 g0 = *(const f32x4*)(gn + n0), g1 = *(const f32x4*)(gn + n0 + 4);
;                         u32x4 o4; o4[0] = pk2(v0[0] * g0[0], v0[1] * g0[1]); o4[1] = pk2(v0[2] * g0[2], v0[3] * g0[3]);
;                         o4[2] = pk2(v1[0] * g1[0], v1[1] * g1[1]); o4[3] = pk2(v1[2] * g1[2], v1[3] * g1[3]);
;                         *(u32x4*)(hb + (size_t)m * Nn + n0) = o4;
;                         sq += v0[0] * v0[0] + v0[1] * v0[1] + v0[2] * v0[2] + v0[3] * v0[3] + v1[0] * v1[0] + v1[1] * v1[1] + v1[2] * v1[2] + v1[3] * v1[3];
;                     }
;                 }
;             }
;             if (EPI == 2 && hb) {
;                 sq += __shfl_xor(sq, 16); sq += __shfl_xor(sq, 32);
;                 if (fq == 0) atomicAdd(ssq_out + m, sq);
.LBB0_695:
	v_cndmask_b32_e64 v145, 0, 1, s[24:25]
	v_cmp_ne_u32_e64 s[8:9], 1, v145
	s_andn2_b64 vcc, exec, s[24:25]
	global_store_dwordx4 v[176:177], v[140:143], off offset:128
	global_store_dwordx4 v[176:177], v[136:139], off offset:144
	s_cbranch_vccnz .LBB0_697
	global_load_dwordx4 v[146:149], v188, s[12:13] offset:144
	global_load_dwordx4 v[192:195], v188, s[12:13] offset:128
	v_mov_b32_e32 v165, v189
	s_waitcnt vmcnt(1)
	v_pk_mul_f32 v[146:147], v[136:137], v[146:147]
	s_waitcnt vmcnt(0)
	v_pk_mul_f32 v[186:187], v[140:141], v[192:193]
	v_pk_mul_f32 v[140:141], v[140:141], v[140:141]
	v_pk_mul_f32 v[150:151], v[142:143], v[194:195]
	v_pk_mul_f32 v[142:143], v[142:143], v[142:143]
	v_add_f32_e32 v140, v140, v141
	v_add_f32_e32 v140, v142, v140
	v_pk_mul_f32 v[136:137], v[136:137], v[136:137]
	v_add_f32_e32 v140, v143, v140
	v_add_f32_e32 v136, v136, v140
	v_pk_mul_f32 v[148:149], v[138:139], v[148:149]
	v_pk_mul_f32 v[138:139], v[138:139], v[138:139]
	v_add_f32_e32 v136, v137, v136
	v_add_f32_e32 v136, v138, v136
	v_add_f32_e32 v136, v139, v136
	v_cvt_pk_bf16_f32 v192, v186, v187
	v_cvt_pk_bf16_f32 v193, v150, v151
	v_cvt_pk_bf16_f32 v194, v146, v147
	v_cvt_pk_bf16_f32 v195, v148, v149
	v_lshl_add_u64 v[146:147], v[174:175], 0, v[164:165]
	v_add_f32_e32 v144, v136, v144
	v_lshl_add_u64 v[146:147], v[146:147], 0, v[254:255]
	global_store_dwordx4 v[146:147], v[192:195], off
.LBB0_697:
	s_and_b64 vcc, exec, s[8:9]
	global_store_dwordx4 v[176:177], v[132:135], off offset:256
	global_store_dwordx4 v[176:177], v[128:131], off offset:272
	s_cbranch_vccnz .LBB0_699
	global_load_dwordx4 v[136:139], v188, s[12:13] offset:272
	global_load_dwordx4 v[140:143], v188, s[12:13] offset:256
	v_mov_b32_e32 v165, v189
	s_waitcnt vmcnt(1)
	v_pk_mul_f32 v[136:137], v[128:129], v[136:137]
	s_waitcnt vmcnt(0)
	v_pk_mul_f32 v[140:141], v[132:133], v[140:141]
	v_pk_mul_f32 v[132:133], v[132:133], v[132:133]
	v_pk_mul_f32 v[142:143], v[134:135], v[142:143]
	v_pk_mul_f32 v[134:135], v[134:135], v[134:135]
	v_add_f32_e32 v132, v132, v133
	v_add_f32_e32 v132, v134, v132
	v_pk_mul_f32 v[128:129], v[128:129], v[128:129]
	v_add_f32_e32 v132, v135, v132
	v_add_f32_e32 v128, v128, v132
	v_pk_mul_f32 v[138:139], v[130:131], v[138:139]
	v_pk_mul_f32 v[130:131], v[130:131], v[130:131]
	v_add_f32_e32 v128, v129, v128
	v_add_f32_e32 v128, v130, v128
	v_add_f32_e32 v128, v131, v128
	v_cvt_pk_bf16_f32 v140, v140, v141
	v_cvt_pk_bf16_f32 v141, v142, v143
	v_cvt_pk_bf16_f32 v142, v136, v137
	v_cvt_pk_bf16_f32 v143, v138, v139
	v_lshl_add_u64 v[136:137], v[174:175], 0, v[164:165]
	v_add_f32_e32 v144, v128, v144
	v_lshl_add_u64 v[136:137], v[136:137], 0, v[254:255]
	v_lshl_add_u64 v[136:137], v[136:137], 0, v[254:255]
	global_store_dwordx4 v[136:137], v[140:143], off
.LBB0_699:
	s_and_b64 vcc, exec, s[8:9]
	global_store_dwordx4 v[176:177], v[124:127], off offset:384
	global_store_dwordx4 v[176:177], v[120:123], off offset:400
	s_cbranch_vccnz .LBB0_703
	global_load_dwordx4 v[128:131], v188, s[12:13] offset:400
	global_load_dwordx4 v[132:135], v188, s[12:13] offset:384
	v_mov_b32_e32 v165, v189
	s_waitcnt vmcnt(1)
	v_pk_mul_f32 v[128:129], v[120:121], v[128:129]
	s_waitcnt vmcnt(0)
	v_pk_mul_f32 v[132:133], v[124:125], v[132:133]
	v_mul_f32_e32 v125, v125, v125
	v_fmac_f32_e32 v125, v124, v124
	v_fmac_f32_e32 v125, v126, v126
	v_fmac_f32_e32 v125, v127, v127
	v_fmac_f32_e32 v125, v120, v120
	v_fmac_f32_e32 v125, v121, v121
	v_fmac_f32_e32 v125, v122, v122
	v_fmac_f32_e32 v125, v123, v123
	v_add_f32_e32 v120, v125, v144
	ds_bpermute_b32 v121, v230, v120
	v_pk_mul_f32 v[134:135], v[126:127], v[134:135]
	v_pk_mul_f32 v[130:131], v[122:123], v[130:131]
	v_cvt_pk_bf16_f32 v132, v132, v133
	v_cvt_pk_bf16_f32 v133, v134, v135
	s_waitcnt lgkmcnt(0)
	v_add_f32_e32 v120, v120, v121
	ds_bpermute_b32 v121, v191, v120
	v_cvt_pk_bf16_f32 v134, v128, v129
	v_cvt_pk_bf16_f32 v135, v130, v131
	v_lshl_add_u64 v[128:129], v[174:175], 0, v[164:165]
	v_lshl_add_u64 v[128:129], v[128:129], 0, v[254:255]
	v_lshl_add_u64 v[128:129], v[128:129], 0, v[254:255]
	v_lshl_add_u64 v[128:129], v[128:129], 0, v[254:255]
	global_store_dwordx4 v[128:129], v[132:135], off
	s_and_saveexec_b64 s[16:17], s[6:7]
	s_cbranch_execz .LBB0_702
	v_lshl_add_u64 v[122:123], v[158:159], 2, s[10:11]
	s_waitcnt lgkmcnt(0)
	v_add_f32_e32 v120, v120, v121
	global_atomic_add_f32 v[122:123], v120, off

; DI unsigned pk2(float lo, float hi) { f32x2 v = {lo, hi}; bf16x2_t r = __builtin_convertvector(v, bf16x2_t); return __builtin_bit_cast(unsigned, r); }
; template <int EPI> ...
;     ...
;                 } else {
;                     *(f32x4*)(xout + (size_t)m * Nn + n0) = v0;
;                     *(f32x4*)(xout + (size_t)m * Nn + n0 + 4) = v1;
;                     if (hb) {
;                         const f32x4 g0 = *(const f32x4*)(gn + n0), g1 = *(const f32x4*)(gn + n0 + 4);
;                         u32x4 o4; o4[0] = pk2(v0[0] * g0[0], v0[1] * g0[1]); o4[1] = pk2(v0[2] * g0[2], v0[3] * g0[3]);
;                         o4[2] = pk2(v1[0] * g1[0], v1[1] * g1[1]); o4[3] = pk2(v1[2] * g1[2], v1[3] * g1[3]);
;                         *(u32x4*)(hb + (size_t)m * Nn + n0) = o4;
;                         sq += v0[0] * v0[0] + v0[1] * v0[1] + v0[2] * v0[2] + v0[3] * v0[3] + v1[0] * v1[0] + v1[1] * v1[1] + v1[2] * v1[2] + v1[3] * v1[3];
;                     }
;                 }
;             }
;             if (EPI == 2 && hb) {
;                 sq += __shfl_xor(sq, 16); sq += __shfl_xor(sq, 32);
;                 if (fq == 0) atomicAdd(ssq_out + m, sq);
.LBB0_703:
	v_readlane_b32 s52, v251, 34
	v_readlane_b32 s56, v251, 38
	v_readlane_b32 s57, v251, 39
	s_and_b64 vcc, exec, s[8:9]
	v_readlane_b32 s53, v251, 35
	s_waitcnt lgkmcnt(0)
	v_lshl_add_u64 v[120:121], s[56:57], 0, v[172:173]
	v_lshl_add_u64 v[120:121], v[120:121], 0, v[188:189]
	v_readlane_b32 s54, v251, 36
	v_readlane_b32 s55, v251, 37
	v_readlane_b32 s58, v251, 40
	v_readlane_b32 s59, v251, 41
	v_readlane_b32 s60, v251, 42
	v_readlane_b32 s61, v251, 43
	v_readlane_b32 s62, v251, 44
	v_readlane_b32 s63, v251, 45
	v_readlane_b32 s64, v251, 46
	v_readlane_b32 s65, v251, 47
	v_readlane_b32 s66, v251, 48
	v_readlane_b32 s67, v251, 49
	global_store_dwordx4 v[120:121], v[116:119], off
	global_store_dwordx4 v[120:121], v[112:115], off offset:16
	s_cbranch_vccnz .LBB0_717
	v_readlane_b32 s52, v251, 0
	v_lshlrev_b64 v[122:123], 5, v[170:171]
	v_readlane_b32 s66, v251, 14
	v_readlane_b32 s67, v251, 15
	v_mov_b32_e32 v165, v189
	v_readlane_b32 s53, v251, 1
	v_lshl_add_u64 v[130:131], v[122:123], 1, s[66:67]
	global_load_dwordx4 v[122:125], v188, s[12:13] offset:16
	global_load_dwordx4 v[126:129], v188, s[12:13]
	v_readlane_b32 s54, v251, 2
	v_readlane_b32 s55, v251, 3
	v_readlane_b32 s56, v251, 4
	v_readlane_b32 s57, v251, 5
	v_readlane_b32 s58, v251, 6
	v_readlane_b32 s59, v251, 7
	v_readlane_b32 s60, v251, 8
	v_readlane_b32 s61, v251, 9
	v_readlane_b32 s62, v251, 10
	v_readlane_b32 s63, v251, 11
	v_readlane_b32 s64, v251, 12
	v_readlane_b32 s65, v251, 13
	s_waitcnt vmcnt(1)
	v_pk_mul_f32 v[124:125], v[114:115], v[124:125]
	s_waitcnt vmcnt(0)
	v_pk_mul_f32 v[128:129], v[118:119], v[128:129]
	v_pk_mul_f32 v[126:127], v[116:117], v[126:127]
	v_pk_mul_f32 v[122:123], v[112:113], v[122:123]
	v_cvt_pk_bf16_f32 v126, v126, v127
	v_cvt_pk_bf16_f32 v127, v128, v129
	v_cvt_pk_bf16_f32 v129, v124, v125
	v_mul_f32_e32 v124, v117, v117
	v_fmac_f32_e32 v124, v116, v116
	v_fmac_f32_e32 v124, v118, v118
	v_fmac_f32_e32 v124, v119, v119
	v_fmac_f32_e32 v124, v112, v112
	v_cvt_pk_bf16_f32 v128, v122, v123
	v_lshl_add_u64 v[122:123], v[130:131], 0, v[164:165]
	v_fmac_f32_e32 v124, v113, v113
	global_store_dwordx4 v[122:123], v[126:129], off
	v_fmac_f32_e32 v124, v114, v114
	global_store_dwordx4 v[120:121], v[108:111], off offset:128
	global_store_dwordx4 v[120:121], v[104:107], off offset:144
	v_fmac_f32_e32 v124, v115, v115
	global_load_dwordx4 v[112:115], v188, s[12:13] offset:144
	global_load_dwordx4 v[116:119], v188, s[12:13] offset:128
	s_waitcnt vmcnt(1)
	v_pk_mul_f32 v[112:113], v[104:105], v[112:113]
	s_waitcnt vmcnt(0)
	v_pk_mul_f32 v[118:119], v[110:111], v[118:119]
	v_pk_mul_f32 v[116:117], v[108:109], v[116:117]
	v_pk_mul_f32 v[114:115], v[106:107], v[114:115]
	v_cvt_pk_bf16_f32 v116, v116, v117
	v_cvt_pk_bf16_f32 v117, v118, v119
	v_cvt_pk_bf16_f32 v118, v112, v113
	v_mul_f32_e32 v112, v109, v109
	v_fmac_f32_e32 v112, v108, v108
	v_fmac_f32_e32 v112, v110, v110
	v_fmac_f32_e32 v112, v111, v111
	v_fmac_f32_e32 v112, v104, v104
	v_fmac_f32_e32 v112, v105, v105
	v_cvt_pk_bf16_f32 v119, v114, v115
	v_fmac_f32_e32 v112, v106, v106
	v_lshl_add_u64 v[122:123], v[122:123], 0, v[254:255]
	global_store_dwordx4 v[122:123], v[116:119], off
	v_fmac_f32_e32 v112, v107, v107
	global_store_dwordx4 v[120:121], v[100:103], off offset:256
	global_store_dwordx4 v[120:121], v[96:99], off offset:272
	v_add_f32_e32 v124, v124, v112
	global_load_dwordx4 v[112:115], v188, s[12:13] offset:272
	global_load_dwordx4 v[116:119], v188, s[12:13] offset:256
	s_waitcnt vmcnt(1)
	v_pk_mul_f32 v[112:113], v[96:97], v[112:113]
	s_waitcnt vmcnt(0)
	v_pk_mul_f32 v[118:119], v[102:103], v[118:119]
	v_pk_mul_f32 v[116:117], v[100:101], v[116:117]
	v_pk_mul_f32 v[114:115], v[98:99], v[114:115]
	v_cvt_pk_bf16_f32 v116, v116, v117
	v_cvt_pk_bf16_f32 v117, v118, v119
	v_cvt_pk_bf16_f32 v118, v112, v113
	v_mul_f32_e32 v112, v101, v101
	v_fmac_f32_e32 v112, v100, v100
	v_fmac_f32_e32 v112, v102, v102
	v_fmac_f32_e32 v112, v103, v103
	v_fmac_f32_e32 v112, v96, v96
	v_fmac_f32_e32 v112, v97, v97
	v_cvt_pk_bf16_f32 v119, v114, v115
	v_fmac_f32_e32 v112, v98, v98
	v_lshl_add_u64 v[122:123], v[122:123], 0, v[254:255]
	global_store_dwordx4 v[122:123], v[116:119], off
	v_fmac_f32_e32 v112, v99, v99
	global_store_dwordx4 v[120:121], v[92:95], off offset:384
	global_store_dwordx4 v[120:121], v[88:91], off offset:400
	v_add_f32_e32 v124, v124, v112
	global_load_dwordx4 v[112:115], v188, s[12:13] offset:400
	global_load_dwordx4 v[116:119], v188, s[12:13] offset:384
	s_waitcnt vmcnt(1)
	v_pk_mul_f32 v[112:113], v[88:89], v[112:113]
	s_waitcnt vmcnt(0)
	v_pk_mul_f32 v[118:119], v[94:95], v[118:119]
	v_pk_mul_f32 v[116:117], v[92:93], v[116:117]
	v_pk_mul_f32 v[114:115], v[90:91], v[114:115]
	v_cvt_pk_bf16_f32 v116, v116, v117
	v_cvt_pk_bf16_f32 v117, v118, v119
	v_cvt_pk_bf16_f32 v118, v112, v113
	v_mul_f32_e32 v112, v93, v93
	v_fmac_f32_e32 v112, v92, v92
	v_fmac_f32_e32 v112, v94, v94
	v_fmac_f32_e32 v112, v95, v95
	v_fmac_f32_e32 v112, v88, v88
	v_fmac_f32_e32 v112, v89, v89
	v_fmac_f32_e32 v112, v90, v90
	v_fmac_f32_e32 v112, v91, v91
	v_add_f32_e32 v112, v124, v112
	ds_bpermute_b32 v113, v230, v112
	v_cvt_pk_bf16_f32 v119, v114, v115
	v_lshl_add_u64 v[122:123], v[122:123], 0, v[254:255]
	global_store_dwordx4 v[122:123], v[116:119], off
	s_waitcnt lgkmcnt(0)
	v_add_f32_e32 v112, v112, v113
	ds_bpermute_b32 v113, v191, v112
	s_and_saveexec_b64 s[16:17], s[6:7]
	s_cbranch_execz .LBB0_706
	v_lshl_add_u64 v[114:115], v[158:159], 2, s[10:11]
	s_waitcnt lgkmcnt(0)
	v_add_f32_e32 v112, v112, v113
	global_atomic_add_f32 v[114:115], v112, off offset:64

; template <int EPI> ...
;     ...
;         for (int i = 0; i < 4; ++i) {
;             const int m = mt * 128 + wr * 64 + i * 16 + fr;
;             float rsc = 1.f;
;             if (EPI != 2 && rs_in) rsc = rsqrtf(rs_in[m] * (1.f / DM) + 1e-6f);
;             float sq = 0.f;
; #pragma unroll
;             for (int jp = 0; jp < 4; ++jp) {
;                 const int n0 = nt * 256 + wc * 128 + 32 * jp + 8 * fq;
;                 f32x4 v0 = acc[i][2 * jp] * rsc, v1 = acc[i][2 * jp + 1] * rsc;
;                 if (EPI == 0) {
;                     u32x4 o4; o4[0] = pk2(v0[0], v0[1]); o4[1] = pk2(v0[2], v0[3]); o4[2] = pk2(v1[0], v1[1]); o4[3] = pk2(v1[2], v1[3]);
;                     *(u32x4*)(outb + (size_t)m * Nn + n0) = o4;
;                     if (n0 >= C_BA && n0 < C_BA + 12) *(f32x4*)(side + (size_t)m * 12 + (n0 - C_BA)) = v0;
;                     if (n0 + 4 >= C_BA && n0 + 4 < C_BA + 12) *(f32x4*)(side + (size_t)m * 12 + (n0 + 4 - C_BA)) = v1;
;                 } else if (EPI == 1) {
; #pragma unroll
;                     for (int e = 0; e < 4; ++e) { const float r0 = fmaxf(v0[e], 0.f), r1 = fmaxf(v1[e], 0.f); v0[e] = r0 * r0; v1[e] = r1 * r1; }
;                     u32x4 o4; o4[0] = pk2(v0[0], v0[1]); o4[1] = pk2(v0[2], v0[3]); o4[2] = pk2(v1[0], v1[1]); o4[3] = pk2(v1[2], v1[3]);
;                     *(u32x4*)(outb + (size_t)m * Nn + n0) = o4;
;                 } else {
;                     *(f32x4*)(xout + (size_t)m * Nn + n0) = v0;
;                     *(f32x4*)(xout + (size_t)m * Nn + n0 + 4) = v1;
;                     if (hb) {
;                         const f32x4 g0 = *(const f32x4*)(gn + n0), g1 = *(const f32x4*)(gn + n0 + 4);
;                         u32x4 o4; o4[0] = pk2(v0[0] * g0[0], v0[1] * g0[1]); o4[1] = pk2(v0[2] * g0[2], v0[3] * g0[3]);
;                         o4[2] = pk2(v1[0] * g1[0], v1[1] * g1[1]); o4[3] = pk2(v1[2] * g1[2], v1[3] * g1[3]);
;                         *(u32x4*)(hb + (size_t)m * Nn + n0) = o4;
;                         sq += v0[0] * v0[0] + v0[1] * v0[1] + v0[2] * v0[2] + v0[3] * v0[3] + v1[0] * v1[0] + v1[1] * v1[1] + v1[2] * v1[2] + v1[3] * v1[3];
;                     }
;                 }
;             }
;             if (EPI == 2 && hb) {
;                 sq += __shfl_xor(sq, 16); sq += __shfl_xor(sq, 32);
;                 if (fq == 0) atomicAdd(ssq_out + m, sq);
;             }
.LBB0_708:
	v_readlane_b32 s52, v251, 34
	v_readlane_b32 s56, v251, 38
	v_readlane_b32 s57, v251, 39
	s_and_b64 vcc, exec, s[8:9]
	v_readlane_b32 s53, v251, 35
	v_lshl_add_u64 v[88:89], s[56:57], 0, v[168:169]
	v_lshl_add_u64 v[88:89], v[88:89], 0, v[188:189]
	v_readlane_b32 s54, v251, 36
	v_readlane_b32 s55, v251, 37
	v_readlane_b32 s58, v251, 40
	v_readlane_b32 s59, v251, 41
	v_readlane_b32 s60, v251, 42
	v_readlane_b32 s61, v251, 43
	v_readlane_b32 s62, v251, 44
	v_readlane_b32 s63, v251, 45
	v_readlane_b32 s64, v251, 46
	v_readlane_b32 s65, v251, 47
	v_readlane_b32 s66, v251, 48
	v_readlane_b32 s67, v251, 49
	global_store_dwordx4 v[88:89], v[84:87], off
	global_store_dwordx4 v[88:89], v[80:83], off offset:16
	s_cbranch_vccnz .LBB0_718
	v_readlane_b32 s52, v251, 0
	v_lshlrev_b64 v[90:91], 5, v[166:167]
	v_readlane_b32 s66, v251, 14
	v_readlane_b32 s67, v251, 15
	v_mov_b32_e32 v165, v189
	v_readlane_b32 s53, v251, 1
	v_lshl_add_u64 v[98:99], v[90:91], 1, s[66:67]
	global_load_dwordx4 v[90:93], v188, s[12:13] offset:16
	global_load_dwordx4 v[94:97], v188, s[12:13]
	v_readlane_b32 s54, v251, 2
	v_readlane_b32 s55, v251, 3
	v_readlane_b32 s56, v251, 4
	v_readlane_b32 s57, v251, 5
	v_readlane_b32 s58, v251, 6
	v_readlane_b32 s59, v251, 7
	v_readlane_b32 s60, v251, 8
	v_readlane_b32 s61, v251, 9
	v_readlane_b32 s62, v251, 10
	v_readlane_b32 s63, v251, 11
	v_readlane_b32 s64, v251, 12
	v_readlane_b32 s65, v251, 13
	s_waitcnt vmcnt(1)
	v_pk_mul_f32 v[92:93], v[82:83], v[92:93]
	s_waitcnt vmcnt(0)
	v_pk_mul_f32 v[96:97], v[86:87], v[96:97]
	v_pk_mul_f32 v[94:95], v[84:85], v[94:95]
	v_pk_mul_f32 v[90:91], v[80:81], v[90:91]
	v_cvt_pk_bf16_f32 v94, v94, v95
	v_cvt_pk_bf16_f32 v95, v96, v97
	v_cvt_pk_bf16_f32 v97, v92, v93
	v_mul_f32_e32 v92, v85, v85
	v_fmac_f32_e32 v92, v84, v84
	v_fmac_f32_e32 v92, v86, v86
	v_fmac_f32_e32 v92, v87, v87
	v_fmac_f32_e32 v92, v80, v80
	v_cvt_pk_bf16_f32 v96, v90, v91
	v_lshl_add_u64 v[90:91], v[98:99], 0, v[164:165]
	v_fmac_f32_e32 v92, v81, v81
	global_store_dwordx4 v[90:91], v[94:97], off
	v_fmac_f32_e32 v92, v82, v82
	global_store_dwordx4 v[88:89], v[76:79], off offset:128
	global_store_dwordx4 v[88:89], v[72:75], off offset:144
	v_fmac_f32_e32 v92, v83, v83
	global_load_dwordx4 v[80:83], v188, s[12:13] offset:144
	global_load_dwordx4 v[84:87], v188, s[12:13] offset:128
	s_waitcnt vmcnt(1)
	v_pk_mul_f32 v[80:81], v[72:73], v[80:81]
	s_waitcnt vmcnt(0)
	v_pk_mul_f32 v[86:87], v[78:79], v[86:87]
	v_pk_mul_f32 v[84:85], v[76:77], v[84:85]
	v_pk_mul_f32 v[82:83], v[74:75], v[82:83]
	v_cvt_pk_bf16_f32 v84, v84, v85
	v_cvt_pk_bf16_f32 v85, v86, v87
	v_cvt_pk_bf16_f32 v86, v80, v81
	v_mul_f32_e32 v80, v77, v77
	v_fmac_f32_e32 v80, v76, v76
	v_fmac_f32_e32 v80, v78, v78
	v_fmac_f32_e32 v80, v79, v79
	v_fmac_f32_e32 v80, v72, v72
	v_fmac_f32_e32 v80, v73, v73
	v_cvt_pk_bf16_f32 v87, v82, v83
	v_fmac_f32_e32 v80, v74, v74
	v_lshl_add_u64 v[90:91], v[90:91], 0, v[254:255]
	global_store_dwordx4 v[90:91], v[84:87], off
	v_fmac_f32_e32 v80, v75, v75
	global_store_dwordx4 v[88:89], v[68:71], off offset:256
	global_store_dwordx4 v[88:89], v[64:67], off offset:272
	v_add_f32_e32 v92, v92, v80
	global_load_dwordx4 v[80:83], v188, s[12:13] offset:272
	global_load_dwordx4 v[84:87], v188, s[12:13] offset:256
	s_waitcnt vmcnt(1)
	v_pk_mul_f32 v[80:81], v[64:65], v[80:81]
	s_waitcnt vmcnt(0)
	v_pk_mul_f32 v[86:87], v[70:71], v[86:87]
	v_pk_mul_f32 v[84:85], v[68:69], v[84:85]
	v_pk_mul_f32 v[82:83], v[66:67], v[82:83]
	v_cvt_pk_bf16_f32 v84, v84, v85
	v_cvt_pk_bf16_f32 v85, v86, v87
	v_cvt_pk_bf16_f32 v86, v80, v81
	v_mul_f32_e32 v80, v69, v69
	v_fmac_f32_e32 v80, v68, v68
	v_fmac_f32_e32 v80, v70, v70
	v_fmac_f32_e32 v80, v71, v71
	v_fmac_f32_e32 v80, v64, v64
	v_fmac_f32_e32 v80, v65, v65
	v_cvt_pk_bf16_f32 v87, v82, v83
	v_fmac_f32_e32 v80, v66, v66
	v_lshl_add_u64 v[90:91], v[90:91], 0, v[254:255]
	global_store_dwordx4 v[90:91], v[84:87], off
	v_fmac_f32_e32 v80, v67, v67
	global_store_dwordx4 v[88:89], v[60:63], off offset:384
	global_store_dwordx4 v[88:89], v[56:59], off offset:400
	v_add_f32_e32 v92, v92, v80
	global_load_dwordx4 v[80:83], v188, s[12:13] offset:400
	global_load_dwordx4 v[84:87], v188, s[12:13] offset:384
	s_waitcnt vmcnt(1)
	v_pk_mul_f32 v[80:81], v[56:57], v[80:81]
	s_waitcnt vmcnt(0)
	v_pk_mul_f32 v[86:87], v[62:63], v[86:87]
	v_pk_mul_f32 v[84:85], v[60:61], v[84:85]
	v_pk_mul_f32 v[82:83], v[58:59], v[82:83]
	v_cvt_pk_bf16_f32 v84, v84, v85
	v_cvt_pk_bf16_f32 v85, v86, v87
	v_cvt_pk_bf16_f32 v86, v80, v81
	v_mul_f32_e32 v80, v61, v61
	v_fmac_f32_e32 v80, v60, v60
	v_fmac_f32_e32 v80, v62, v62
	v_fmac_f32_e32 v80, v63, v63
	v_fmac_f32_e32 v80, v56, v56
	v_fmac_f32_e32 v80, v57, v57
	v_fmac_f32_e32 v80, v58, v58
	v_fmac_f32_e32 v80, v59, v59
	v_add_f32_e32 v80, v92, v80
	ds_bpermute_b32 v81, v230, v80
	v_cvt_pk_bf16_f32 v87, v82, v83
	v_lshl_add_u64 v[90:91], v[90:91], 0, v[254:255]
	global_store_dwordx4 v[90:91], v[84:87], off
	s_waitcnt lgkmcnt(0)
	v_add_f32_e32 v80, v80, v81
	ds_bpermute_b32 v81, v191, v80
	s_and_saveexec_b64 s[16:17], s[6:7]
	s_cbranch_execz .LBB0_711
	v_lshl_add_u64 v[82:83], v[158:159], 2, s[10:11]
	s_waitcnt lgkmcnt(0)
	v_add_f32_e32 v80, v80, v81
	global_atomic_add_f32 v[82:83], v80, off offset:128

; template <int EPI> ...
;     ...
;         for (int i = 0; i < 4; ++i) {
;             const int m = mt * 128 + wr * 64 + i * 16 + fr;
;             float rsc = 1.f;
;             if (EPI != 2 && rs_in) rsc = rsqrtf(rs_in[m] * (1.f / DM) + 1e-6f);
;             float sq = 0.f;
; #pragma unroll
;             for (int jp = 0; jp < 4; ++jp) {
;                 const int n0 = nt * 256 + wc * 128 + 32 * jp + 8 * fq;
;                 f32x4 v0 = acc[i][2 * jp] * rsc, v1 = acc[i][2 * jp + 1] * rsc;
;                 if (EPI == 0) {
;                     u32x4 o4; o4[0] = pk2(v0[0], v0[1]); o4[1] = pk2(v0[2], v0[3]); o4[2] = pk2(v1[0], v1[1]); o4[3] = pk2(v1[2], v1[3]);
;                     *(u32x4*)(outb + (size_t)m * Nn + n0) = o4;
;                     if (n0 >= C_BA && n0 < C_BA + 12) *(f32x4*)(side + (size_t)m * 12 + (n0 - C_BA)) = v0;
;                     if (n0 + 4 >= C_BA && n0 + 4 < C_BA + 12) *(f32x4*)(side + (size_t)m * 12 + (n0 + 4 - C_BA)) = v1;
;                 } else if (EPI == 1) {
; #pragma unroll
;                     for (int e = 0; e < 4; ++e) { const float r0 = fmaxf(v0[e], 0.f), r1 = fmaxf(v1[e], 0.f); v0[e] = r0 * r0; v1[e] = r1 * r1; }
;                     u32x4 o4; o4[0] = pk2(v0[0], v0[1]); o4[1] = pk2(v0[2], v0[3]); o4[2] = pk2(v1[0], v1[1]); o4[3] = pk2(v1[2], v1[3]);
;                     *(u32x4*)(outb + (size_t)m * Nn + n0) = o4;
;                 } else {
;                     *(f32x4*)(xout + (size_t)m * Nn + n0) = v0;
;                     *(f32x4*)(xout + (size_t)m * Nn + n0 + 4) = v1;
;                     if (hb) {
;                         const f32x4 g0 = *(const f32x4*)(gn + n0), g1 = *(const f32x4*)(gn + n0 + 4);
;                         u32x4 o4; o4[0] = pk2(v0[0] * g0[0], v0[1] * g0[1]); o4[1] = pk2(v0[2] * g0[2], v0[3] * g0[3]);
;                         o4[2] = pk2(v1[0] * g1[0], v1[1] * g1[1]); o4[3] = pk2(v1[2] * g1[2], v1[3] * g1[3]);
;                         *(u32x4*)(hb + (size_t)m * Nn + n0) = o4;
;                         sq += v0[0] * v0[0] + v0[1] * v0[1] + v0[2] * v0[2] + v0[3] * v0[3] + v1[0] * v1[0] + v1[1] * v1[1] + v1[2] * v1[2] + v1[3] * v1[3];
;                     }
;                 }
;             }
;             if (EPI == 2 && hb) {
;                 sq += __shfl_xor(sq, 16); sq += __shfl_xor(sq, 32);
;                 if (fq == 0) atomicAdd(ssq_out + m, sq);
;             }
.LBB0_713:
	v_readlane_b32 s52, v251, 34
	v_readlane_b32 s56, v251, 38
	v_readlane_b32 s57, v251, 39
	s_and_b64 vcc, exec, s[8:9]
	v_readlane_b32 s53, v251, 35
	v_lshl_add_u64 v[56:57], s[56:57], 0, v[162:163]
	v_lshl_add_u64 v[56:57], v[56:57], 0, v[188:189]
	v_readlane_b32 s54, v251, 36
	v_readlane_b32 s55, v251, 37
	v_readlane_b32 s58, v251, 40
	v_readlane_b32 s59, v251, 41
	v_readlane_b32 s60, v251, 42
	v_readlane_b32 s61, v251, 43
	v_readlane_b32 s62, v251, 44
	v_readlane_b32 s63, v251, 45
	v_readlane_b32 s64, v251, 46
	v_readlane_b32 s65, v251, 47
	v_readlane_b32 s66, v251, 48
	v_readlane_b32 s67, v251, 49
	global_store_dwordx4 v[56:57], v[52:55], off
	global_store_dwordx4 v[56:57], v[48:51], off offset:16
	s_cbranch_vccnz .LBB0_719
	global_load_dwordx4 v[58:61], v188, s[12:13]
	global_load_dwordx4 v[62:65], v188, s[12:13] offset:16
	v_readlane_b32 s52, v251, 0
	v_lshlrev_b64 v[66:67], 5, v[160:161]
	v_readlane_b32 s66, v251, 14
	v_readlane_b32 s67, v251, 15
	v_mov_b32_e32 v165, v189
	v_mul_f32_e32 v68, v45, v45
	v_lshl_add_u64 v[66:67], v[66:67], 1, s[66:67]
	v_lshl_add_u64 v[66:67], v[66:67], 0, v[164:165]
	v_mul_f32_e32 v69, v37, v37
	v_fmac_f32_e32 v68, v44, v44
	v_mul_f32_e32 v70, v29, v29
	v_fmac_f32_e32 v69, v36, v36
	v_fmac_f32_e32 v68, v46, v46
	v_fmac_f32_e32 v70, v28, v28
	v_fmac_f32_e32 v69, v38, v38
	v_fmac_f32_e32 v68, v47, v47
	v_fmac_f32_e32 v70, v30, v30
	v_fmac_f32_e32 v69, v39, v39
	v_fmac_f32_e32 v68, v40, v40
	v_fmac_f32_e32 v70, v31, v31
	v_fmac_f32_e32 v69, v32, v32
	v_fmac_f32_e32 v68, v41, v41
	v_fmac_f32_e32 v70, v24, v24
	v_fmac_f32_e32 v69, v33, v33
	v_fmac_f32_e32 v68, v42, v42
	v_fmac_f32_e32 v70, v25, v25
	v_fmac_f32_e32 v69, v34, v34
	v_fmac_f32_e32 v68, v43, v43
	v_fmac_f32_e32 v70, v26, v26
	v_fmac_f32_e32 v69, v35, v35
	v_fmac_f32_e32 v70, v27, v27
	v_readlane_b32 s53, v251, 1
	v_readlane_b32 s54, v251, 2
	v_readlane_b32 s55, v251, 3
	v_readlane_b32 s56, v251, 4
	v_readlane_b32 s57, v251, 5
	v_readlane_b32 s58, v251, 6
	v_readlane_b32 s59, v251, 7
	v_readlane_b32 s60, v251, 8
	v_readlane_b32 s61, v251, 9
	v_readlane_b32 s62, v251, 10
	v_readlane_b32 s63, v251, 11
	v_readlane_b32 s64, v251, 12
	v_readlane_b32 s65, v251, 13
	s_waitcnt vmcnt(1)
	v_pk_mul_f32 v[60:61], v[54:55], v[60:61]
	v_pk_mul_f32 v[58:59], v[52:53], v[58:59]
	s_waitcnt vmcnt(0)
	v_pk_mul_f32 v[64:65], v[50:51], v[64:65]
	v_pk_mul_f32 v[62:63], v[48:49], v[62:63]
	v_cvt_pk_bf16_f32 v58, v58, v59
	v_cvt_pk_bf16_f32 v59, v60, v61
	v_cvt_pk_bf16_f32 v60, v62, v63
	v_cvt_pk_bf16_f32 v61, v64, v65
	global_store_dwordx4 v[66:67], v[58:61], off
	global_store_dwordx4 v[56:57], v[44:47], off offset:128
	global_store_dwordx4 v[56:57], v[40:43], off offset:144
	global_load_dwordx4 v[58:61], v188, s[12:13] offset:128
	s_nop 0
	global_load_dwordx4 v[62:65], v188, s[12:13] offset:144
	v_mul_f32_e32 v53, v53, v53
	v_fmac_f32_e32 v53, v52, v52
	v_fmac_f32_e32 v53, v54, v54
	v_fmac_f32_e32 v53, v55, v55
	v_fmac_f32_e32 v53, v48, v48
	v_fmac_f32_e32 v53, v49, v49
	v_fmac_f32_e32 v53, v50, v50
	v_fmac_f32_e32 v53, v51, v51
	v_add_f32_e32 v48, v53, v68
	v_add_f32_e32 v48, v48, v69
	v_add_f32_e32 v48, v48, v70
	ds_bpermute_b32 v49, v230, v48
	s_waitcnt lgkmcnt(0)
	v_add_f32_e32 v48, v48, v49
	ds_bpermute_b32 v49, v191, v48
	s_waitcnt vmcnt(1)
	v_pk_mul_f32 v[60:61], v[46:47], v[60:61]
	v_pk_mul_f32 v[58:59], v[44:45], v[58:59]
	s_waitcnt vmcnt(0)
	v_pk_mul_f32 v[64:65], v[42:43], v[64:65]
	v_pk_mul_f32 v[62:63], v[40:41], v[62:63]
	v_cvt_pk_bf16_f32 v58, v58, v59
	v_cvt_pk_bf16_f32 v59, v60, v61
	v_cvt_pk_bf16_f32 v60, v62, v63
	v_cvt_pk_bf16_f32 v61, v64, v65
	v_lshl_add_u64 v[66:67], v[66:67], 0, v[254:255]
	global_store_dwordx4 v[66:67], v[58:61], off
	global_store_dwordx4 v[56:57], v[36:39], off offset:256
	global_store_dwordx4 v[56:57], v[32:35], off offset:272
	global_load_dwordx4 v[58:61], v188, s[12:13] offset:256
	s_nop 0
	global_load_dwordx4 v[62:65], v188, s[12:13] offset:272
	s_waitcnt vmcnt(1)
	v_pk_mul_f32 v[60:61], v[38:39], v[60:61]
	v_pk_mul_f32 v[58:59], v[36:37], v[58:59]
	s_waitcnt vmcnt(0)
	v_pk_mul_f32 v[64:65], v[34:35], v[64:65]
	v_pk_mul_f32 v[62:63], v[32:33], v[62:63]
	v_cvt_pk_bf16_f32 v58, v58, v59
	v_cvt_pk_bf16_f32 v59, v60, v61
	v_cvt_pk_bf16_f32 v60, v62, v63
	v_cvt_pk_bf16_f32 v61, v64, v65
	v_lshl_add_u64 v[66:67], v[66:67], 0, v[254:255]
	global_store_dwordx4 v[66:67], v[58:61], off
	global_store_dwordx4 v[56:57], v[28:31], off offset:384
	global_store_dwordx4 v[56:57], v[24:27], off offset:400
	global_load_dwordx4 v[58:61], v188, s[12:13] offset:384
	s_nop 0
	global_load_dwordx4 v[62:65], v188, s[12:13] offset:400
	s_waitcnt vmcnt(1)
	v_pk_mul_f32 v[52:53], v[30:31], v[60:61]
	v_pk_mul_f32 v[50:51], v[28:29], v[58:59]
	s_waitcnt vmcnt(0)
	v_pk_mul_f32 v[54:55], v[26:27], v[64:65]
	v_pk_mul_f32 v[58:59], v[24:25], v[62:63]
	v_cvt_pk_bf16_f32 v50, v50, v51
	v_cvt_pk_bf16_f32 v51, v52, v53
	v_cvt_pk_bf16_f32 v52, v58, v59
	v_cvt_pk_bf16_f32 v53, v54, v55
	v_lshl_add_u64 v[66:67], v[66:67], 0, v[254:255]
	global_store_dwordx4 v[66:67], v[50:53], off
	s_and_saveexec_b64 s[8:9], s[6:7]
	s_cbranch_execz .LBB0_716
	v_lshl_add_u64 v[50:51], v[158:159], 2, s[10:11]
	s_waitcnt lgkmcnt(0)
	v_add_f32_e32 v48, v48, v49
	global_atomic_add_f32 v[50:51], v48, off offset:192

; DI unsigned pk2(float lo, float hi) { f32x2 v = {lo, hi}; bf16x2_t r = __builtin_convertvector(v, bf16x2_t); return __builtin_bit_cast(unsigned, r); }
; template <int EPI> ...
;     ...
;         for (int i = 0; i < 4; ++i) {
;             const int m = mt * 128 + wr * 64 + i * 16 + fr;
;             float rsc = 1.f;
;             if (EPI != 2 && rs_in) rsc = rsqrtf(rs_in[m] * (1.f / DM) + 1e-6f);
;             float sq = 0.f;
; #pragma unroll
;             for (int jp = 0; jp < 4; ++jp) {
;                 const int n0 = nt * 256 + wc * 128 + 32 * jp + 8 * fq;
;                 f32x4 v0 = acc[i][2 * jp] * rsc, v1 = acc[i][2 * jp + 1] * rsc;
;                 if (EPI == 0) {
;                     u32x4 o4; o4[0] = pk2(v0[0], v0[1]); o4[1] = pk2(v0[2], v0[3]); o4[2] = pk2(v1[0], v1[1]); o4[3] = pk2(v1[2], v1[3]);
;                     *(u32x4*)(outb + (size_t)m * Nn + n0) = o4;
;                     if (n0 >= C_BA && n0 < C_BA + 12) *(f32x4*)(side + (size_t)m * 12 + (n0 - C_BA)) = v0;
;                     if (n0 + 4 >= C_BA && n0 + 4 < C_BA + 12) *(f32x4*)(side + (size_t)m * 12 + (n0 + 4 - C_BA)) = v1;
;                 } else if (EPI == 1) {
; #pragma unroll
;                     for (int e = 0; e < 4; ++e) { const float r0 = fmaxf(v0[e], 0.f), r1 = fmaxf(v1[e], 0.f); v0[e] = r0 * r0; v1[e] = r1 * r1; }
;                     u32x4 o4; o4[0] = pk2(v0[0], v0[1]); o4[1] = pk2(v0[2], v0[3]); o4[2] = pk2(v1[0], v1[1]); o4[3] = pk2(v1[2], v1[3]);
;                     *(u32x4*)(outb + (size_t)m * Nn + n0) = o4;
.LBB0_776:
	s_nop 0
	v_or_b32_e32 v56, 48, v154
	v_pk_mul_f32 v[48:49], v[48:49], v[88:89] op_sel_hi:[1,0]
	v_ashrrev_i32_e32 v57, 31, v56
	v_readlane_b32 s52, v250, 51
	v_pk_mul_f32 v[54:55], v[54:55], v[88:89] op_sel_hi:[1,0]
	v_pk_mul_f32 v[52:53], v[52:53], v[88:89] op_sel_hi:[1,0]
	v_pk_mul_f32 v[50:51], v[50:51], v[88:89] op_sel_hi:[1,0]
	v_max_f32_e32 v48, 0, v48
	v_max_f32_e32 v49, 0, v49
	v_lshlrev_b64 v[56:57], 6, v[56:57]
	v_readlane_b32 s58, v250, 57
	v_readlane_b32 s59, v250, 58
	v_max_f32_e32 v52, 0, v52
	v_max_f32_e32 v53, 0, v53
	v_pk_mul_f32 v[58:59], v[48:49], v[48:49]
	v_max_f32_e32 v48, 0, v54
	v_max_f32_e32 v50, 0, v50
	v_max_f32_e32 v49, 0, v55
	v_max_f32_e32 v51, 0, v51
	v_lshl_add_u64 v[56:57], s[58:59], 0, v[56:57]
	v_pk_mul_f32 v[52:53], v[52:53], v[52:53]
	v_pk_mul_f32 v[54:55], v[48:49], v[48:49]
	v_pk_mul_f32 v[60:61], v[50:51], v[50:51]
	v_pk_mul_f32 v[40:41], v[40:41], v[88:89] op_sel_hi:[1,0]
	v_cvt_pk_bf16_f32 v48, v52, v53
	v_cvt_pk_bf16_f32 v49, v54, v55
	v_cvt_pk_bf16_f32 v50, v58, v59
	v_cvt_pk_bf16_f32 v51, v60, v61
	v_lshl_add_u64 v[52:53], v[152:153], 1, v[56:57]
	v_pk_mul_f32 v[46:47], v[46:47], v[88:89] op_sel_hi:[1,0]
	v_pk_mul_f32 v[44:45], v[44:45], v[88:89] op_sel_hi:[1,0]
	v_pk_mul_f32 v[42:43], v[42:43], v[88:89] op_sel_hi:[1,0]
	v_max_f32_e32 v40, 0, v40
	v_max_f32_e32 v41, 0, v41
	global_store_dwordx4 v[52:53], v[48:51], off
	v_max_f32_e32 v44, 0, v44
	v_max_f32_e32 v45, 0, v45
	v_pk_mul_f32 v[48:49], v[40:41], v[40:41]
	v_max_f32_e32 v40, 0, v46
	v_max_f32_e32 v42, 0, v42
	v_max_f32_e32 v41, 0, v47
	v_max_f32_e32 v43, 0, v43
	v_pk_mul_f32 v[44:45], v[44:45], v[44:45]
	v_pk_mul_f32 v[46:47], v[40:41], v[40:41]
	v_pk_mul_f32 v[50:51], v[42:43], v[42:43]
	v_pk_mul_f32 v[32:33], v[32:33], v[88:89] op_sel_hi:[1,0]
	v_cvt_pk_bf16_f32 v40, v44, v45
	v_cvt_pk_bf16_f32 v41, v46, v47
	v_cvt_pk_bf16_f32 v42, v48, v49
	v_cvt_pk_bf16_f32 v43, v50, v51
	v_pk_mul_f32 v[38:39], v[38:39], v[88:89] op_sel_hi:[1,0]
	v_pk_mul_f32 v[36:37], v[36:37], v[88:89] op_sel_hi:[1,0]
	v_pk_mul_f32 v[34:35], v[34:35], v[88:89] op_sel_hi:[1,0]
	v_max_f32_e32 v32, 0, v32
	v_max_f32_e32 v33, 0, v33
	v_lshl_add_u64 v[52:53], v[52:53], 0, v[254:255]
	global_store_dwordx4 v[52:53], v[40:43], off
	v_max_f32_e32 v36, 0, v36
	v_max_f32_e32 v37, 0, v37
	v_pk_mul_f32 v[40:41], v[32:33], v[32:33]
	v_max_f32_e32 v32, 0, v38
	v_max_f32_e32 v34, 0, v34
	v_max_f32_e32 v33, 0, v39
	v_max_f32_e32 v35, 0, v35
	v_pk_mul_f32 v[36:37], v[36:37], v[36:37]
	v_pk_mul_f32 v[38:39], v[32:33], v[32:33]
	v_pk_mul_f32 v[42:43], v[34:35], v[34:35]
	v_pk_mul_f32 v[24:25], v[24:25], v[88:89] op_sel_hi:[1,0]
	v_cvt_pk_bf16_f32 v32, v36, v37
	v_cvt_pk_bf16_f32 v33, v38, v39
	v_cvt_pk_bf16_f32 v34, v40, v41
	v_cvt_pk_bf16_f32 v35, v42, v43
	v_pk_mul_f32 v[30:31], v[30:31], v[88:89] op_sel_hi:[1,0]
	v_pk_mul_f32 v[28:29], v[28:29], v[88:89] op_sel_hi:[1,0]
	v_pk_mul_f32 v[26:27], v[26:27], v[88:89] op_sel_hi:[1,0]
	v_max_f32_e32 v24, 0, v24
	v_max_f32_e32 v25, 0, v25
	v_lshl_add_u64 v[52:53], v[52:53], 0, v[254:255]
	global_store_dwordx4 v[52:53], v[32:35], off
	v_max_f32_e32 v28, 0, v28
	v_max_f32_e32 v29, 0, v29
	v_pk_mul_f32 v[32:33], v[24:25], v[24:25]
	v_max_f32_e32 v24, 0, v30
	v_max_f32_e32 v26, 0, v26
	v_max_f32_e32 v25, 0, v31
	v_max_f32_e32 v27, 0, v27
	v_pk_mul_f32 v[28:29], v[28:29], v[28:29]
	v_pk_mul_f32 v[30:31], v[24:25], v[24:25]
	v_pk_mul_f32 v[34:35], v[26:27], v[26:27]
	v_cvt_pk_bf16_f32 v24, v28, v29
	v_cvt_pk_bf16_f32 v25, v30, v31
	v_cvt_pk_bf16_f32 v26, v32, v33
	v_cvt_pk_bf16_f32 v27, v34, v35
	s_andn2_b64 vcc, exec, s[8:9]
	v_readlane_b32 s53, v250, 52
	v_readlane_b32 s54, v250, 53
	v_readlane_b32 s55, v250, 54
	v_readlane_b32 s56, v250, 55
	v_readlane_b32 s57, v250, 56
	v_readlane_b32 s60, v250, 59
	v_readlane_b32 s61, v250, 60
	v_readlane_b32 s62, v250, 61
	v_readlane_b32 s63, v250, 62
	v_readlane_b32 s64, v250, 63
	v_readlane_b32 s65, v249, 0
	v_readlane_b32 s66, v249, 1
	v_readlane_b32 s67, v249, 2
	v_lshl_add_u64 v[52:53], v[52:53], 0, v[254:255]
	global_store_dwordx4 v[52:53], v[24:27], off
	s_cbranch_vccz .LBB0_787

; template <int EPI> ...
;     ...
;     const int idx0 = blockIdx.x >> 3;
;     if (idx0 < perX) {
;         int mt0, nt0; tile_of(idx0, mt0, nt0);
;         const bf16_t* A0 = A + (size_t)(mt0 * 128 + lrow) * K + lcc * 8;
;         const bf16_t* B0 = Bt + (size_t)(nt0 * 256 + lrowp) * K + lcc * 8;
;         G_LOAD(A0, B0, 0);
;         G_STORE(0);
;         G_LOAD(A0, B0, 1);
;         __syncthreads();
;     }
;     for (int idx = idx0; idx < perX; idx += nbx) {
;         int mt, nt; tile_of(idx, mt, nt);
;         int mtn, ntn; tile_of(idx + nbx < perX ? idx + nbx : idx, mtn, ntn);
;         const bf16_t* Ag = A + (size_t)(mt * 128 + lrow) * K + lcc * 8;
;         const bf16_t* Bg = Bt + (size_t)(nt * 256 + lrowp) * K + lcc * 8;
;         const bf16_t* An = A + (size_t)(mtn * 128 + lrow) * K + lcc * 8;
;         const bf16_t* Bn = Bt + (size_t)(ntn * 256 + lrowp) * K + lcc * 8;
;         f32x4 acc[4][8];
; #pragma unroll
;         for (int i = 0; i < 4; ++i)
; #pragma unroll
;             for (int j = 0; j < 8; ++j) {
;                 if (EPI == 2)
;                     acc[i][j] = *(const f32x4*)(xin + (size_t)(mt * 128 + wr * 64 + i * 16 + fr) * Nn + nt * 256 + wc * 128 + 32 * (j >> 1) + 8 * fq + 4 * (j & 1));
;                 else acc[i][j] = (f32x4){0.f, 0.f, 0.f, 0.f};
;             }
;         for (int kt = 0; kt < nk; ++kt) {
;             const int buf = kt & 1;
;             const bf16_t* a_ = sA + buf * 128 * 40 + (wr * 64 + fr) * 40 + fq * 8;
;             const bf16_t* b_ = sB + buf * 256 * 40 + (wc * 128 + fr) * 40 + fq * 8;
;             bf16x8 af[4];
; #pragma unroll
;             for (int i = 0; i < 4; ++i) af[i] = *(const bf16x8*)(a_ + i * 16 * 40);
; #pragma unroll
;             for (int jh = 0; jh < 2; ++jh) {
;                 bf16x8 bfr[4];
; #pragma unroll
;                 for (int j = 0; j < 4; ++j) bfr[j] = *(const bf16x8*)(b_ + (jh * 4 + j) * 16 * 40);
; #pragma unroll
;                 for (int i = 0; i < 4; ++i)
; #pragma unroll
;                     for (int j = 0; j < 4; ++j) acc[i][jh * 4 + j] = mfma(bfr[j], af[i], acc[i][jh * 4 + j]);
;             }
;             G_STORE(buf ^ 1);
;             {
;                 const bool cur = kt + 2 < nk;
;                 const bf16_t* pa = cur ? Ag : An; const bf16_t* pb = cur ? Bg : Bn;
;                 const int st = cur ? kt + 2 : kt + 2 - nk;
;                 G_LOAD(pa, pb, st);
.LBB0_778:
	v_readlane_b32 s16, v253, 4
	v_readlane_b32 s17, v253, 6
	v_readlane_b32 s18, v253, 5
	s_nop 3
	s_cmp_eq_u32 s18, 0
	s_cbranch_scc1 .Lg778_entry
	v_and_b32_e32 v8, 63, v210
	v_lshrrev_b32_e32 v9, 6, v210
	s_nop 0
	v_readfirstlane_b32 s18, v9
	v_lshrrev_b32_e32 v9, 4, v8
	v_sub_u32_e32 v10, 0, v9
	v_and_b32_e32 v10, 3, v10
	v_and_b32_e32 v11, 3, v8
	v_xor_b32_e32 v11, v11, v10
	v_lshrrev_b32_e32 v12, 2, v8
	v_lshlrev_b32_e32 v0, 6, v12
	v_lshl_add_u32 v0, v11, 4, v0
	s_lshl_b32 vcc_lo, s18, 11
	v_add_u32_e32 v0, vcc_lo, v0
	v_add_u32_e32 v0, 0x1000, v0
	v_add_u32_e32 v1, 0x0, v0
	v_and_b32_e32 v13, 3, v12
	v_lshl_add_u32 v13, v9, 3, v13
	v_lshlrev_b32_e32 v2, 6, v13
	v_lshl_add_u32 v2, v11, 4, v2
	s_lshl_b32 vcc_lo, s18, 12
	v_add_u32_e32 v2, vcc_lo, v2
	v_add_u32_e32 v2, 0x800, v2
	v_add_u32_e32 v3, 0xfffffd00, v2
	v_add_u32_e32 v4, 0x1000, v2
	v_add_u32_e32 v5, 0xd00, v2
	v_and_b32_e32 v10, 15, v8
	v_lshrrev_b32_e32 v11, 2, v10
	v_sub_u32_e32 v11, 0, v11
	v_and_b32_e32 v11, 3, v11
	v_xor_b32_e32 v11, v9, v11
	v_lshlrev_b32_e32 v6, 6, v10
	v_lshl_add_u32 v6, v11, 4, v6
	s_lshr_b32 vcc_lo, s18, 1
	s_mul_i32 vcc_lo, vcc_lo, 0x3000
	s_and_b32 vcc_hi, s18, 1
	s_mul_i32 vcc_hi, vcc_hi, 0x3000
	s_add_u32 vcc_hi, vcc_hi, 0x800
	v_add_u32_e32 v7, vcc_hi, v6
	v_add_u32_e32 v6, vcc_lo, v6
	s_mul_i32 s17, s18, 0x1800
	v_writelane_b32 v253, s17, 6
	v_writelane_b32 v253, 0, 5
	v_readlane_b32 vcc_lo, v253, 0
	v_readlane_b32 vcc_hi, v253, 1
	s_lshl_b32 s18, s7, 13
	s_nop 1
	s_add_u32 s98, vcc_lo, s18
	s_addc_u32 s99, vcc_hi, 0
	s_sub_u32 s98, s98, 0x1000
	s_subb_u32 s99, s99, 0
	v_readlane_b32 vcc_lo, v253, 2
	v_readlane_b32 vcc_hi, v253, 3
	s_lshl_b32 s18, s6, 14
	s_nop 1
	s_add_u32 s100, vcc_lo, s18
	s_addc_u32 s101, vcc_hi, 0
	s_sub_u32 s100, s100, 0x1000
	s_subb_u32 s101, s101, 0
	s_add_u32 m0, s16, s17
	s_nop 0
	global_load_lds_dwordx4 v0, s[98:99]
	global_load_lds_dwordx4 v1, s[98:99] offset:1024
	global_load_lds_dwordx4 v2, s[100:101] offset:2048
	global_load_lds_dwordx4 v3, s[100:101] offset:3072
	s_add_u32 m0, m0, 0x1000
	s_nop 0
	global_load_lds_dwordx4 v4, s[100:101]
	global_load_lds_dwordx4 v5, s[100:101] offset:1024
	s_add_u32 s98, s98, 0x200000
	s_addc_u32 s99, s99, 0
	s_add_u32 s100, s100, 0x40000
	s_addc_u32 s101, s101, 0
	s_add_u32 s18, s16, 0x6000
	s_cmp_eq_u32 s18, 0x12000
	s_cselect_b32 s18, 0, s18
	s_add_u32 m0, s18, s17
	s_nop 0
	global_load_lds_dwordx4 v0, s[98:99]
	global_load_lds_dwordx4 v1, s[98:99] offset:1024
	global_load_lds_dwordx4 v2, s[100:101] offset:2048
	global_load_lds_dwordx4 v3, s[100:101] offset:3072
	s_add_u32 m0, m0, 0x1000
	s_nop 0
	global_load_lds_dwordx4 v4, s[100:101]
	global_load_lds_dwordx4 v5, s[100:101] offset:1024
	s_add_u32 s98, s98, 0x200000
	s_addc_u32 s99, s99, 0
	s_add_u32 s100, s100, 0x40000
	s_addc_u32 s101, s101, 0
	s_add_u32 s18, s18, 0x6000
	s_cmp_eq_u32 s18, 0x12000
	s_cselect_b32 s18, 0, s18
	s_add_u32 m0, s18, s17
	s_nop 0
	global_load_lds_dwordx4 v0, s[98:99]
	global_load_lds_dwordx4 v1, s[98:99] offset:1024
	global_load_lds_dwordx4 v2, s[100:101] offset:2048
	global_load_lds_dwordx4 v3, s[100:101] offset:3072
	s_add_u32 m0, m0, 0x1000
	s_nop 0
	global_load_lds_dwordx4 v4, s[100:101]
	global_load_lds_dwordx4 v5, s[100:101] offset:1024
	s_add_u32 s98, s98, 0x200000
	s_addc_u32 s99, s99, 0
	s_add_u32 s100, s100, 0x40000
	s_addc_u32 s101, s101, 0
.Lg778_entry:
	v_mov_b32_e32 v254, 0x200000
	v_mov_b32_e32 v255, 0
	s_mov_b32 s15, 0
	s_waitcnt vmcnt(0)
	s_barrier
	v_add_u32_e32 v8, s16, v6
	v_add_u32_e32 v9, s16, v7
	ds_read_b128 v[172:175], v9
	ds_read_b128 v[176:179], v9 offset:1024
	ds_read_b128 v[180:183], v9 offset:2048
	ds_read_b128 v[184:187], v9 offset:3072
	ds_read_b128 v[10:13], v8
	ds_read_b128 v[14:17], v8 offset:1024
	ds_read_b128 v[18:21], v8 offset:6144
	ds_read_b128 v[152:155], v8 offset:7168
	ds_read_b128 v[192:195], v9 offset:6144
	ds_read_b128 v[196:199], v9 offset:7168
	ds_read_b128 v[200:203], v9 offset:8192
	ds_read_b128 v[204:207], v9 offset:9216

; DI f32x4 mfma(bf16x8 a, bf16x8 b, f32x4 c) { return __builtin_amdgcn_mfma_f32_16x16x32_bf16(a, b, c, 0, 0, 0); }
; #define G_LOAD(PA, PB, STEP) do { _Pragma("unroll") for (int i_ = 0; i_ < 2; ++i_) ra[i_] = *(const u32x4*)((PA) + (size_t)(64 * i_) * K + (STEP) * 32); \
;         _Pragma("unroll") for (int i_ = 0; i_ < 4; ++i_) rb[i_] = *(const u32x4*)((PB) + (size_t)(64 * i_) * K + (STEP) * 32); } while (0)
; #define G_STORE(BUF) do { _Pragma("unroll") for (int i_ = 0; i_ < 2; ++i_) *(u32x4*)(sA + (BUF) * 128 * 40 + (lrow + 64 * i_) * 40 + lcc * 8) = ra[i_]; \
;         _Pragma("unroll") for (int i_ = 0; i_ < 4; ++i_) *(u32x4*)(sB + (BUF) * 256 * 40 + (lrow + 64 * i_) * 40 + lcc * 8) = rb[i_]; } while (0)
; template <int EPI> ...
;     ...
;         int mt, nt; tile_of(idx, mt, nt);
;         int mtn, ntn; tile_of(idx + nbx < perX ? idx + nbx : idx, mtn, ntn);
;         const bf16_t* Ag = A + (size_t)(mt * 128 + lrow) * K + lcc * 8;
;         const bf16_t* Bg = Bt + (size_t)(nt * 256 + lrowp) * K + lcc * 8;
;         const bf16_t* An = A + (size_t)(mtn * 128 + lrow) * K + lcc * 8;
;         const bf16_t* Bn = Bt + (size_t)(ntn * 256 + lrowp) * K + lcc * 8;
;     ...
;         for (int kt = 0; kt < nk; ++kt) {
;             const int buf = kt & 1;
;             const bf16_t* a_ = sA + buf * 128 * 40 + (wr * 64 + fr) * 40 + fq * 8;
;             const bf16_t* b_ = sB + buf * 256 * 40 + (wc * 128 + fr) * 40 + fq * 8;
;             bf16x8 af[4];
; #pragma unroll
;             for (int i = 0; i < 4; ++i) af[i] = *(const bf16x8*)(a_ + i * 16 * 40);
; #pragma unroll
;             for (int jh = 0; jh < 2; ++jh) {
;                 bf16x8 bfr[4];
; #pragma unroll
;                 for (int j = 0; j < 4; ++j) bfr[j] = *(const bf16x8*)(b_ + (jh * 4 + j) * 16 * 40);
; #pragma unroll
;                 for (int i = 0; i < 4; ++i)
; #pragma unroll
;                     for (int j = 0; j < 4; ++j) acc[i][jh * 4 + j] = mfma(bfr[j], af[i], acc[i][jh * 4 + j]);
;             }
;             G_STORE(buf ^ 1);
;             {
;                 const bool cur = kt + 2 < nk;
;                 const bf16_t* pa = cur ? Ag : An; const bf16_t* pb = cur ? Bg : Bn;
;                 const int st = cur ? kt + 2 : kt + 2 - nk;
;                 G_LOAD(pa, pb, st);
;             }
;             __syncthreads();
;         }
.Lg778_swret:
	s_add_u32 m0, s16, s17
	v_mfma_f32_16x16x32_bf16 v[132:135], v[192:195], v[10:13], v[132:135]
	global_load_lds_dwordx4 v0, s[98:99]
	v_mfma_f32_16x16x32_bf16 v[128:131], v[196:199], v[10:13], v[128:131]
	v_mfma_f32_16x16x32_bf16 v[124:127], v[200:203], v[10:13], v[124:127]
	global_load_lds_dwordx4 v1, s[98:99] offset:1024
	v_mfma_f32_16x16x32_bf16 v[120:123], v[204:207], v[10:13], v[120:123]
	ds_read_b128 v[10:13], v8
	v_mfma_f32_16x16x32_bf16 v[100:103], v[192:195], v[14:17], v[100:103]
	global_load_lds_dwordx4 v2, s[100:101] offset:2048
	v_mfma_f32_16x16x32_bf16 v[96:99], v[196:199], v[14:17], v[96:99]
	v_mfma_f32_16x16x32_bf16 v[92:95], v[200:203], v[14:17], v[92:95]
	global_load_lds_dwordx4 v3, s[100:101] offset:3072
	v_mfma_f32_16x16x32_bf16 v[88:91], v[204:207], v[14:17], v[88:91]
	ds_read_b128 v[14:17], v8 offset:1024
	v_mfma_f32_16x16x32_bf16 v[68:71], v[192:195], v[18:21], v[68:71]
	s_add_u32 m0, m0, 0x1000
	v_mfma_f32_16x16x32_bf16 v[64:67], v[196:199], v[18:21], v[64:67]
	global_load_lds_dwordx4 v4, s[100:101]
	v_mfma_f32_16x16x32_bf16 v[60:63], v[200:203], v[18:21], v[60:63]
	v_mfma_f32_16x16x32_bf16 v[56:59], v[204:207], v[18:21], v[56:59]
	ds_read_b128 v[18:21], v8 offset:6144
	v_mfma_f32_16x16x32_bf16 v[36:39], v[192:195], v[152:155], v[36:39]
	global_load_lds_dwordx4 v5, s[100:101] offset:1024
	v_mfma_f32_16x16x32_bf16 v[32:35], v[196:199], v[152:155], v[32:35]
	v_mfma_f32_16x16x32_bf16 v[28:31], v[200:203], v[152:155], v[28:31]
	v_mfma_f32_16x16x32_bf16 v[24:27], v[204:207], v[152:155], v[24:27]
	ds_read_b128 v[152:155], v8 offset:7168
	ds_read_b128 v[192:195], v9 offset:6144
	ds_read_b128 v[196:199], v9 offset:7168
	ds_read_b128 v[200:203], v9 offset:8192
	ds_read_b128 v[204:207], v9 offset:9216
	s_add_u32 s98, s98, 0x200000
	s_addc_u32 s99, s99, 0
	s_add_u32 s100, s100, 0x40000
	s_addc_u32 s101, s101, 0
	s_add_u32 s16, s16, 0x6000
	s_cmp_eq_u32 s16, 0x12000
	s_cselect_b32 s16, 0, s16
	s_add_u32 s15, s15, 1
	s_cmp_lt_u32 s15, 31
	s_cbranch_scc1 .Lg778_top
	s_waitcnt lgkmcnt(4)
	v_mfma_f32_16x16x32_bf16 v[148:151], v[172:175], v[10:13], v[148:151]
	v_mfma_f32_16x16x32_bf16 v[116:119], v[172:175], v[14:17], v[116:119]
	v_mfma_f32_16x16x32_bf16 v[84:87], v[172:175], v[18:21], v[84:87]
	v_mfma_f32_16x16x32_bf16 v[52:55], v[172:175], v[152:155], v[52:55]
	v_mfma_f32_16x16x32_bf16 v[144:147], v[176:179], v[10:13], v[144:147]
	v_mfma_f32_16x16x32_bf16 v[112:115], v[176:179], v[14:17], v[112:115]
	v_mfma_f32_16x16x32_bf16 v[80:83], v[176:179], v[18:21], v[80:83]
	v_mfma_f32_16x16x32_bf16 v[48:51], v[176:179], v[152:155], v[48:51]
	v_mfma_f32_16x16x32_bf16 v[140:143], v[180:183], v[10:13], v[140:143]
	v_mfma_f32_16x16x32_bf16 v[108:111], v[180:183], v[14:17], v[108:111]
	v_mfma_f32_16x16x32_bf16 v[76:79], v[180:183], v[18:21], v[76:79]
	v_mfma_f32_16x16x32_bf16 v[44:47], v[180:183], v[152:155], v[44:47]
	v_mfma_f32_16x16x32_bf16 v[136:139], v[184:187], v[10:13], v[136:139]
	v_mfma_f32_16x16x32_bf16 v[104:107], v[184:187], v[14:17], v[104:107]
	v_mfma_f32_16x16x32_bf16 v[72:75], v[184:187], v[18:21], v[72:75]
	v_mfma_f32_16x16x32_bf16 v[40:43], v[184:187], v[152:155], v[40:43]
	s_waitcnt vmcnt(6)
	s_waitcnt lgkmcnt(0)
	s_barrier
	s_add_u32 m0, s16, s17
	v_mfma_f32_16x16x32_bf16 v[132:135], v[192:195], v[10:13], v[132:135]
	global_load_lds_dwordx4 v0, s[98:99]
	v_mfma_f32_16x16x32_bf16 v[128:131], v[196:199], v[10:13], v[128:131]
	v_mfma_f32_16x16x32_bf16 v[124:127], v[200:203], v[10:13], v[124:127]
	global_load_lds_dwordx4 v1, s[98:99] offset:1024
	v_mfma_f32_16x16x32_bf16 v[120:123], v[204:207], v[10:13], v[120:123]
	v_mfma_f32_16x16x32_bf16 v[100:103], v[192:195], v[14:17], v[100:103]
	global_load_lds_dwordx4 v2, s[100:101] offset:2048
	v_mfma_f32_16x16x32_bf16 v[96:99], v[196:199], v[14:17], v[96:99]
	v_mfma_f32_16x16x32_bf16 v[92:95], v[200:203], v[14:17], v[92:95]
	global_load_lds_dwordx4 v3, s[100:101] offset:3072
	v_mfma_f32_16x16x32_bf16 v[88:91], v[204:207], v[14:17], v[88:91]
	v_mfma_f32_16x16x32_bf16 v[68:71], v[192:195], v[18:21], v[68:71]
	s_add_u32 m0, m0, 0x1000
	v_mfma_f32_16x16x32_bf16 v[64:67], v[196:199], v[18:21], v[64:67]
	global_load_lds_dwordx4 v4, s[100:101]
	v_mfma_f32_16x16x32_bf16 v[60:63], v[200:203], v[18:21], v[60:63]
	v_mfma_f32_16x16x32_bf16 v[56:59], v[204:207], v[18:21], v[56:59]
	v_mfma_f32_16x16x32_bf16 v[36:39], v[192:195], v[152:155], v[36:39]
	global_load_lds_dwordx4 v5, s[100:101] offset:1024
	v_mfma_f32_16x16x32_bf16 v[32:35], v[196:199], v[152:155], v[32:35]
	v_mfma_f32_16x16x32_bf16 v[28:31], v[200:203], v[152:155], v[28:31]
	v_mfma_f32_16x16x32_bf16 v[24:27], v[204:207], v[152:155], v[24:27]
	s_add_u32 s98, s98, 0x200000
	s_addc_u32 s99, s99, 0
	s_add_u32 s100, s100, 0x40000
	s_addc_u32 s101, s101, 0
	s_add_u32 s16, s16, 0x6000
	s_cmp_eq_u32 s16, 0x12000
	s_cselect_b32 s16, 0, s16
	s_add_u32 s15, s15, 1
	s_branch .Lg778_end
.Lg778_sw:
	v_readlane_b32 vcc_lo, v253, 0
	v_readlane_b32 vcc_hi, v253, 1
	s_lshl_b32 s18, s13, 13
	s_nop 1
	s_add_u32 s98, vcc_lo, s18
	s_addc_u32 s99, vcc_hi, 0
	s_sub_u32 s98, s98, 0x1000
	s_subb_u32 s99, s99, 0
	v_readlane_b32 vcc_lo, v253, 2
	v_readlane_b32 vcc_hi, v253, 3
	s_lshl_b32 s18, s14, 14
	s_nop 1
	s_add_u32 s100, vcc_lo, s18
	s_addc_u32 s101, vcc_hi, 0
	s_sub_u32 s100, s100, 0x1000
	s_subb_u32 s101, s101, 0
	s_branch .Lg778_swret

; DI unsigned pk2(float lo, float hi) { f32x2 v = {lo, hi}; bf16x2_t r = __builtin_convertvector(v, bf16x2_t); return __builtin_bit_cast(unsigned, r); }
; template <int EPI> ...
;     ...
;         for (int i = 0; i < 4; ++i) {
;             const int m = mt * 128 + wr * 64 + i * 16 + fr;
;             float rsc = 1.f;
;             if (EPI != 2 && rs_in) rsc = rsqrtf(rs_in[m] * (1.f / DM) + 1e-6f);
;             float sq = 0.f;
; #pragma unroll
;             for (int jp = 0; jp < 4; ++jp) {
;                 const int n0 = nt * 256 + wc * 128 + 32 * jp + 8 * fq;
;                 f32x4 v0 = acc[i][2 * jp] * rsc, v1 = acc[i][2 * jp + 1] * rsc;
;                 if (EPI == 0) {
;                     u32x4 o4; o4[0] = pk2(v0[0], v0[1]); o4[1] = pk2(v0[2], v0[3]); o4[2] = pk2(v1[0], v1[1]); o4[3] = pk2(v1[2], v1[3]);
;                     *(u32x4*)(outb + (size_t)m * Nn + n0) = o4;
;                     if (n0 >= C_BA && n0 < C_BA + 12) *(f32x4*)(side + (size_t)m * 12 + (n0 - C_BA)) = v0;
;                     if (n0 + 4 >= C_BA && n0 + 4 < C_BA + 12) *(f32x4*)(side + (size_t)m * 12 + (n0 + 4 - C_BA)) = v1;
;                 } else if (EPI == 1) {
; #pragma unroll
;                     for (int e = 0; e < 4; ++e) { const float r0 = fmaxf(v0[e], 0.f), r1 = fmaxf(v1[e], 0.f); v0[e] = r0 * r0; v1[e] = r1 * r1; }
;                     u32x4 o4; o4[0] = pk2(v0[0], v0[1]); o4[1] = pk2(v0[2], v0[3]); o4[2] = pk2(v1[0], v1[1]); o4[3] = pk2(v1[2], v1[3]);
;                     *(u32x4*)(outb + (size_t)m * Nn + n0) = o4;
.LBB0_781:
	v_pk_mul_f32 v[144:145], v[144:145], v[164:165] op_sel_hi:[1,0]
	v_readlane_b32 s52, v250, 51
	v_pk_mul_f32 v[150:151], v[150:151], v[164:165] op_sel_hi:[1,0]
	v_pk_mul_f32 v[148:149], v[148:149], v[164:165] op_sel_hi:[1,0]
	v_pk_mul_f32 v[146:147], v[146:147], v[164:165] op_sel_hi:[1,0]
	v_max_f32_e32 v144, 0, v144
	v_max_f32_e32 v145, 0, v145
	v_lshl_or_b32 v152, s6, 8, v170
	v_lshlrev_b64 v[172:173], 6, v[154:155]
	v_readlane_b32 s58, v250, 57
	v_readlane_b32 s59, v250, 58
	v_max_f32_e32 v148, 0, v148
	v_max_f32_e32 v149, 0, v149
	v_pk_mul_f32 v[174:175], v[144:145], v[144:145]
	v_max_f32_e32 v144, 0, v150
	v_max_f32_e32 v146, 0, v146
	v_max_f32_e32 v145, 0, v151
	v_max_f32_e32 v147, 0, v147
	v_lshl_add_u64 v[172:173], s[58:59], 0, v[172:173]
	v_pk_mul_f32 v[148:149], v[148:149], v[148:149]
	v_pk_mul_f32 v[150:151], v[144:145], v[144:145]
	v_pk_mul_f32 v[176:177], v[146:147], v[146:147]
	v_lshrrev_b32_e32 v153, 5, v152
	v_and_b32_e32 v152, 31, v152
	v_lshl_or_b32 v152, v153, 20, v152
	v_mov_b32_e32 v153, 0
	v_pk_mul_f32 v[136:137], v[136:137], v[164:165] op_sel_hi:[1,0]
	v_cvt_pk_bf16_f32 v144, v148, v149
	v_cvt_pk_bf16_f32 v145, v150, v151
	v_cvt_pk_bf16_f32 v146, v174, v175
	v_cvt_pk_bf16_f32 v147, v176, v177
	v_lshl_add_u64 v[148:149], v[152:153], 1, v[172:173]
	v_pk_mul_f32 v[142:143], v[142:143], v[164:165] op_sel_hi:[1,0]
	v_pk_mul_f32 v[140:141], v[140:141], v[164:165] op_sel_hi:[1,0]
	v_pk_mul_f32 v[138:139], v[138:139], v[164:165] op_sel_hi:[1,0]
	v_max_f32_e32 v136, 0, v136
	v_max_f32_e32 v137, 0, v137
	global_store_dwordx4 v[148:149], v[144:147], off
	v_max_f32_e32 v140, 0, v140
	v_max_f32_e32 v141, 0, v141
	v_pk_mul_f32 v[144:145], v[136:137], v[136:137]
	v_max_f32_e32 v136, 0, v142
	v_max_f32_e32 v138, 0, v138
	v_max_f32_e32 v137, 0, v143
	v_max_f32_e32 v139, 0, v139
	v_pk_mul_f32 v[140:141], v[140:141], v[140:141]
	v_pk_mul_f32 v[142:143], v[136:137], v[136:137]
	v_pk_mul_f32 v[146:147], v[138:139], v[138:139]
	v_pk_mul_f32 v[128:129], v[128:129], v[164:165] op_sel_hi:[1,0]
	v_cvt_pk_bf16_f32 v136, v140, v141
	v_cvt_pk_bf16_f32 v137, v142, v143
	v_cvt_pk_bf16_f32 v138, v144, v145
	v_cvt_pk_bf16_f32 v139, v146, v147
	v_pk_mul_f32 v[134:135], v[134:135], v[164:165] op_sel_hi:[1,0]
	v_pk_mul_f32 v[132:133], v[132:133], v[164:165] op_sel_hi:[1,0]
	v_pk_mul_f32 v[130:131], v[130:131], v[164:165] op_sel_hi:[1,0]
	v_max_f32_e32 v128, 0, v128
	v_max_f32_e32 v129, 0, v129
	v_lshl_add_u64 v[148:149], v[148:149], 0, v[254:255]
	global_store_dwordx4 v[148:149], v[136:139], off
	v_max_f32_e32 v132, 0, v132
	v_max_f32_e32 v133, 0, v133
	v_pk_mul_f32 v[136:137], v[128:129], v[128:129]
	v_max_f32_e32 v128, 0, v134
	v_max_f32_e32 v130, 0, v130
	v_max_f32_e32 v129, 0, v135
	v_max_f32_e32 v131, 0, v131
	v_pk_mul_f32 v[132:133], v[132:133], v[132:133]
	v_pk_mul_f32 v[134:135], v[128:129], v[128:129]
	v_pk_mul_f32 v[138:139], v[130:131], v[130:131]
	v_pk_mul_f32 v[124:125], v[124:125], v[164:165] op_sel_hi:[1,0]
	v_pk_mul_f32 v[120:121], v[120:121], v[164:165] op_sel_hi:[1,0]
	v_cvt_pk_bf16_f32 v128, v132, v133
	v_cvt_pk_bf16_f32 v129, v134, v135
	v_cvt_pk_bf16_f32 v130, v136, v137
	v_cvt_pk_bf16_f32 v131, v138, v139
	v_pk_mul_f32 v[126:127], v[126:127], v[164:165] op_sel_hi:[1,0]
	v_pk_mul_f32 v[122:123], v[122:123], v[164:165] op_sel_hi:[1,0]
	v_max_f32_e32 v124, 0, v124
	v_max_f32_e32 v120, 0, v120
	v_max_f32_e32 v125, 0, v125
	v_max_f32_e32 v121, 0, v121
	v_lshl_add_u64 v[148:149], v[148:149], 0, v[254:255]
	global_store_dwordx4 v[148:149], v[128:131], off
	v_pk_mul_f32 v[124:125], v[124:125], v[124:125]
	v_max_f32_e32 v122, 0, v122
	v_pk_mul_f32 v[128:129], v[120:121], v[120:121]
	v_max_f32_e32 v120, 0, v126
	v_max_f32_e32 v121, 0, v127
	v_max_f32_e32 v123, 0, v123
	v_pk_mul_f32 v[126:127], v[120:121], v[120:121]
	v_pk_mul_f32 v[130:131], v[122:123], v[122:123]
	v_cvt_pk_bf16_f32 v120, v124, v125
	v_cndmask_b32_e64 v124, 0, 1, s[20:21]
	v_cvt_pk_bf16_f32 v121, v126, v127
	v_cvt_pk_bf16_f32 v122, v128, v129
	v_cvt_pk_bf16_f32 v123, v130, v131
	v_cmp_ne_u32_e64 s[6:7], 1, v124
	s_andn2_b64 vcc, exec, s[20:21]
	v_readlane_b32 s53, v250, 52
	v_readlane_b32 s54, v250, 53
	v_readlane_b32 s55, v250, 54
	v_readlane_b32 s56, v250, 55
	v_readlane_b32 s57, v250, 56
	v_readlane_b32 s60, v250, 59
	v_readlane_b32 s61, v250, 60
	v_readlane_b32 s62, v250, 61
	v_readlane_b32 s63, v250, 62
	v_readlane_b32 s64, v250, 63
	v_readlane_b32 s65, v249, 0
	v_readlane_b32 s66, v249, 1
	v_readlane_b32 s67, v249, 2
	v_lshl_add_u64 v[148:149], v[148:149], 0, v[254:255]
	global_store_dwordx4 v[148:149], v[120:123], off
	s_cbranch_vccnz .LBB0_783
	global_load_dword v120, v[160:161], off offset:64
	s_waitcnt vmcnt(0)
	v_fmamk_f32 v120, v120, 0x3a800000, v212
	v_mul_f32_e32 v121, 0x4b800000, v120
	v_cmp_gt_f32_e32 vcc, s28, v120
	s_nop 1
	v_cndmask_b32_e32 v120, v120, v121, vcc
	v_rsq_f32_e32 v120, v120
	s_nop 0
	v_mul_f32_e32 v121, 0x45800000, v120
	v_cndmask_b32_e32 v162, v120, v121, vcc
; DI unsigned pk2(float lo, float hi) { f32x2 v = {lo, hi}; bf16x2_t r = __builtin_convertvector(v, bf16x2_t); return __builtin_bit_cast(unsigned, r); }
; template <int EPI> ...
;     ...
;         for (int i = 0; i < 4; ++i) {
;             const int m = mt * 128 + wr * 64 + i * 16 + fr;
;             float rsc = 1.f;
;             if (EPI != 2 && rs_in) rsc = rsqrtf(rs_in[m] * (1.f / DM) + 1e-6f);
;             float sq = 0.f;
; #pragma unroll
;             for (int jp = 0; jp < 4; ++jp) {
;                 const int n0 = nt * 256 + wc * 128 + 32 * jp + 8 * fq;
;                 f32x4 v0 = acc[i][2 * jp] * rsc, v1 = acc[i][2 * jp + 1] * rsc;
;                 if (EPI == 0) {
;                     u32x4 o4; o4[0] = pk2(v0[0], v0[1]); o4[1] = pk2(v0[2], v0[3]); o4[2] = pk2(v1[0], v1[1]); o4[3] = pk2(v1[2], v1[3]);
;                     *(u32x4*)(outb + (size_t)m * Nn + n0) = o4;
;                     if (n0 >= C_BA && n0 < C_BA + 12) *(f32x4*)(side + (size_t)m * 12 + (n0 - C_BA)) = v0;
;                     if (n0 + 4 >= C_BA && n0 + 4 < C_BA + 12) *(f32x4*)(side + (size_t)m * 12 + (n0 + 4 - C_BA)) = v1;
;                 } else if (EPI == 1) {
; #pragma unroll
;                     for (int e = 0; e < 4; ++e) { const float r0 = fmaxf(v0[e], 0.f), r1 = fmaxf(v1[e], 0.f); v0[e] = r0 * r0; v1[e] = r1 * r1; }
;                     u32x4 o4; o4[0] = pk2(v0[0], v0[1]); o4[1] = pk2(v0[2], v0[3]); o4[2] = pk2(v1[0], v1[1]); o4[3] = pk2(v1[2], v1[3]);
;                     *(u32x4*)(outb + (size_t)m * Nn + n0) = o4;
.LBB0_783:
	s_nop 0
	v_or_b32_e32 v120, 16, v154
	v_pk_mul_f32 v[112:113], v[112:113], v[162:163] op_sel_hi:[1,0]
	v_ashrrev_i32_e32 v121, 31, v120
	v_readlane_b32 s52, v250, 51
	v_pk_mul_f32 v[118:119], v[118:119], v[162:163] op_sel_hi:[1,0]
	v_pk_mul_f32 v[116:117], v[116:117], v[162:163] op_sel_hi:[1,0]
	v_pk_mul_f32 v[114:115], v[114:115], v[162:163] op_sel_hi:[1,0]
	v_max_f32_e32 v112, 0, v112
	v_max_f32_e32 v113, 0, v113
	v_lshlrev_b64 v[120:121], 6, v[120:121]
	v_readlane_b32 s58, v250, 57
	v_readlane_b32 s59, v250, 58
	v_max_f32_e32 v116, 0, v116
	v_max_f32_e32 v117, 0, v117
	v_pk_mul_f32 v[122:123], v[112:113], v[112:113]
	v_max_f32_e32 v112, 0, v118
	v_max_f32_e32 v114, 0, v114
	v_max_f32_e32 v113, 0, v119
	v_max_f32_e32 v115, 0, v115
	v_lshl_add_u64 v[120:121], s[58:59], 0, v[120:121]
	v_pk_mul_f32 v[116:117], v[116:117], v[116:117]
	v_pk_mul_f32 v[118:119], v[112:113], v[112:113]
	v_pk_mul_f32 v[124:125], v[114:115], v[114:115]
	v_pk_mul_f32 v[104:105], v[104:105], v[162:163] op_sel_hi:[1,0]
	v_cvt_pk_bf16_f32 v112, v116, v117
	v_cvt_pk_bf16_f32 v113, v118, v119
	v_cvt_pk_bf16_f32 v114, v122, v123
	v_cvt_pk_bf16_f32 v115, v124, v125
	v_lshl_add_u64 v[116:117], v[152:153], 1, v[120:121]
	v_pk_mul_f32 v[110:111], v[110:111], v[162:163] op_sel_hi:[1,0]
	v_pk_mul_f32 v[108:109], v[108:109], v[162:163] op_sel_hi:[1,0]
	v_pk_mul_f32 v[106:107], v[106:107], v[162:163] op_sel_hi:[1,0]
	v_max_f32_e32 v104, 0, v104
	v_max_f32_e32 v105, 0, v105
	global_store_dwordx4 v[116:117], v[112:115], off
	v_max_f32_e32 v108, 0, v108
	v_max_f32_e32 v109, 0, v109
	v_pk_mul_f32 v[112:113], v[104:105], v[104:105]
	v_max_f32_e32 v104, 0, v110
	v_max_f32_e32 v106, 0, v106
	v_max_f32_e32 v105, 0, v111
	v_max_f32_e32 v107, 0, v107
	v_pk_mul_f32 v[108:109], v[108:109], v[108:109]
	v_pk_mul_f32 v[110:111], v[104:105], v[104:105]
	v_pk_mul_f32 v[114:115], v[106:107], v[106:107]
	v_pk_mul_f32 v[96:97], v[96:97], v[162:163] op_sel_hi:[1,0]
	v_cvt_pk_bf16_f32 v104, v108, v109
	v_cvt_pk_bf16_f32 v105, v110, v111
	v_cvt_pk_bf16_f32 v106, v112, v113
	v_cvt_pk_bf16_f32 v107, v114, v115
	v_pk_mul_f32 v[102:103], v[102:103], v[162:163] op_sel_hi:[1,0]
	v_pk_mul_f32 v[100:101], v[100:101], v[162:163] op_sel_hi:[1,0]
	v_pk_mul_f32 v[98:99], v[98:99], v[162:163] op_sel_hi:[1,0]
	v_max_f32_e32 v96, 0, v96
	v_max_f32_e32 v97, 0, v97
	v_lshl_add_u64 v[116:117], v[116:117], 0, v[254:255]
	global_store_dwordx4 v[116:117], v[104:107], off
	v_max_f32_e32 v100, 0, v100
	v_max_f32_e32 v101, 0, v101
	v_pk_mul_f32 v[104:105], v[96:97], v[96:97]
	v_max_f32_e32 v96, 0, v102
	v_max_f32_e32 v98, 0, v98
	v_max_f32_e32 v97, 0, v103
	v_max_f32_e32 v99, 0, v99
	v_pk_mul_f32 v[100:101], v[100:101], v[100:101]
	v_pk_mul_f32 v[102:103], v[96:97], v[96:97]
	v_pk_mul_f32 v[106:107], v[98:99], v[98:99]
	v_pk_mul_f32 v[88:89], v[88:89], v[162:163] op_sel_hi:[1,0]
	v_cvt_pk_bf16_f32 v96, v100, v101
	v_cvt_pk_bf16_f32 v97, v102, v103
	v_cvt_pk_bf16_f32 v98, v104, v105
	v_cvt_pk_bf16_f32 v99, v106, v107
	v_pk_mul_f32 v[94:95], v[94:95], v[162:163] op_sel_hi:[1,0]
	v_pk_mul_f32 v[92:93], v[92:93], v[162:163] op_sel_hi:[1,0]
	v_pk_mul_f32 v[90:91], v[90:91], v[162:163] op_sel_hi:[1,0]
	v_max_f32_e32 v88, 0, v88
	v_max_f32_e32 v89, 0, v89
	v_lshl_add_u64 v[116:117], v[116:117], 0, v[254:255]
	global_store_dwordx4 v[116:117], v[96:99], off
	v_max_f32_e32 v92, 0, v92
	v_max_f32_e32 v93, 0, v93
	v_pk_mul_f32 v[96:97], v[88:89], v[88:89]
	v_max_f32_e32 v88, 0, v94
	v_max_f32_e32 v90, 0, v90
	v_max_f32_e32 v89, 0, v95
	v_max_f32_e32 v91, 0, v91
	v_pk_mul_f32 v[92:93], v[92:93], v[92:93]
	v_pk_mul_f32 v[94:95], v[88:89], v[88:89]
	v_pk_mul_f32 v[98:99], v[90:91], v[90:91]
	v_cvt_pk_bf16_f32 v88, v92, v93
	v_cvt_pk_bf16_f32 v89, v94, v95
	v_cvt_pk_bf16_f32 v90, v96, v97
	v_cvt_pk_bf16_f32 v91, v98, v99
	v_lshl_add_u64 v[116:117], v[116:117], 0, v[254:255]
	global_store_dwordx4 v[116:117], v[88:91], off
	s_and_b64 vcc, exec, s[6:7]
	v_readlane_b32 s53, v250, 52
	v_mov_b32_e32 v88, 1.0
	v_mov_b32_e32 v90, 1.0
	v_readlane_b32 s54, v250, 53
	v_readlane_b32 s55, v250, 54
	v_readlane_b32 s56, v250, 55
	v_readlane_b32 s57, v250, 56
	v_readlane_b32 s60, v250, 59
	v_readlane_b32 s61, v250, 60
	v_readlane_b32 s62, v250, 61
	v_readlane_b32 s63, v250, 62
	v_readlane_b32 s64, v250, 63
	v_readlane_b32 s65, v249, 0
	v_readlane_b32 s66, v249, 1
	v_readlane_b32 s67, v249, 2
	s_cbranch_vccnz .LBB0_785
	global_load_dword v89, v[160:161], off offset:128
	s_waitcnt vmcnt(0)
	v_fmamk_f32 v89, v89, 0x3a800000, v212
	v_mul_f32_e32 v90, 0x4b800000, v89
	v_cmp_gt_f32_e32 vcc, s28, v89
	s_nop 1
	v_cndmask_b32_e32 v89, v89, v90, vcc
	v_rsq_f32_e32 v89, v89
	s_nop 0
	v_mul_f32_e32 v90, 0x45800000, v89
	v_cndmask_b32_e32 v90, v89, v90, vcc
; DI unsigned pk2(float lo, float hi) { f32x2 v = {lo, hi}; bf16x2_t r = __builtin_convertvector(v, bf16x2_t); return __builtin_bit_cast(unsigned, r); }
; template <int EPI> ...
;     ...
;         for (int i = 0; i < 4; ++i) {
;             const int m = mt * 128 + wr * 64 + i * 16 + fr;
;             float rsc = 1.f;
;             if (EPI != 2 && rs_in) rsc = rsqrtf(rs_in[m] * (1.f / DM) + 1e-6f);
;             float sq = 0.f;
; #pragma unroll
;             for (int jp = 0; jp < 4; ++jp) {
;                 const int n0 = nt * 256 + wc * 128 + 32 * jp + 8 * fq;
;                 f32x4 v0 = acc[i][2 * jp] * rsc, v1 = acc[i][2 * jp + 1] * rsc;
;                 if (EPI == 0) {
;                     u32x4 o4; o4[0] = pk2(v0[0], v0[1]); o4[1] = pk2(v0[2], v0[3]); o4[2] = pk2(v1[0], v1[1]); o4[3] = pk2(v1[2], v1[3]);
;                     *(u32x4*)(outb + (size_t)m * Nn + n0) = o4;
;                     if (n0 >= C_BA && n0 < C_BA + 12) *(f32x4*)(side + (size_t)m * 12 + (n0 - C_BA)) = v0;
;                     if (n0 + 4 >= C_BA && n0 + 4 < C_BA + 12) *(f32x4*)(side + (size_t)m * 12 + (n0 + 4 - C_BA)) = v1;
;                 } else if (EPI == 1) {
; #pragma unroll
;                     for (int e = 0; e < 4; ++e) { const float r0 = fmaxf(v0[e], 0.f), r1 = fmaxf(v1[e], 0.f); v0[e] = r0 * r0; v1[e] = r1 * r1; }
;                     u32x4 o4; o4[0] = pk2(v0[0], v0[1]); o4[1] = pk2(v0[2], v0[3]); o4[2] = pk2(v1[0], v1[1]); o4[3] = pk2(v1[2], v1[3]);
;                     *(u32x4*)(outb + (size_t)m * Nn + n0) = o4;
.LBB0_785:
	v_or_b32_e32 v92, 32, v154
	v_pk_mul_f32 v[80:81], v[80:81], v[90:91] op_sel_hi:[1,0]
	v_ashrrev_i32_e32 v93, 31, v92
	v_readlane_b32 s52, v250, 51
	v_pk_mul_f32 v[86:87], v[86:87], v[90:91] op_sel_hi:[1,0]
	v_pk_mul_f32 v[84:85], v[84:85], v[90:91] op_sel_hi:[1,0]
	v_pk_mul_f32 v[82:83], v[82:83], v[90:91] op_sel_hi:[1,0]
	v_max_f32_e32 v80, 0, v80
	v_max_f32_e32 v81, 0, v81
	v_lshlrev_b64 v[92:93], 6, v[92:93]
	v_readlane_b32 s58, v250, 57
	v_readlane_b32 s59, v250, 58
	v_max_f32_e32 v84, 0, v84
	v_max_f32_e32 v85, 0, v85
	v_pk_mul_f32 v[94:95], v[80:81], v[80:81]
	v_max_f32_e32 v80, 0, v86
	v_max_f32_e32 v82, 0, v82
	v_max_f32_e32 v81, 0, v87
	v_max_f32_e32 v83, 0, v83
	v_lshl_add_u64 v[92:93], s[58:59], 0, v[92:93]
	v_pk_mul_f32 v[84:85], v[84:85], v[84:85]
	v_pk_mul_f32 v[86:87], v[80:81], v[80:81]
	v_pk_mul_f32 v[96:97], v[82:83], v[82:83]
	v_pk_mul_f32 v[72:73], v[72:73], v[90:91] op_sel_hi:[1,0]
	v_cvt_pk_bf16_f32 v80, v84, v85
	v_cvt_pk_bf16_f32 v81, v86, v87
	v_cvt_pk_bf16_f32 v82, v94, v95
	v_cvt_pk_bf16_f32 v83, v96, v97
	v_lshl_add_u64 v[84:85], v[152:153], 1, v[92:93]
	v_pk_mul_f32 v[78:79], v[78:79], v[90:91] op_sel_hi:[1,0]
	v_pk_mul_f32 v[76:77], v[76:77], v[90:91] op_sel_hi:[1,0]
	v_pk_mul_f32 v[74:75], v[74:75], v[90:91] op_sel_hi:[1,0]
	v_max_f32_e32 v72, 0, v72
	v_max_f32_e32 v73, 0, v73
	global_store_dwordx4 v[84:85], v[80:83], off
	v_max_f32_e32 v76, 0, v76
	v_max_f32_e32 v77, 0, v77
	v_pk_mul_f32 v[80:81], v[72:73], v[72:73]
	v_max_f32_e32 v72, 0, v78
	v_max_f32_e32 v74, 0, v74
	v_max_f32_e32 v73, 0, v79
	v_max_f32_e32 v75, 0, v75
	v_pk_mul_f32 v[76:77], v[76:77], v[76:77]
	v_pk_mul_f32 v[78:79], v[72:73], v[72:73]
	v_pk_mul_f32 v[82:83], v[74:75], v[74:75]
	v_pk_mul_f32 v[64:65], v[64:65], v[90:91] op_sel_hi:[1,0]
	v_cvt_pk_bf16_f32 v72, v76, v77
	v_cvt_pk_bf16_f32 v73, v78, v79
	v_cvt_pk_bf16_f32 v74, v80, v81
	v_cvt_pk_bf16_f32 v75, v82, v83
	v_pk_mul_f32 v[70:71], v[70:71], v[90:91] op_sel_hi:[1,0]
	v_pk_mul_f32 v[68:69], v[68:69], v[90:91] op_sel_hi:[1,0]
	v_pk_mul_f32 v[66:67], v[66:67], v[90:91] op_sel_hi:[1,0]
	v_max_f32_e32 v64, 0, v64
	v_max_f32_e32 v65, 0, v65
	v_lshl_add_u64 v[84:85], v[84:85], 0, v[254:255]
	global_store_dwordx4 v[84:85], v[72:75], off
	v_max_f32_e32 v68, 0, v68
	v_max_f32_e32 v69, 0, v69
	v_pk_mul_f32 v[72:73], v[64:65], v[64:65]
	v_max_f32_e32 v64, 0, v70
	v_max_f32_e32 v66, 0, v66
	v_max_f32_e32 v65, 0, v71
	v_max_f32_e32 v67, 0, v67
	v_pk_mul_f32 v[68:69], v[68:69], v[68:69]
	v_pk_mul_f32 v[70:71], v[64:65], v[64:65]
	v_pk_mul_f32 v[74:75], v[66:67], v[66:67]
	v_pk_mul_f32 v[56:57], v[56:57], v[90:91] op_sel_hi:[1,0]
	v_cvt_pk_bf16_f32 v64, v68, v69
	v_cvt_pk_bf16_f32 v65, v70, v71
	v_cvt_pk_bf16_f32 v66, v72, v73
	v_cvt_pk_bf16_f32 v67, v74, v75
	v_pk_mul_f32 v[62:63], v[62:63], v[90:91] op_sel_hi:[1,0]
	v_pk_mul_f32 v[60:61], v[60:61], v[90:91] op_sel_hi:[1,0]
	v_pk_mul_f32 v[58:59], v[58:59], v[90:91] op_sel_hi:[1,0]
	v_max_f32_e32 v56, 0, v56
	v_max_f32_e32 v57, 0, v57
	v_lshl_add_u64 v[84:85], v[84:85], 0, v[254:255]
	global_store_dwordx4 v[84:85], v[64:67], off
	v_max_f32_e32 v60, 0, v60
	v_max_f32_e32 v61, 0, v61
	v_pk_mul_f32 v[64:65], v[56:57], v[56:57]
	v_max_f32_e32 v56, 0, v62
	v_max_f32_e32 v58, 0, v58
	v_max_f32_e32 v57, 0, v63
	v_max_f32_e32 v59, 0, v59
	v_pk_mul_f32 v[60:61], v[60:61], v[60:61]
	v_pk_mul_f32 v[62:63], v[56:57], v[56:57]
	v_pk_mul_f32 v[66:67], v[58:59], v[58:59]
	v_cvt_pk_bf16_f32 v56, v60, v61
	v_cvt_pk_bf16_f32 v57, v62, v63
	v_cvt_pk_bf16_f32 v58, v64, v65
	v_cvt_pk_bf16_f32 v59, v66, v67
	s_and_b64 vcc, exec, s[6:7]
	v_readlane_b32 s53, v250, 52
	v_readlane_b32 s54, v250, 53
	v_readlane_b32 s55, v250, 54
	v_readlane_b32 s56, v250, 55
	v_readlane_b32 s57, v250, 56
	v_readlane_b32 s60, v250, 59
	v_readlane_b32 s61, v250, 60
	v_readlane_b32 s62, v250, 61
	v_readlane_b32 s63, v250, 62
	v_readlane_b32 s64, v250, 63
	v_readlane_b32 s65, v249, 0
	v_readlane_b32 s66, v249, 1
	v_readlane_b32 s67, v249, 2
	v_lshl_add_u64 v[84:85], v[84:85], 0, v[254:255]
	global_store_dwordx4 v[84:85], v[56:59], off
	s_cbranch_vccnz .LBB0_776
	global_load_dword v56, v[160:161], off offset:192
	s_waitcnt vmcnt(0)
	v_fmamk_f32 v56, v56, 0x3a800000, v212
	v_mul_f32_e32 v57, 0x4b800000, v56
	v_cmp_gt_f32_e32 vcc, s28, v56
	s_nop 1
	v_cndmask_b32_e32 v56, v56, v57, vcc
	v_rsq_f32_e32 v56, v56
	s_nop 0
	v_mul_f32_e32 v57, 0x45800000, v56
	v_cndmask_b32_e32 v88, v56, v57, vcc
	s_branch .LBB0_776

; template <int EPI> ...
;     ...
;     const int idx0 = blockIdx.x >> 3;
;     if (idx0 < perX) {
;         int mt0, nt0; tile_of(idx0, mt0, nt0);
;         const bf16_t* A0 = A + (size_t)(mt0 * 128 + lrow) * K + lcc * 8;
;         const bf16_t* B0 = Bt + (size_t)(nt0 * 256 + lrowp) * K + lcc * 8;
;         G_LOAD(A0, B0, 0);
;         G_STORE(0);
;         G_LOAD(A0, B0, 1);
;         __syncthreads();
;     }
;     for (int idx = idx0; idx < perX; idx += nbx) {
;         int mt, nt; tile_of(idx, mt, nt);
;         int mtn, ntn; tile_of(idx + nbx < perX ? idx + nbx : idx, mtn, ntn);
;         const bf16_t* Ag = A + (size_t)(mt * 128 + lrow) * K + lcc * 8;
;         const bf16_t* Bg = Bt + (size_t)(nt * 256 + lrowp) * K + lcc * 8;
;         const bf16_t* An = A + (size_t)(mtn * 128 + lrow) * K + lcc * 8;
;         const bf16_t* Bn = Bt + (size_t)(ntn * 256 + lrowp) * K + lcc * 8;
;         f32x4 acc[4][8];
; #pragma unroll
;         for (int i = 0; i < 4; ++i)
; #pragma unroll
;             for (int j = 0; j < 8; ++j) {
;                 if (EPI == 2)
;                     acc[i][j] = *(const f32x4*)(xin + (size_t)(mt * 128 + wr * 64 + i * 16 + fr) * Nn + nt * 256 + wc * 128 + 32 * (j >> 1) + 8 * fq + 4 * (j & 1));
;                 else acc[i][j] = (f32x4){0.f, 0.f, 0.f, 0.f};
;             }
;         for (int kt = 0; kt < nk; ++kt) {
;             const int buf = kt & 1;
;             const bf16_t* a_ = sA + buf * 128 * 40 + (wr * 64 + fr) * 40 + fq * 8;
;             const bf16_t* b_ = sB + buf * 256 * 40 + (wc * 128 + fr) * 40 + fq * 8;
;             bf16x8 af[4];
; #pragma unroll
;             for (int i = 0; i < 4; ++i) af[i] = *(const bf16x8*)(a_ + i * 16 * 40);
; #pragma unroll
;             for (int jh = 0; jh < 2; ++jh) {
;                 bf16x8 bfr[4];
; #pragma unroll
;                 for (int j = 0; j < 4; ++j) bfr[j] = *(const bf16x8*)(b_ + (jh * 4 + j) * 16 * 40);
; #pragma unroll
;                 for (int i = 0; i < 4; ++i)
; #pragma unroll
;                     for (int j = 0; j < 4; ++j) acc[i][jh * 4 + j] = mfma(bfr[j], af[i], acc[i][jh * 4 + j]);
;             }
;             G_STORE(buf ^ 1);
;             {
;                 const bool cur = kt + 2 < nk;
;                 const bf16_t* pa = cur ? Ag : An; const bf16_t* pb = cur ? Bg : Bn;
;                 const int st = cur ? kt + 2 : kt + 2 - nk;
;                 G_LOAD(pa, pb, st);
.LBB0_843:
	v_readlane_b32 s15, v253, 4
	v_readlane_b32 s16, v253, 6
	v_readlane_b32 s17, v253, 5
	s_nop 3
	s_cmp_eq_u32 s17, 0
	s_cbranch_scc1 .Lg843_entry
	v_and_b32_e32 v8, 63, v210
	v_lshrrev_b32_e32 v9, 6, v210
	s_nop 0
	v_readfirstlane_b32 s17, v9
	v_lshrrev_b32_e32 v9, 4, v8
	v_sub_u32_e32 v10, 0, v9
	v_and_b32_e32 v10, 3, v10
	v_and_b32_e32 v11, 3, v8
	v_xor_b32_e32 v11, v11, v10
	v_lshrrev_b32_e32 v12, 2, v8
	v_lshlrev_b32_e32 v0, 6, v12
	v_lshl_add_u32 v0, v11, 4, v0
	s_lshl_b32 vcc_lo, s17, 11
	v_add_u32_e32 v0, vcc_lo, v0
	v_add_u32_e32 v0, 0x1000, v0
	v_add_u32_e32 v1, 0x0, v0
	v_and_b32_e32 v13, 3, v12
	v_lshl_add_u32 v13, v9, 3, v13
	v_lshlrev_b32_e32 v2, 6, v13
	v_lshl_add_u32 v2, v11, 4, v2
	s_lshl_b32 vcc_lo, s17, 12
	v_add_u32_e32 v2, vcc_lo, v2
	v_add_u32_e32 v2, 0x800, v2
	v_add_u32_e32 v3, 0xfffffd00, v2
	v_add_u32_e32 v4, 0x1000, v2
	v_add_u32_e32 v5, 0xd00, v2
	v_and_b32_e32 v10, 15, v8
	v_lshrrev_b32_e32 v11, 2, v10
	v_sub_u32_e32 v11, 0, v11
	v_and_b32_e32 v11, 3, v11
	v_xor_b32_e32 v11, v9, v11
	v_lshlrev_b32_e32 v6, 6, v10
	v_lshl_add_u32 v6, v11, 4, v6
	s_lshr_b32 vcc_lo, s17, 1
	s_mul_i32 vcc_lo, vcc_lo, 0x3000
	s_and_b32 vcc_hi, s17, 1
	s_mul_i32 vcc_hi, vcc_hi, 0x3000
	s_add_u32 vcc_hi, vcc_hi, 0x800
	v_add_u32_e32 v7, vcc_hi, v6
	v_add_u32_e32 v6, vcc_lo, v6
	s_mul_i32 s16, s17, 0x1800
	v_writelane_b32 v253, s16, 6
	v_writelane_b32 v253, 0, 5
	v_readlane_b32 vcc_lo, v253, 0
	v_readlane_b32 vcc_hi, v253, 1
	s_lshl_b32 s17, s9, 13
	s_nop 1
	s_add_u32 s98, vcc_lo, s17
	s_addc_u32 s99, vcc_hi, 0
	s_sub_u32 s98, s98, 0x1000
	s_subb_u32 s99, s99, 0
	v_readlane_b32 vcc_lo, v253, 2
	v_readlane_b32 vcc_hi, v253, 3
	s_lshl_b32 s17, s10, 14
	s_nop 1
	s_add_u32 s100, vcc_lo, s17
	s_addc_u32 s101, vcc_hi, 0
	s_sub_u32 s100, s100, 0x1000
	s_subb_u32 s101, s101, 0
	s_add_u32 m0, s15, s16
	s_nop 0
	global_load_lds_dwordx4 v0, s[98:99]
	global_load_lds_dwordx4 v1, s[98:99] offset:1024
	global_load_lds_dwordx4 v2, s[100:101] offset:2048
	global_load_lds_dwordx4 v3, s[100:101] offset:3072
	s_add_u32 m0, m0, 0x1000
	s_nop 0
	global_load_lds_dwordx4 v4, s[100:101]
	global_load_lds_dwordx4 v5, s[100:101] offset:1024
	s_add_u32 s98, s98, 0x200000
	s_addc_u32 s99, s99, 0
	s_add_u32 s100, s100, 0x10000
	s_addc_u32 s101, s101, 0
	s_add_u32 s17, s15, 0x6000
	s_cmp_eq_u32 s17, 0x12000
	s_cselect_b32 s17, 0, s17
	s_add_u32 m0, s17, s16
	s_nop 0
	global_load_lds_dwordx4 v0, s[98:99]
	global_load_lds_dwordx4 v1, s[98:99] offset:1024
	global_load_lds_dwordx4 v2, s[100:101] offset:2048
	global_load_lds_dwordx4 v3, s[100:101] offset:3072
	s_add_u32 m0, m0, 0x1000
	s_nop 0
	global_load_lds_dwordx4 v4, s[100:101]
	global_load_lds_dwordx4 v5, s[100:101] offset:1024
	s_add_u32 s98, s98, 0x200000
	s_addc_u32 s99, s99, 0
	s_add_u32 s100, s100, 0x10000
	s_addc_u32 s101, s101, 0
	s_add_u32 s17, s17, 0x6000
	s_cmp_eq_u32 s17, 0x12000
	s_cselect_b32 s17, 0, s17
	s_add_u32 m0, s17, s16
	s_nop 0
	global_load_lds_dwordx4 v0, s[98:99]
	global_load_lds_dwordx4 v1, s[98:99] offset:1024
	global_load_lds_dwordx4 v2, s[100:101] offset:2048
	global_load_lds_dwordx4 v3, s[100:101] offset:3072
	s_add_u32 m0, m0, 0x1000
	s_nop 0
	global_load_lds_dwordx4 v4, s[100:101]
	global_load_lds_dwordx4 v5, s[100:101] offset:1024
	s_add_u32 s98, s98, 0x200000
	s_addc_u32 s99, s99, 0
	s_add_u32 s100, s100, 0x10000
	s_addc_u32 s101, s101, 0

; DI f32x4 mfma(bf16x8 a, bf16x8 b, f32x4 c) { return __builtin_amdgcn_mfma_f32_16x16x32_bf16(a, b, c, 0, 0, 0); }
; #define G_LOAD(PA, PB, STEP) do { _Pragma("unroll") for (int i_ = 0; i_ < 2; ++i_) ra[i_] = *(const u32x4*)((PA) + (size_t)(64 * i_) * K + (STEP) * 32); \
;         _Pragma("unroll") for (int i_ = 0; i_ < 4; ++i_) rb[i_] = *(const u32x4*)((PB) + (size_t)(64 * i_) * K + (STEP) * 32); } while (0)
; #define G_STORE(BUF) do { _Pragma("unroll") for (int i_ = 0; i_ < 2; ++i_) *(u32x4*)(sA + (BUF) * 128 * 40 + (lrow + 64 * i_) * 40 + lcc * 8) = ra[i_]; \
;         _Pragma("unroll") for (int i_ = 0; i_ < 4; ++i_) *(u32x4*)(sB + (BUF) * 256 * 40 + (lrow + 64 * i_) * 40 + lcc * 8) = rb[i_]; } while (0)
; template <int EPI> ...
;     ...
;         int mt, nt; tile_of(idx, mt, nt);
;         int mtn, ntn; tile_of(idx + nbx < perX ? idx + nbx : idx, mtn, ntn);
;         const bf16_t* Ag = A + (size_t)(mt * 128 + lrow) * K + lcc * 8;
;         const bf16_t* Bg = Bt + (size_t)(nt * 256 + lrowp) * K + lcc * 8;
;         const bf16_t* An = A + (size_t)(mtn * 128 + lrow) * K + lcc * 8;
;         const bf16_t* Bn = Bt + (size_t)(ntn * 256 + lrowp) * K + lcc * 8;
;     ...
;         for (int kt = 0; kt < nk; ++kt) {
;             const int buf = kt & 1;
;             const bf16_t* a_ = sA + buf * 128 * 40 + (wr * 64 + fr) * 40 + fq * 8;
;             const bf16_t* b_ = sB + buf * 256 * 40 + (wc * 128 + fr) * 40 + fq * 8;
;             bf16x8 af[4];
; #pragma unroll
;             for (int i = 0; i < 4; ++i) af[i] = *(const bf16x8*)(a_ + i * 16 * 40);
; #pragma unroll
;             for (int jh = 0; jh < 2; ++jh) {
;                 bf16x8 bfr[4];
; #pragma unroll
;                 for (int j = 0; j < 4; ++j) bfr[j] = *(const bf16x8*)(b_ + (jh * 4 + j) * 16 * 40);
; #pragma unroll
;                 for (int i = 0; i < 4; ++i)
; #pragma unroll
;                     for (int j = 0; j < 4; ++j) acc[i][jh * 4 + j] = mfma(bfr[j], af[i], acc[i][jh * 4 + j]);
;             }
;             G_STORE(buf ^ 1);
;             {
;                 const bool cur = kt + 2 < nk;
;                 const bf16_t* pa = cur ? Ag : An; const bf16_t* pb = cur ? Bg : Bn;
;                 const int st = cur ? kt + 2 : kt + 2 - nk;
;                 G_LOAD(pa, pb, st);
;             }
;             __syncthreads();
;         }
.Lg843_swret:
	s_add_u32 m0, s15, s16
	v_mfma_f32_16x16x32_bf16 v[132:135], v[196:199], v[10:13], v[132:135]
	global_load_lds_dwordx4 v0, s[98:99]
	v_mfma_f32_16x16x32_bf16 v[128:131], v[200:203], v[10:13], v[128:131]
	v_mfma_f32_16x16x32_bf16 v[124:127], v[204:207], v[10:13], v[124:127]
	global_load_lds_dwordx4 v1, s[98:99] offset:1024
	v_mfma_f32_16x16x32_bf16 v[120:123], v[232:235], v[10:13], v[120:123]
	ds_read_b128 v[10:13], v8
	v_mfma_f32_16x16x32_bf16 v[100:103], v[196:199], v[14:17], v[100:103]
	global_load_lds_dwordx4 v2, s[100:101] offset:2048
	v_mfma_f32_16x16x32_bf16 v[96:99], v[200:203], v[14:17], v[96:99]
	v_mfma_f32_16x16x32_bf16 v[92:95], v[204:207], v[14:17], v[92:95]
	global_load_lds_dwordx4 v3, s[100:101] offset:3072
	v_mfma_f32_16x16x32_bf16 v[88:91], v[232:235], v[14:17], v[88:91]
	ds_read_b128 v[14:17], v8 offset:1024
	v_mfma_f32_16x16x32_bf16 v[68:71], v[196:199], v[18:21], v[68:71]
	s_add_u32 m0, m0, 0x1000
	v_mfma_f32_16x16x32_bf16 v[64:67], v[200:203], v[18:21], v[64:67]
	global_load_lds_dwordx4 v4, s[100:101]
	v_mfma_f32_16x16x32_bf16 v[60:63], v[204:207], v[18:21], v[60:63]
	v_mfma_f32_16x16x32_bf16 v[56:59], v[232:235], v[18:21], v[56:59]
	ds_read_b128 v[18:21], v8 offset:6144
	v_mfma_f32_16x16x32_bf16 v[36:39], v[196:199], v[154:157], v[36:39]
	global_load_lds_dwordx4 v5, s[100:101] offset:1024
	v_mfma_f32_16x16x32_bf16 v[32:35], v[200:203], v[154:157], v[32:35]
	v_mfma_f32_16x16x32_bf16 v[28:31], v[204:207], v[154:157], v[28:31]
	v_mfma_f32_16x16x32_bf16 v[24:27], v[232:235], v[154:157], v[24:27]
	ds_read_b128 v[154:157], v8 offset:7168
	ds_read_b128 v[196:199], v9 offset:6144
	ds_read_b128 v[200:203], v9 offset:7168
	ds_read_b128 v[204:207], v9 offset:8192
	ds_read_b128 v[232:235], v9 offset:9216
	s_add_u32 s98, s98, 0x200000
	s_addc_u32 s99, s99, 0
	s_add_u32 s100, s100, 0x10000
	s_addc_u32 s101, s101, 0
	s_add_u32 s15, s15, 0x6000
	s_cmp_eq_u32 s15, 0x12000
	s_cselect_b32 s15, 0, s15
	s_add_u32 s14, s14, 1
	s_cmp_lt_u32 s14, 127
	s_cbranch_scc1 .Lg843_top
	s_waitcnt lgkmcnt(4)
	v_mfma_f32_16x16x32_bf16 v[148:151], v[174:177], v[10:13], v[148:151]
	v_mfma_f32_16x16x32_bf16 v[116:119], v[174:177], v[14:17], v[116:119]
	v_mfma_f32_16x16x32_bf16 v[84:87], v[174:177], v[18:21], v[84:87]
	v_mfma_f32_16x16x32_bf16 v[52:55], v[174:177], v[154:157], v[52:55]
	v_mfma_f32_16x16x32_bf16 v[144:147], v[178:181], v[10:13], v[144:147]
	v_mfma_f32_16x16x32_bf16 v[112:115], v[178:181], v[14:17], v[112:115]
	v_mfma_f32_16x16x32_bf16 v[80:83], v[178:181], v[18:21], v[80:83]
	v_mfma_f32_16x16x32_bf16 v[48:51], v[178:181], v[154:157], v[48:51]
	v_mfma_f32_16x16x32_bf16 v[140:143], v[182:185], v[10:13], v[140:143]
	v_mfma_f32_16x16x32_bf16 v[108:111], v[182:185], v[14:17], v[108:111]
	v_mfma_f32_16x16x32_bf16 v[76:79], v[182:185], v[18:21], v[76:79]
	v_mfma_f32_16x16x32_bf16 v[44:47], v[182:185], v[154:157], v[44:47]
	v_mfma_f32_16x16x32_bf16 v[136:139], v[192:195], v[10:13], v[136:139]
	v_mfma_f32_16x16x32_bf16 v[104:107], v[192:195], v[14:17], v[104:107]
	v_mfma_f32_16x16x32_bf16 v[72:75], v[192:195], v[18:21], v[72:75]
	v_mfma_f32_16x16x32_bf16 v[40:43], v[192:195], v[154:157], v[40:43]
	s_waitcnt vmcnt(6)
	s_waitcnt lgkmcnt(0)
	s_barrier
	s_add_u32 m0, s15, s16
	v_mfma_f32_16x16x32_bf16 v[132:135], v[196:199], v[10:13], v[132:135]
	global_load_lds_dwordx4 v0, s[98:99]
	v_mfma_f32_16x16x32_bf16 v[128:131], v[200:203], v[10:13], v[128:131]
	v_mfma_f32_16x16x32_bf16 v[124:127], v[204:207], v[10:13], v[124:127]
	global_load_lds_dwordx4 v1, s[98:99] offset:1024
	v_mfma_f32_16x16x32_bf16 v[120:123], v[232:235], v[10:13], v[120:123]
	v_mfma_f32_16x16x32_bf16 v[100:103], v[196:199], v[14:17], v[100:103]
	global_load_lds_dwordx4 v2, s[100:101] offset:2048
	v_mfma_f32_16x16x32_bf16 v[96:99], v[200:203], v[14:17], v[96:99]
	v_mfma_f32_16x16x32_bf16 v[92:95], v[204:207], v[14:17], v[92:95]
	global_load_lds_dwordx4 v3, s[100:101] offset:3072
	v_mfma_f32_16x16x32_bf16 v[88:91], v[232:235], v[14:17], v[88:91]
	v_mfma_f32_16x16x32_bf16 v[68:71], v[196:199], v[18:21], v[68:71]
	s_add_u32 m0, m0, 0x1000
	v_mfma_f32_16x16x32_bf16 v[64:67], v[200:203], v[18:21], v[64:67]
	global_load_lds_dwordx4 v4, s[100:101]
	v_mfma_f32_16x16x32_bf16 v[60:63], v[204:207], v[18:21], v[60:63]
	v_mfma_f32_16x16x32_bf16 v[56:59], v[232:235], v[18:21], v[56:59]
	v_mfma_f32_16x16x32_bf16 v[36:39], v[196:199], v[154:157], v[36:39]
	global_load_lds_dwordx4 v5, s[100:101] offset:1024
	v_mfma_f32_16x16x32_bf16 v[32:35], v[200:203], v[154:157], v[32:35]
	v_mfma_f32_16x16x32_bf16 v[28:31], v[204:207], v[154:157], v[28:31]
	v_mfma_f32_16x16x32_bf16 v[24:27], v[232:235], v[154:157], v[24:27]
	s_add_u32 s98, s98, 0x200000
	s_addc_u32 s99, s99, 0
	s_add_u32 s100, s100, 0x10000
	s_addc_u32 s101, s101, 0
	s_add_u32 s15, s15, 0x6000
	s_cmp_eq_u32 s15, 0x12000
	s_cselect_b32 s15, 0, s15
	s_add_u32 s14, s14, 1
	s_branch .Lg843_end
.Lg843_sw:
	v_readlane_b32 vcc_lo, v253, 0
	v_readlane_b32 vcc_hi, v253, 1
	s_lshl_b32 s17, s12, 13
	s_nop 1
	s_add_u32 s98, vcc_lo, s17
	s_addc_u32 s99, vcc_hi, 0
	s_sub_u32 s98, s98, 0x1000
	s_subb_u32 s99, s99, 0
	v_readlane_b32 vcc_lo, v253, 2
	v_readlane_b32 vcc_hi, v253, 3
	s_lshl_b32 s17, s13, 14
	s_nop 1
	s_add_u32 s100, vcc_lo, s17
	s_addc_u32 s101, vcc_hi, 0
	s_sub_u32 s100, s100, 0x1000
	s_subb_u32 s101, s101, 0
	s_branch .Lg843_swret

; template <int EPI> ...
;     ...
;     const int idx0 = blockIdx.x >> 3;
;     if (idx0 < perX) {
;         int mt0, nt0; tile_of(idx0, mt0, nt0);
;         const bf16_t* A0 = A + (size_t)(mt0 * 128 + lrow) * K + lcc * 8;
;         const bf16_t* B0 = Bt + (size_t)(nt0 * 256 + lrowp) * K + lcc * 8;
;         G_LOAD(A0, B0, 0);
;         G_STORE(0);
;         G_LOAD(A0, B0, 1);
;         __syncthreads();
;     }
;     for (int idx = idx0; idx < perX; idx += nbx) {
;         int mt, nt; tile_of(idx, mt, nt);
;         int mtn, ntn; tile_of(idx + nbx < perX ? idx + nbx : idx, mtn, ntn);
;         const bf16_t* Ag = A + (size_t)(mt * 128 + lrow) * K + lcc * 8;
;         const bf16_t* Bg = Bt + (size_t)(nt * 256 + lrowp) * K + lcc * 8;
;         const bf16_t* An = A + (size_t)(mtn * 128 + lrow) * K + lcc * 8;
;         const bf16_t* Bn = Bt + (size_t)(ntn * 256 + lrowp) * K + lcc * 8;
;         f32x4 acc[4][8];
; #pragma unroll
;         for (int i = 0; i < 4; ++i)
; #pragma unroll
;             for (int j = 0; j < 8; ++j) {
;                 if (EPI == 2)
;                     acc[i][j] = *(const f32x4*)(xin + (size_t)(mt * 128 + wr * 64 + i * 16 + fr) * Nn + nt * 256 + wc * 128 + 32 * (j >> 1) + 8 * fq + 4 * (j & 1));
;                 else acc[i][j] = (f32x4){0.f, 0.f, 0.f, 0.f};
;             }
;         for (int kt = 0; kt < nk; ++kt) {
;             const int buf = kt & 1;
;             const bf16_t* a_ = sA + buf * 128 * 40 + (wr * 64 + fr) * 40 + fq * 8;
;             const bf16_t* b_ = sB + buf * 256 * 40 + (wc * 128 + fr) * 40 + fq * 8;
;             bf16x8 af[4];
; #pragma unroll
;             for (int i = 0; i < 4; ++i) af[i] = *(const bf16x8*)(a_ + i * 16 * 40);
; #pragma unroll
;             for (int jh = 0; jh < 2; ++jh) {
;                 bf16x8 bfr[4];
; #pragma unroll
;                 for (int j = 0; j < 4; ++j) bfr[j] = *(const bf16x8*)(b_ + (jh * 4 + j) * 16 * 40);
; #pragma unroll
;                 for (int i = 0; i < 4; ++i)
; #pragma unroll
;                     for (int j = 0; j < 4; ++j) acc[i][jh * 4 + j] = mfma(bfr[j], af[i], acc[i][jh * 4 + j]);
;             }
;             G_STORE(buf ^ 1);
;             {
;                 const bool cur = kt + 2 < nk;
;                 const bf16_t* pa = cur ? Ag : An; const bf16_t* pb = cur ? Bg : Bn;
;                 const int st = cur ? kt + 2 : kt + 2 - nk;
;                 G_LOAD(pa, pb, st);
.LBB0_853:
	v_readlane_b32 s15, v253, 4
	v_readlane_b32 s16, v253, 6
	v_readlane_b32 s17, v253, 5
	s_nop 3
	s_cmp_eq_u32 s17, 0
	s_cbranch_scc1 .Lg853_entry
	v_and_b32_e32 v8, 63, v210
	v_lshrrev_b32_e32 v9, 6, v210
	s_nop 0
	v_readfirstlane_b32 s17, v9
	v_lshrrev_b32_e32 v9, 4, v8
	v_sub_u32_e32 v10, 0, v9
	v_and_b32_e32 v10, 3, v10
	v_and_b32_e32 v11, 3, v8
	v_xor_b32_e32 v11, v11, v10
	v_lshrrev_b32_e32 v12, 2, v8
	v_lshlrev_b32_e32 v0, 6, v12
	v_lshl_add_u32 v0, v11, 4, v0
	s_lshl_b32 vcc_lo, s17, 11
	v_add_u32_e32 v0, vcc_lo, v0
	v_add_u32_e32 v0, 0x1000, v0
	v_add_u32_e32 v1, 0x0, v0
	v_and_b32_e32 v13, 3, v12
	v_lshl_add_u32 v13, v9, 3, v13
	v_lshlrev_b32_e32 v2, 6, v13
	v_lshl_add_u32 v2, v11, 4, v2
	s_lshl_b32 vcc_lo, s17, 12
	v_add_u32_e32 v2, vcc_lo, v2
	v_add_u32_e32 v2, 0x800, v2
	v_add_u32_e32 v3, 0xfffffd00, v2
	v_add_u32_e32 v4, 0x1000, v2
	v_add_u32_e32 v5, 0xd00, v2
	v_and_b32_e32 v10, 15, v8
	v_lshrrev_b32_e32 v11, 2, v10
	v_sub_u32_e32 v11, 0, v11
	v_and_b32_e32 v11, 3, v11
	v_xor_b32_e32 v11, v9, v11
	v_lshlrev_b32_e32 v6, 6, v10
	v_lshl_add_u32 v6, v11, 4, v6
	s_lshr_b32 vcc_lo, s17, 1
	s_mul_i32 vcc_lo, vcc_lo, 0x3000
	s_and_b32 vcc_hi, s17, 1
	s_mul_i32 vcc_hi, vcc_hi, 0x3000
	s_add_u32 vcc_hi, vcc_hi, 0x800
	v_add_u32_e32 v7, vcc_hi, v6
	v_add_u32_e32 v6, vcc_lo, v6
	s_mul_i32 s16, s17, 0x1800
	v_writelane_b32 v253, s16, 6
	v_writelane_b32 v253, 0, 5
	v_readlane_b32 vcc_lo, v253, 0
	v_readlane_b32 vcc_hi, v253, 1
	s_lshl_b32 s17, s6, 13
	s_nop 1
	s_add_u32 s98, vcc_lo, s17
	s_addc_u32 s99, vcc_hi, 0
	s_sub_u32 s98, s98, 0x1000
	s_subb_u32 s99, s99, 0
	v_readlane_b32 vcc_lo, v253, 2
	v_readlane_b32 vcc_hi, v253, 3
	s_lshl_b32 s17, s7, 14
	s_nop 1
	s_add_u32 s100, vcc_lo, s17
	s_addc_u32 s101, vcc_hi, 0
	s_sub_u32 s100, s100, 0x1000
	s_subb_u32 s101, s101, 0
	s_add_u32 m0, s15, s16
	s_nop 0
	global_load_lds_dwordx4 v0, s[98:99]
	global_load_lds_dwordx4 v1, s[98:99] offset:1024
	global_load_lds_dwordx4 v2, s[100:101] offset:2048
	global_load_lds_dwordx4 v3, s[100:101] offset:3072
	s_add_u32 m0, m0, 0x1000
	s_nop 0
	global_load_lds_dwordx4 v4, s[100:101]
	global_load_lds_dwordx4 v5, s[100:101] offset:1024
	s_add_u32 s98, s98, 0x200000
	s_addc_u32 s99, s99, 0
	s_add_u32 s100, s100, 0x10000
	s_addc_u32 s101, s101, 0
	s_add_u32 s17, s15, 0x6000
	s_cmp_eq_u32 s17, 0x12000
	s_cselect_b32 s17, 0, s17
	s_add_u32 m0, s17, s16
	s_nop 0
	global_load_lds_dwordx4 v0, s[98:99]
	global_load_lds_dwordx4 v1, s[98:99] offset:1024
	global_load_lds_dwordx4 v2, s[100:101] offset:2048
	global_load_lds_dwordx4 v3, s[100:101] offset:3072
	s_add_u32 m0, m0, 0x1000
	s_nop 0
	global_load_lds_dwordx4 v4, s[100:101]
	global_load_lds_dwordx4 v5, s[100:101] offset:1024
	s_add_u32 s98, s98, 0x200000
	s_addc_u32 s99, s99, 0
	s_add_u32 s100, s100, 0x10000
	s_addc_u32 s101, s101, 0
	s_add_u32 s17, s17, 0x6000
	s_cmp_eq_u32 s17, 0x12000
	s_cselect_b32 s17, 0, s17
	s_add_u32 m0, s17, s16
	s_nop 0
	global_load_lds_dwordx4 v0, s[98:99]
	global_load_lds_dwordx4 v1, s[98:99] offset:1024
	global_load_lds_dwordx4 v2, s[100:101] offset:2048
	global_load_lds_dwordx4 v3, s[100:101] offset:3072
	s_add_u32 m0, m0, 0x1000
	s_nop 0
	global_load_lds_dwordx4 v4, s[100:101]
	global_load_lds_dwordx4 v5, s[100:101] offset:1024
	s_add_u32 s98, s98, 0x200000
	s_addc_u32 s99, s99, 0
	s_add_u32 s100, s100, 0x10000
	s_addc_u32 s101, s101, 0
.Lg853_entry:
	v_mov_b32_e32 v254, 0x200000
	v_mov_b32_e32 v255, 0
	s_mov_b32 s14, 0
	s_waitcnt vmcnt(0)
	s_barrier
	v_add_u32_e32 v8, s15, v6
	v_add_u32_e32 v9, s15, v7
	ds_read_b128 v[174:177], v9
	ds_read_b128 v[192:195], v9 offset:1024
	ds_read_b128 v[196:199], v9 offset:2048
	ds_read_b128 v[200:203], v9 offset:3072
	ds_read_b128 v[10:13], v8
	ds_read_b128 v[14:17], v8 offset:1024
	ds_read_b128 v[18:21], v8 offset:6144
	ds_read_b128 v[154:157], v8 offset:7168
	ds_read_b128 v[204:207], v9 offset:6144
	ds_read_b128 v[232:235], v9 offset:7168
	ds_read_b128 v[236:239], v9 offset:8192
	ds_read_b128 v[240:243], v9 offset:9216

; DI f32x4 mfma(bf16x8 a, bf16x8 b, f32x4 c) { return __builtin_amdgcn_mfma_f32_16x16x32_bf16(a, b, c, 0, 0, 0); }
; #define G_LOAD(PA, PB, STEP) do { _Pragma("unroll") for (int i_ = 0; i_ < 2; ++i_) ra[i_] = *(const u32x4*)((PA) + (size_t)(64 * i_) * K + (STEP) * 32); \
;         _Pragma("unroll") for (int i_ = 0; i_ < 4; ++i_) rb[i_] = *(const u32x4*)((PB) + (size_t)(64 * i_) * K + (STEP) * 32); } while (0)
; #define G_STORE(BUF) do { _Pragma("unroll") for (int i_ = 0; i_ < 2; ++i_) *(u32x4*)(sA + (BUF) * 128 * 40 + (lrow + 64 * i_) * 40 + lcc * 8) = ra[i_]; \
;         _Pragma("unroll") for (int i_ = 0; i_ < 4; ++i_) *(u32x4*)(sB + (BUF) * 256 * 40 + (lrow + 64 * i_) * 40 + lcc * 8) = rb[i_]; } while (0)
; template <int EPI> ...
;     ...
;         for (int kt = 0; kt < nk; ++kt) {
;             const int buf = kt & 1;
;             const bf16_t* a_ = sA + buf * 128 * 40 + (wr * 64 + fr) * 40 + fq * 8;
;             const bf16_t* b_ = sB + buf * 256 * 40 + (wc * 128 + fr) * 40 + fq * 8;
;             bf16x8 af[4];
; #pragma unroll
;             for (int i = 0; i < 4; ++i) af[i] = *(const bf16x8*)(a_ + i * 16 * 40);
; #pragma unroll
;             for (int jh = 0; jh < 2; ++jh) {
;                 bf16x8 bfr[4];
; #pragma unroll
;                 for (int j = 0; j < 4; ++j) bfr[j] = *(const bf16x8*)(b_ + (jh * 4 + j) * 16 * 40);
; #pragma unroll
;                 for (int i = 0; i < 4; ++i)
; #pragma unroll
;                     for (int j = 0; j < 4; ++j) acc[i][jh * 4 + j] = mfma(bfr[j], af[i], acc[i][jh * 4 + j]);
;             }
;             G_STORE(buf ^ 1);
;             {
;                 const bool cur = kt + 2 < nk;
;                 const bf16_t* pa = cur ? Ag : An; const bf16_t* pb = cur ? Bg : Bn;
;                 const int st = cur ? kt + 2 : kt + 2 - nk;
;                 G_LOAD(pa, pb, st);
;             }
;             __syncthreads();
;         }
.Lg853_swret:
	s_add_u32 m0, s15, s16
	v_mfma_f32_16x16x32_bf16 v[132:135], v[204:207], v[10:13], v[132:135]
	global_load_lds_dwordx4 v0, s[98:99]
	v_mfma_f32_16x16x32_bf16 v[128:131], v[232:235], v[10:13], v[128:131]
	v_mfma_f32_16x16x32_bf16 v[124:127], v[236:239], v[10:13], v[124:127]
	global_load_lds_dwordx4 v1, s[98:99] offset:1024
	v_mfma_f32_16x16x32_bf16 v[120:123], v[240:243], v[10:13], v[120:123]
	ds_read_b128 v[10:13], v8
	v_mfma_f32_16x16x32_bf16 v[100:103], v[204:207], v[14:17], v[100:103]
	global_load_lds_dwordx4 v2, s[100:101] offset:2048
	v_mfma_f32_16x16x32_bf16 v[96:99], v[232:235], v[14:17], v[96:99]
	v_mfma_f32_16x16x32_bf16 v[92:95], v[236:239], v[14:17], v[92:95]
	global_load_lds_dwordx4 v3, s[100:101] offset:3072
	v_mfma_f32_16x16x32_bf16 v[88:91], v[240:243], v[14:17], v[88:91]
	ds_read_b128 v[14:17], v8 offset:1024
	v_mfma_f32_16x16x32_bf16 v[68:71], v[204:207], v[18:21], v[68:71]
	s_add_u32 m0, m0, 0x1000
	v_mfma_f32_16x16x32_bf16 v[64:67], v[232:235], v[18:21], v[64:67]
	global_load_lds_dwordx4 v4, s[100:101]
	v_mfma_f32_16x16x32_bf16 v[60:63], v[236:239], v[18:21], v[60:63]
	v_mfma_f32_16x16x32_bf16 v[56:59], v[240:243], v[18:21], v[56:59]
	ds_read_b128 v[18:21], v8 offset:6144
	v_mfma_f32_16x16x32_bf16 v[36:39], v[204:207], v[154:157], v[36:39]
	global_load_lds_dwordx4 v5, s[100:101] offset:1024
	v_mfma_f32_16x16x32_bf16 v[32:35], v[232:235], v[154:157], v[32:35]
	v_mfma_f32_16x16x32_bf16 v[28:31], v[236:239], v[154:157], v[28:31]
	v_mfma_f32_16x16x32_bf16 v[24:27], v[240:243], v[154:157], v[24:27]
	ds_read_b128 v[154:157], v8 offset:7168
	ds_read_b128 v[204:207], v9 offset:6144
	ds_read_b128 v[232:235], v9 offset:7168
	ds_read_b128 v[236:239], v9 offset:8192
	ds_read_b128 v[240:243], v9 offset:9216
	s_add_u32 s98, s98, 0x200000
	s_addc_u32 s99, s99, 0
	s_add_u32 s100, s100, 0x10000
	s_addc_u32 s101, s101, 0
	s_add_u32 s15, s15, 0x6000
	s_cmp_eq_u32 s15, 0x12000
	s_cselect_b32 s15, 0, s15
	s_add_u32 s14, s14, 1
	s_cmp_lt_u32 s14, 127
	s_cbranch_scc1 .Lg853_top
	s_waitcnt lgkmcnt(4)
	v_mfma_f32_16x16x32_bf16 v[148:151], v[174:177], v[10:13], v[148:151]
	v_mfma_f32_16x16x32_bf16 v[116:119], v[174:177], v[14:17], v[116:119]
	v_mfma_f32_16x16x32_bf16 v[84:87], v[174:177], v[18:21], v[84:87]
	v_mfma_f32_16x16x32_bf16 v[52:55], v[174:177], v[154:157], v[52:55]
	v_mfma_f32_16x16x32_bf16 v[144:147], v[192:195], v[10:13], v[144:147]
	v_mfma_f32_16x16x32_bf16 v[112:115], v[192:195], v[14:17], v[112:115]
	v_mfma_f32_16x16x32_bf16 v[80:83], v[192:195], v[18:21], v[80:83]
	v_mfma_f32_16x16x32_bf16 v[48:51], v[192:195], v[154:157], v[48:51]
	v_mfma_f32_16x16x32_bf16 v[140:143], v[196:199], v[10:13], v[140:143]
	v_mfma_f32_16x16x32_bf16 v[108:111], v[196:199], v[14:17], v[108:111]
	v_mfma_f32_16x16x32_bf16 v[76:79], v[196:199], v[18:21], v[76:79]
	v_mfma_f32_16x16x32_bf16 v[44:47], v[196:199], v[154:157], v[44:47]
	v_mfma_f32_16x16x32_bf16 v[136:139], v[200:203], v[10:13], v[136:139]
	v_mfma_f32_16x16x32_bf16 v[104:107], v[200:203], v[14:17], v[104:107]
	v_mfma_f32_16x16x32_bf16 v[72:75], v[200:203], v[18:21], v[72:75]
	v_mfma_f32_16x16x32_bf16 v[40:43], v[200:203], v[154:157], v[40:43]
	s_waitcnt vmcnt(6)
	s_waitcnt lgkmcnt(0)
	s_barrier
	s_add_u32 m0, s15, s16
	v_mfma_f32_16x16x32_bf16 v[132:135], v[204:207], v[10:13], v[132:135]
	global_load_lds_dwordx4 v0, s[98:99]
	v_mfma_f32_16x16x32_bf16 v[128:131], v[232:235], v[10:13], v[128:131]
	v_mfma_f32_16x16x32_bf16 v[124:127], v[236:239], v[10:13], v[124:127]
	global_load_lds_dwordx4 v1, s[98:99] offset:1024
	v_mfma_f32_16x16x32_bf16 v[120:123], v[240:243], v[10:13], v[120:123]
	v_mfma_f32_16x16x32_bf16 v[100:103], v[204:207], v[14:17], v[100:103]
	global_load_lds_dwordx4 v2, s[100:101] offset:2048
	v_mfma_f32_16x16x32_bf16 v[96:99], v[232:235], v[14:17], v[96:99]
	v_mfma_f32_16x16x32_bf16 v[92:95], v[236:239], v[14:17], v[92:95]
	global_load_lds_dwordx4 v3, s[100:101] offset:3072
	v_mfma_f32_16x16x32_bf16 v[88:91], v[240:243], v[14:17], v[88:91]
	v_mfma_f32_16x16x32_bf16 v[68:71], v[204:207], v[18:21], v[68:71]
	s_add_u32 m0, m0, 0x1000
	v_mfma_f32_16x16x32_bf16 v[64:67], v[232:235], v[18:21], v[64:67]
	global_load_lds_dwordx4 v4, s[100:101]
	v_mfma_f32_16x16x32_bf16 v[60:63], v[236:239], v[18:21], v[60:63]
	v_mfma_f32_16x16x32_bf16 v[56:59], v[240:243], v[18:21], v[56:59]
	v_mfma_f32_16x16x32_bf16 v[36:39], v[204:207], v[154:157], v[36:39]
	global_load_lds_dwordx4 v5, s[100:101] offset:1024
	v_mfma_f32_16x16x32_bf16 v[32:35], v[232:235], v[154:157], v[32:35]
	v_mfma_f32_16x16x32_bf16 v[28:31], v[236:239], v[154:157], v[28:31]
	v_mfma_f32_16x16x32_bf16 v[24:27], v[240:243], v[154:157], v[24:27]
	s_add_u32 s98, s98, 0x200000
	s_addc_u32 s99, s99, 0
	s_add_u32 s100, s100, 0x10000
	s_addc_u32 s101, s101, 0
	s_add_u32 s15, s15, 0x6000
	s_cmp_eq_u32 s15, 0x12000
	s_cselect_b32 s15, 0, s15
	s_add_u32 s14, s14, 1
	s_branch .Lg853_end
; template <int EPI> ...
;     ...
;         int mt, nt; tile_of(idx, mt, nt);
;         int mtn, ntn; tile_of(idx + nbx < perX ? idx + nbx : idx, mtn, ntn);
;         const bf16_t* Ag = A + (size_t)(mt * 128 + lrow) * K + lcc * 8;
;         const bf16_t* Bg = Bt + (size_t)(nt * 256 + lrowp) * K + lcc * 8;
;         const bf16_t* An = A + (size_t)(mtn * 128 + lrow) * K + lcc * 8;
;         const bf16_t* Bn = Bt + (size_t)(ntn * 256 + lrowp) * K + lcc * 8;
;     ...
;         for (int i = 0; i < 4; ++i) {
;             const int m = mt * 128 + wr * 64 + i * 16 + fr;
;             float rsc = 1.f;
;             if (EPI != 2 && rs_in) rsc = rsqrtf(rs_in[m] * (1.f / DM) + 1e-6f);
;             float sq = 0.f;
; #pragma unroll
;             for (int jp = 0; jp < 4; ++jp) {
;                 const int n0 = nt * 256 + wc * 128 + 32 * jp + 8 * fq;
;                 f32x4 v0 = acc[i][2 * jp] * rsc, v1 = acc[i][2 * jp + 1] * rsc;
;                 if (EPI == 0) {
;                     u32x4 o4; o4[0] = pk2(v0[0], v0[1]); o4[1] = pk2(v0[2], v0[3]); o4[2] = pk2(v1[0], v1[1]); o4[3] = pk2(v1[2], v1[3]);
;                     *(u32x4*)(outb + (size_t)m * Nn + n0) = o4;
;                     if (n0 >= C_BA && n0 < C_BA + 12) *(f32x4*)(side + (size_t)m * 12 + (n0 - C_BA)) = v0;
;                     if (n0 + 4 >= C_BA && n0 + 4 < C_BA + 12) *(f32x4*)(side + (size_t)m * 12 + (n0 + 4 - C_BA)) = v1;
;                 } else if (EPI == 1) {
; #pragma unroll
;                     for (int e = 0; e < 4; ++e) { const float r0 = fmaxf(v0[e], 0.f), r1 = fmaxf(v1[e], 0.f); v0[e] = r0 * r0; v1[e] = r1 * r1; }
;                     u32x4 o4; o4[0] = pk2(v0[0], v0[1]); o4[1] = pk2(v0[2], v0[3]); o4[2] = pk2(v1[0], v1[1]); o4[3] = pk2(v1[2], v1[3]);
;                     *(u32x4*)(outb + (size_t)m * Nn + n0) = o4;
;                 } else {
;                     *(f32x4*)(xout + (size_t)m * Nn + n0) = v0;
;                     *(f32x4*)(xout + (size_t)m * Nn + n0 + 4) = v1;
;                     if (hb) {
;                         const f32x4 g0 = *(const f32x4*)(gn + n0), g1 = *(const f32x4*)(gn + n0 + 4);
;                         u32x4 o4; o4[0] = pk2(v0[0] * g0[0], v0[1] * g0[1]); o4[1] = pk2(v0[2] * g0[2], v0[3] * g0[3]);
;                         o4[2] = pk2(v1[0] * g1[0], v1[1] * g1[1]); o4[3] = pk2(v1[2] * g1[2], v1[3] * g1[3]);
;                         *(u32x4*)(hb + (size_t)m * Nn + n0) = o4;
.Lg853_sw:
	v_readlane_b32 vcc_lo, v253, 0
	v_readlane_b32 vcc_hi, v253, 1
	s_lshl_b32 s17, s11, 13
	s_nop 1
	s_add_u32 s98, vcc_lo, s17
	s_addc_u32 s99, vcc_hi, 0
	s_sub_u32 s98, s98, 0x1000
	s_subb_u32 s99, s99, 0
	v_readlane_b32 vcc_lo, v253, 2
	v_readlane_b32 vcc_hi, v253, 3
	s_lshl_b32 s17, s13, 14
	s_nop 1
	s_add_u32 s100, vcc_lo, s17
	s_addc_u32 s101, vcc_hi, 0
	s_sub_u32 s100, s100, 0x1000
	s_subb_u32 s101, s101, 0
	s_branch .Lg853_swret
.Lg853_end:
	s_setprio 0
	v_writelane_b32 v253, s15, 4
	v_readlane_b32 s52, v251, 34
	v_readlane_b32 s53, v251, 35
	v_readlane_b32 s54, v251, 36
	v_readlane_b32 s55, v251, 37
	v_readlane_b32 s56, v251, 38
	v_readlane_b32 s57, v251, 39
	v_readlane_b32 s58, v251, 40
	v_readlane_b32 s59, v251, 41
	v_readlane_b32 s60, v251, 42
	v_readlane_b32 s61, v251, 43
	v_readlane_b32 s62, v251, 44
	v_readlane_b32 s63, v251, 45
	v_readlane_b32 s64, v251, 46
	v_readlane_b32 s65, v251, 47
	v_readlane_b32 s66, v251, 48
	v_readlane_b32 s67, v251, 49
	v_or_b32_e32 v185, s10, v184
	v_lshl_add_u64 v[164:165], s[56:57], 0, v[164:165]
	v_readlane_b32 s52, v250, 51
	v_readlane_b32 s6, v250, 42
	v_lshlrev_b64 v[174:175], 6, v[170:171]
	v_readlane_b32 s54, v250, 53
	v_readlane_b32 s55, v250, 54
	v_lshlrev_b32_e32 v188, 2, v185
	v_readlane_b32 s7, v250, 43
	v_lshl_add_u64 v[174:175], s[54:55], 0, v[174:175]
	v_lshl_add_u64 v[176:177], v[164:165], 0, v[188:189]
	s_and_b64 vcc, exec, s[6:7]
	v_lshrrev_b32_e32 v164, 5, v185
	v_lshlrev_b32_e32 v164, 20, v164
	v_and_or_b32 v164, v185, 31, v164
	v_lshlrev_b32_e32 v164, 1, v164
	v_readlane_b32 s53, v250, 52
	v_readlane_b32 s56, v250, 55
	v_readlane_b32 s57, v250, 56
	v_readlane_b32 s58, v250, 57
	v_readlane_b32 s59, v250, 58
	v_readlane_b32 s60, v250, 59
	v_readlane_b32 s61, v250, 60
	v_readlane_b32 s62, v250, 61
	v_readlane_b32 s63, v250, 62
	v_readlane_b32 s64, v250, 63
	v_readlane_b32 s65, v249, 0
	v_readlane_b32 s66, v249, 1
	v_readlane_b32 s67, v249, 2
	global_store_dwordx4 v[176:177], v[148:151], off
	global_store_dwordx4 v[176:177], v[144:147], off offset:16
	s_cbranch_vccz .LBB0_856
	v_readlane_b32 s6, v250, 40
	v_readlane_b32 s7, v250, 41
	s_nop 4
	global_load_dwordx4 v[192:195], v188, s[6:7] offset:16
	global_load_dwordx4 v[196:199], v188, s[6:7]
	v_mov_b32_e32 v165, v189
	s_waitcnt vmcnt(1)
	v_pk_mul_f32 v[192:193], v[144:145], v[192:193]
	s_waitcnt vmcnt(0)
	v_pk_mul_f32 v[196:197], v[148:149], v[196:197]
	v_pk_mul_f32 v[148:149], v[148:149], v[148:149]
	v_pk_mul_f32 v[186:187], v[150:151], v[198:199]
	v_pk_mul_f32 v[150:151], v[150:151], v[150:151]
	v_add_f32_e32 v148, v148, v149
	v_add_f32_e32 v148, v150, v148
	v_pk_mul_f32 v[144:145], v[144:145], v[144:145]
	v_add_f32_e32 v148, v151, v148
	v_add_f32_e32 v144, v144, v148
	v_cvt_pk_bf16_f32 v196, v196, v197
	v_cvt_pk_bf16_f32 v197, v186, v187
	v_pk_mul_f32 v[186:187], v[146:147], v[194:195]
	v_pk_mul_f32 v[146:147], v[146:147], v[146:147]
	v_add_f32_e32 v144, v145, v144
	v_add_f32_e32 v144, v146, v144
	v_cvt_pk_bf16_f32 v198, v192, v193
	v_cvt_pk_bf16_f32 v199, v186, v187
	v_lshl_add_u64 v[186:187], v[174:175], 0, v[164:165]
	v_add_f32_e32 v145, v147, v144
	global_store_dwordx4 v[186:187], v[196:199], off
	s_branch .LBB0_857

; DI unsigned pk2(float lo, float hi) { f32x2 v = {lo, hi}; bf16x2_t r = __builtin_convertvector(v, bf16x2_t); return __builtin_bit_cast(unsigned, r); }
; template <int EPI> ...
;     ...
;             for (int jp = 0; jp < 4; ++jp) {
;                 const int n0 = nt * 256 + wc * 128 + 32 * jp + 8 * fq;
;                 f32x4 v0 = acc[i][2 * jp] * rsc, v1 = acc[i][2 * jp + 1] * rsc;
;                 if (EPI == 0) {
;                     u32x4 o4; o4[0] = pk2(v0[0], v0[1]); o4[1] = pk2(v0[2], v0[3]); o4[2] = pk2(v1[0], v1[1]); o4[3] = pk2(v1[2], v1[3]);
;                     *(u32x4*)(outb + (size_t)m * Nn + n0) = o4;
;                     if (n0 >= C_BA && n0 < C_BA + 12) *(f32x4*)(side + (size_t)m * 12 + (n0 - C_BA)) = v0;
;                     if (n0 + 4 >= C_BA && n0 + 4 < C_BA + 12) *(f32x4*)(side + (size_t)m * 12 + (n0 + 4 - C_BA)) = v1;
;                 } else if (EPI == 1) {
; #pragma unroll
;                     for (int e = 0; e < 4; ++e) { const float r0 = fmaxf(v0[e], 0.f), r1 = fmaxf(v1[e], 0.f); v0[e] = r0 * r0; v1[e] = r1 * r1; }
;                     u32x4 o4; o4[0] = pk2(v0[0], v0[1]); o4[1] = pk2(v0[2], v0[3]); o4[2] = pk2(v1[0], v1[1]); o4[3] = pk2(v1[2], v1[3]);
;                     *(u32x4*)(outb + (size_t)m * Nn + n0) = o4;
;                 } else {
;                     *(f32x4*)(xout + (size_t)m * Nn + n0) = v0;
;                     *(f32x4*)(xout + (size_t)m * Nn + n0 + 4) = v1;
;                     if (hb) {
;                         const f32x4 g0 = *(const f32x4*)(gn + n0), g1 = *(const f32x4*)(gn + n0 + 4);
;                         u32x4 o4; o4[0] = pk2(v0[0] * g0[0], v0[1] * g0[1]); o4[1] = pk2(v0[2] * g0[2], v0[3] * g0[3]);
;                         o4[2] = pk2(v1[0] * g1[0], v1[1] * g1[1]); o4[3] = pk2(v1[2] * g1[2], v1[3] * g1[3]);
;                         *(u32x4*)(hb + (size_t)m * Nn + n0) = o4;
;                         sq += v0[0] * v0[0] + v0[1] * v0[1] + v0[2] * v0[2] + v0[3] * v0[3] + v1[0] * v1[0] + v1[1] * v1[1] + v1[2] * v1[2] + v1[3] * v1[3];
;                     }
;                 }
;             }
;             if (EPI == 2 && hb) {
;                 sq += __shfl_xor(sq, 16); sq += __shfl_xor(sq, 32);
;                 if (fq == 0) atomicAdd(ssq_out + m, sq);
;             }
.LBB0_857:
	v_readlane_b32 s10, v250, 42
	v_readlane_b32 s11, v250, 43
	v_or_b32_e32 v144, 32, v185
	s_andn2_b64 vcc, exec, s[10:11]
	v_cndmask_b32_e64 v146, 0, 1, s[10:11]
	v_cmp_ne_u32_e64 s[6:7], 1, v146
	v_lshlrev_b32_e32 v144, 2, v144
	global_store_dwordx4 v[176:177], v[140:143], off offset:128
	global_store_dwordx4 v[176:177], v[136:139], off offset:144
	s_cbranch_vccnz .LBB0_859
	v_readlane_b32 s10, v250, 40
	v_readlane_b32 s11, v250, 41
	s_nop 4
	global_load_dwordx4 v[146:149], v144, s[10:11] offset:16
	global_load_dwordx4 v[192:195], v144, s[10:11]
	v_mov_b32_e32 v165, v189
	s_waitcnt vmcnt(1)
	v_pk_mul_f32 v[146:147], v[136:137], v[146:147]
	s_waitcnt vmcnt(0)
	v_pk_mul_f32 v[186:187], v[140:141], v[192:193]
	v_pk_mul_f32 v[140:141], v[140:141], v[140:141]
	v_pk_mul_f32 v[150:151], v[142:143], v[194:195]
	v_pk_mul_f32 v[142:143], v[142:143], v[142:143]
	v_add_f32_e32 v140, v140, v141
	v_add_f32_e32 v140, v142, v140
	v_pk_mul_f32 v[136:137], v[136:137], v[136:137]
	v_add_f32_e32 v140, v143, v140
	v_add_f32_e32 v136, v136, v140
	v_pk_mul_f32 v[148:149], v[138:139], v[148:149]
	v_pk_mul_f32 v[138:139], v[138:139], v[138:139]
	v_add_f32_e32 v136, v137, v136
	v_add_f32_e32 v136, v138, v136
	v_add_f32_e32 v136, v139, v136
	v_cvt_pk_bf16_f32 v192, v186, v187
	v_cvt_pk_bf16_f32 v193, v150, v151
	v_cvt_pk_bf16_f32 v194, v146, v147
	v_cvt_pk_bf16_f32 v195, v148, v149
	v_lshl_add_u64 v[146:147], v[174:175], 0, v[164:165]
	v_add_f32_e32 v145, v136, v145
	v_lshl_add_u64 v[146:147], v[146:147], 0, v[254:255]
	global_store_dwordx4 v[146:147], v[192:195], off
.LBB0_859:
	s_nop 0
	v_or_b32_e32 v136, 64, v185
	s_and_b64 vcc, exec, s[6:7]
	v_lshlrev_b32_e32 v136, 2, v136
	global_store_dwordx4 v[176:177], v[132:135], off offset:256
	global_store_dwordx4 v[176:177], v[128:131], off offset:272
	s_cbranch_vccnz .LBB0_861
	v_readlane_b32 s10, v250, 40
	v_readlane_b32 s11, v250, 41
	s_nop 4
	global_load_dwordx4 v[138:141], v136, s[10:11] offset:16
	global_load_dwordx4 v[146:149], v136, s[10:11]
	v_mov_b32_e32 v165, v189
	s_waitcnt vmcnt(1)
	v_pk_mul_f32 v[138:139], v[128:129], v[138:139]
	s_waitcnt vmcnt(0)
	v_pk_mul_f32 v[146:147], v[132:133], v[146:147]
	v_pk_mul_f32 v[132:133], v[132:133], v[132:133]
	v_pk_mul_f32 v[142:143], v[134:135], v[148:149]
	v_pk_mul_f32 v[134:135], v[134:135], v[134:135]
	v_add_f32_e32 v132, v132, v133
	v_add_f32_e32 v132, v134, v132
	v_pk_mul_f32 v[128:129], v[128:129], v[128:129]
	v_add_f32_e32 v132, v135, v132
	v_add_f32_e32 v128, v128, v132
	v_pk_mul_f32 v[140:141], v[130:131], v[140:141]
	v_pk_mul_f32 v[130:131], v[130:131], v[130:131]
	v_add_f32_e32 v128, v129, v128
	v_add_f32_e32 v128, v130, v128
	v_add_f32_e32 v128, v131, v128
	v_cvt_pk_bf16_f32 v146, v146, v147
	v_cvt_pk_bf16_f32 v147, v142, v143
	v_cvt_pk_bf16_f32 v148, v138, v139
	v_cvt_pk_bf16_f32 v149, v140, v141
	v_lshl_add_u64 v[138:139], v[174:175], 0, v[164:165]
	v_add_f32_e32 v145, v128, v145
	v_lshl_add_u64 v[138:139], v[138:139], 0, v[254:255]
	v_lshl_add_u64 v[138:139], v[138:139], 0, v[254:255]
	global_store_dwordx4 v[138:139], v[146:149], off
.LBB0_861:
	s_nop 0
	v_or_b32_e32 v128, 0x60, v185
	s_and_b64 vcc, exec, s[6:7]
	v_lshlrev_b32_e32 v128, 2, v128
	global_store_dwordx4 v[176:177], v[124:127], off offset:384
	global_store_dwordx4 v[176:177], v[120:123], off offset:400
	s_cbranch_vccnz .LBB0_865
	v_readlane_b32 s10, v250, 40
	v_readlane_b32 s11, v250, 41
	s_nop 4
	global_load_dwordx4 v[130:133], v128, s[10:11] offset:16
	global_load_dwordx4 v[138:141], v128, s[10:11]
	v_mov_b32_e32 v165, v189
	s_waitcnt vmcnt(1)
	v_pk_mul_f32 v[130:131], v[120:121], v[130:131]
	s_waitcnt vmcnt(0)
	v_pk_mul_f32 v[138:139], v[124:125], v[138:139]
	v_mul_f32_e32 v125, v125, v125
	v_fmac_f32_e32 v125, v124, v124
	v_fmac_f32_e32 v125, v126, v126
	v_fmac_f32_e32 v125, v127, v127
	v_fmac_f32_e32 v125, v120, v120
	v_fmac_f32_e32 v125, v121, v121
	v_fmac_f32_e32 v125, v122, v122
	v_fmac_f32_e32 v125, v123, v123
	v_add_f32_e32 v120, v125, v145
	ds_bpermute_b32 v121, v230, v120
	v_pk_mul_f32 v[134:135], v[126:127], v[140:141]
	v_pk_mul_f32 v[132:133], v[122:123], v[132:133]
	v_cvt_pk_bf16_f32 v138, v138, v139
	v_cvt_pk_bf16_f32 v139, v134, v135
	s_waitcnt lgkmcnt(0)
	v_add_f32_e32 v120, v120, v121
	ds_bpermute_b32 v121, v191, v120
	v_cvt_pk_bf16_f32 v140, v130, v131
	v_cvt_pk_bf16_f32 v141, v132, v133
	v_lshl_add_u64 v[130:131], v[174:175], 0, v[164:165]
	v_lshl_add_u64 v[130:131], v[130:131], 0, v[254:255]
	v_lshl_add_u64 v[130:131], v[130:131], 0, v[254:255]
	v_lshl_add_u64 v[130:131], v[130:131], 0, v[254:255]
	global_store_dwordx4 v[130:131], v[138:141], off
	s_and_saveexec_b64 s[10:11], s[4:5]
	s_cbranch_execz .LBB0_864
	v_lshl_add_u64 v[122:123], v[170:171], 2, s[70:71]
	s_waitcnt lgkmcnt(0)
	v_add_f32_e32 v120, v120, v121
	global_atomic_add_f32 v[122:123], v120, off

; template <int EPI> ...
;     ...
;         for (int i = 0; i < 4; ++i) {
;             const int m = mt * 128 + wr * 64 + i * 16 + fr;
;             float rsc = 1.f;
;             if (EPI != 2 && rs_in) rsc = rsqrtf(rs_in[m] * (1.f / DM) + 1e-6f);
;             float sq = 0.f;
; #pragma unroll
;             for (int jp = 0; jp < 4; ++jp) {
;                 const int n0 = nt * 256 + wc * 128 + 32 * jp + 8 * fq;
;                 f32x4 v0 = acc[i][2 * jp] * rsc, v1 = acc[i][2 * jp + 1] * rsc;
;                 if (EPI == 0) {
;                     u32x4 o4; o4[0] = pk2(v0[0], v0[1]); o4[1] = pk2(v0[2], v0[3]); o4[2] = pk2(v1[0], v1[1]); o4[3] = pk2(v1[2], v1[3]);
;                     *(u32x4*)(outb + (size_t)m * Nn + n0) = o4;
;                     if (n0 >= C_BA && n0 < C_BA + 12) *(f32x4*)(side + (size_t)m * 12 + (n0 - C_BA)) = v0;
;                     if (n0 + 4 >= C_BA && n0 + 4 < C_BA + 12) *(f32x4*)(side + (size_t)m * 12 + (n0 + 4 - C_BA)) = v1;
;                 } else if (EPI == 1) {
; #pragma unroll
;                     for (int e = 0; e < 4; ++e) { const float r0 = fmaxf(v0[e], 0.f), r1 = fmaxf(v1[e], 0.f); v0[e] = r0 * r0; v1[e] = r1 * r1; }
;                     u32x4 o4; o4[0] = pk2(v0[0], v0[1]); o4[1] = pk2(v0[2], v0[3]); o4[2] = pk2(v1[0], v1[1]); o4[3] = pk2(v1[2], v1[3]);
;                     *(u32x4*)(outb + (size_t)m * Nn + n0) = o4;
;                 } else {
;                     *(f32x4*)(xout + (size_t)m * Nn + n0) = v0;
;                     *(f32x4*)(xout + (size_t)m * Nn + n0 + 4) = v1;
;                     if (hb) {
;                         const f32x4 g0 = *(const f32x4*)(gn + n0), g1 = *(const f32x4*)(gn + n0 + 4);
;                         u32x4 o4; o4[0] = pk2(v0[0] * g0[0], v0[1] * g0[1]); o4[1] = pk2(v0[2] * g0[2], v0[3] * g0[3]);
;                         o4[2] = pk2(v1[0] * g1[0], v1[1] * g1[1]); o4[3] = pk2(v1[2] * g1[2], v1[3] * g1[3]);
;                         *(u32x4*)(hb + (size_t)m * Nn + n0) = o4;
;                         sq += v0[0] * v0[0] + v0[1] * v0[1] + v0[2] * v0[2] + v0[3] * v0[3] + v1[0] * v1[0] + v1[1] * v1[1] + v1[2] * v1[2] + v1[3] * v1[3];
;                     }
;                 }
;             }
;             if (EPI == 2 && hb) {
;                 sq += __shfl_xor(sq, 16); sq += __shfl_xor(sq, 32);
;                 if (fq == 0) atomicAdd(ssq_out + m, sq);
;             }
.LBB0_865:
	v_readlane_b32 s52, v251, 34
	v_readlane_b32 s56, v251, 38
	v_readlane_b32 s57, v251, 39
	s_and_b64 vcc, exec, s[6:7]
	v_readlane_b32 s53, v251, 35
	s_waitcnt lgkmcnt(0)
	v_lshl_add_u64 v[120:121], s[56:57], 0, v[172:173]
	v_lshl_add_u64 v[120:121], v[120:121], 0, v[188:189]
	v_readlane_b32 s54, v251, 36
	v_readlane_b32 s55, v251, 37
	v_readlane_b32 s58, v251, 40
	v_readlane_b32 s59, v251, 41
	v_readlane_b32 s60, v251, 42
	v_readlane_b32 s61, v251, 43
	v_readlane_b32 s62, v251, 44
	v_readlane_b32 s63, v251, 45
	v_readlane_b32 s64, v251, 46
	v_readlane_b32 s65, v251, 47
	v_readlane_b32 s66, v251, 48
	v_readlane_b32 s67, v251, 49
	global_store_dwordx4 v[120:121], v[116:119], off
	global_store_dwordx4 v[120:121], v[112:115], off offset:16
	s_cbranch_vccnz .LBB0_879
	v_readlane_b32 s52, v250, 51
	v_readlane_b32 s10, v250, 40
	v_lshlrev_b64 v[122:123], 5, v[166:167]
	v_readlane_b32 s54, v250, 53
	v_readlane_b32 s55, v250, 54
	v_readlane_b32 s11, v250, 41
	v_mov_b32_e32 v165, v189
	v_lshl_add_u64 v[126:127], v[122:123], 1, s[54:55]
	s_nop 2
	global_load_dwordx4 v[122:125], v188, s[10:11] offset:16
	global_load_dwordx4 v[130:133], v188, s[10:11]
	v_readlane_b32 s53, v250, 52
	v_readlane_b32 s56, v250, 55
	v_readlane_b32 s57, v250, 56
	v_readlane_b32 s58, v250, 57
	v_readlane_b32 s59, v250, 58
	v_readlane_b32 s60, v250, 59
	v_readlane_b32 s61, v250, 60
	v_readlane_b32 s62, v250, 61
	v_readlane_b32 s63, v250, 62
	v_readlane_b32 s64, v250, 63
	v_readlane_b32 s65, v249, 0
	v_readlane_b32 s66, v249, 1
	v_readlane_b32 s67, v249, 2
	s_waitcnt vmcnt(1)
	v_pk_mul_f32 v[124:125], v[114:115], v[124:125]
	s_waitcnt vmcnt(0)
	v_pk_mul_f32 v[132:133], v[118:119], v[132:133]
	v_pk_mul_f32 v[130:131], v[116:117], v[130:131]
	v_pk_mul_f32 v[122:123], v[112:113], v[122:123]
	v_cvt_pk_bf16_f32 v130, v130, v131
	v_cvt_pk_bf16_f32 v131, v132, v133
	v_cvt_pk_bf16_f32 v133, v124, v125
	v_mul_f32_e32 v124, v117, v117
	v_fmac_f32_e32 v124, v116, v116
	v_fmac_f32_e32 v124, v118, v118
	v_fmac_f32_e32 v124, v119, v119
	v_fmac_f32_e32 v124, v112, v112
	v_cvt_pk_bf16_f32 v132, v122, v123
	v_lshl_add_u64 v[122:123], v[126:127], 0, v[164:165]
	v_fmac_f32_e32 v124, v113, v113
	global_store_dwordx4 v[122:123], v[130:133], off
	v_fmac_f32_e32 v124, v114, v114
	global_store_dwordx4 v[120:121], v[108:111], off offset:128
	global_store_dwordx4 v[120:121], v[104:107], off offset:144
	v_fmac_f32_e32 v124, v115, v115
	global_load_dwordx4 v[112:115], v144, s[10:11] offset:16
	global_load_dwordx4 v[116:119], v144, s[10:11]
	s_waitcnt vmcnt(1)
	v_pk_mul_f32 v[112:113], v[104:105], v[112:113]
	s_waitcnt vmcnt(0)
	v_pk_mul_f32 v[118:119], v[110:111], v[118:119]
	v_pk_mul_f32 v[116:117], v[108:109], v[116:117]
	v_pk_mul_f32 v[114:115], v[106:107], v[114:115]
	v_cvt_pk_bf16_f32 v116, v116, v117
	v_cvt_pk_bf16_f32 v117, v118, v119
	v_cvt_pk_bf16_f32 v118, v112, v113
	v_mul_f32_e32 v112, v109, v109
	v_fmac_f32_e32 v112, v108, v108
	v_fmac_f32_e32 v112, v110, v110
	v_fmac_f32_e32 v112, v111, v111
	v_fmac_f32_e32 v112, v104, v104
	v_fmac_f32_e32 v112, v105, v105
	v_cvt_pk_bf16_f32 v119, v114, v115
	v_fmac_f32_e32 v112, v106, v106
	v_lshl_add_u64 v[122:123], v[122:123], 0, v[254:255]
	global_store_dwordx4 v[122:123], v[116:119], off
	v_fmac_f32_e32 v112, v107, v107
	global_store_dwordx4 v[120:121], v[100:103], off offset:256
	global_store_dwordx4 v[120:121], v[96:99], off offset:272
	v_add_f32_e32 v124, v124, v112
	global_load_dwordx4 v[112:115], v136, s[10:11] offset:16
	global_load_dwordx4 v[116:119], v136, s[10:11]
	s_waitcnt vmcnt(1)
	v_pk_mul_f32 v[112:113], v[96:97], v[112:113]
	s_waitcnt vmcnt(0)
	v_pk_mul_f32 v[118:119], v[102:103], v[118:119]
	v_pk_mul_f32 v[116:117], v[100:101], v[116:117]
	v_pk_mul_f32 v[114:115], v[98:99], v[114:115]
	v_cvt_pk_bf16_f32 v116, v116, v117
	v_cvt_pk_bf16_f32 v117, v118, v119
	v_cvt_pk_bf16_f32 v118, v112, v113
	v_mul_f32_e32 v112, v101, v101
	v_fmac_f32_e32 v112, v100, v100
	v_fmac_f32_e32 v112, v102, v102
	v_fmac_f32_e32 v112, v103, v103
	v_fmac_f32_e32 v112, v96, v96
	v_fmac_f32_e32 v112, v97, v97
	v_cvt_pk_bf16_f32 v119, v114, v115
	v_fmac_f32_e32 v112, v98, v98
	v_lshl_add_u64 v[122:123], v[122:123], 0, v[254:255]
	global_store_dwordx4 v[122:123], v[116:119], off
	v_fmac_f32_e32 v112, v99, v99
	global_store_dwordx4 v[120:121], v[92:95], off offset:384
	global_store_dwordx4 v[120:121], v[88:91], off offset:400
	v_add_f32_e32 v124, v124, v112
	global_load_dwordx4 v[112:115], v128, s[10:11] offset:16
	global_load_dwordx4 v[116:119], v128, s[10:11]
	s_waitcnt vmcnt(1)
	v_pk_mul_f32 v[112:113], v[88:89], v[112:113]
	s_waitcnt vmcnt(0)
	v_pk_mul_f32 v[118:119], v[94:95], v[118:119]
	v_pk_mul_f32 v[116:117], v[92:93], v[116:117]
	v_pk_mul_f32 v[114:115], v[90:91], v[114:115]
	v_cvt_pk_bf16_f32 v116, v116, v117
	v_cvt_pk_bf16_f32 v117, v118, v119
	v_cvt_pk_bf16_f32 v118, v112, v113
	v_mul_f32_e32 v112, v93, v93
	v_fmac_f32_e32 v112, v92, v92
	v_fmac_f32_e32 v112, v94, v94
	v_fmac_f32_e32 v112, v95, v95
	v_fmac_f32_e32 v112, v88, v88
	v_fmac_f32_e32 v112, v89, v89
	v_fmac_f32_e32 v112, v90, v90
	v_fmac_f32_e32 v112, v91, v91
	v_add_f32_e32 v112, v124, v112
	ds_bpermute_b32 v113, v230, v112
	v_cvt_pk_bf16_f32 v119, v114, v115
	v_lshl_add_u64 v[122:123], v[122:123], 0, v[254:255]
	global_store_dwordx4 v[122:123], v[116:119], off
	s_waitcnt lgkmcnt(0)
	v_add_f32_e32 v112, v112, v113
	ds_bpermute_b32 v113, v191, v112
	s_and_saveexec_b64 s[10:11], s[4:5]
	s_cbranch_execz .LBB0_868
	v_lshl_add_u64 v[114:115], v[166:167], 2, s[70:71]
	s_waitcnt lgkmcnt(0)
	v_add_f32_e32 v112, v112, v113
	global_atomic_add_f32 v[114:115], v112, off

; template <int EPI> ...
;     ...
;         for (int i = 0; i < 4; ++i) {
;             const int m = mt * 128 + wr * 64 + i * 16 + fr;
;             float rsc = 1.f;
;             if (EPI != 2 && rs_in) rsc = rsqrtf(rs_in[m] * (1.f / DM) + 1e-6f);
;             float sq = 0.f;
; #pragma unroll
;             for (int jp = 0; jp < 4; ++jp) {
;                 const int n0 = nt * 256 + wc * 128 + 32 * jp + 8 * fq;
;                 f32x4 v0 = acc[i][2 * jp] * rsc, v1 = acc[i][2 * jp + 1] * rsc;
;                 if (EPI == 0) {
;                     u32x4 o4; o4[0] = pk2(v0[0], v0[1]); o4[1] = pk2(v0[2], v0[3]); o4[2] = pk2(v1[0], v1[1]); o4[3] = pk2(v1[2], v1[3]);
;                     *(u32x4*)(outb + (size_t)m * Nn + n0) = o4;
;                     if (n0 >= C_BA && n0 < C_BA + 12) *(f32x4*)(side + (size_t)m * 12 + (n0 - C_BA)) = v0;
;                     if (n0 + 4 >= C_BA && n0 + 4 < C_BA + 12) *(f32x4*)(side + (size_t)m * 12 + (n0 + 4 - C_BA)) = v1;
;                 } else if (EPI == 1) {
; #pragma unroll
;                     for (int e = 0; e < 4; ++e) { const float r0 = fmaxf(v0[e], 0.f), r1 = fmaxf(v1[e], 0.f); v0[e] = r0 * r0; v1[e] = r1 * r1; }
;                     u32x4 o4; o4[0] = pk2(v0[0], v0[1]); o4[1] = pk2(v0[2], v0[3]); o4[2] = pk2(v1[0], v1[1]); o4[3] = pk2(v1[2], v1[3]);
;                     *(u32x4*)(outb + (size_t)m * Nn + n0) = o4;
;                 } else {
;                     *(f32x4*)(xout + (size_t)m * Nn + n0) = v0;
;                     *(f32x4*)(xout + (size_t)m * Nn + n0 + 4) = v1;
;                     if (hb) {
;                         const f32x4 g0 = *(const f32x4*)(gn + n0), g1 = *(const f32x4*)(gn + n0 + 4);
;                         u32x4 o4; o4[0] = pk2(v0[0] * g0[0], v0[1] * g0[1]); o4[1] = pk2(v0[2] * g0[2], v0[3] * g0[3]);
;                         o4[2] = pk2(v1[0] * g1[0], v1[1] * g1[1]); o4[3] = pk2(v1[2] * g1[2], v1[3] * g1[3]);
;                         *(u32x4*)(hb + (size_t)m * Nn + n0) = o4;
;                         sq += v0[0] * v0[0] + v0[1] * v0[1] + v0[2] * v0[2] + v0[3] * v0[3] + v1[0] * v1[0] + v1[1] * v1[1] + v1[2] * v1[2] + v1[3] * v1[3];
;                     }
;                 }
;             }
;             if (EPI == 2 && hb) {
;                 sq += __shfl_xor(sq, 16); sq += __shfl_xor(sq, 32);
;                 if (fq == 0) atomicAdd(ssq_out + m, sq);
;             }
.LBB0_870:
	v_readlane_b32 s52, v251, 34
	v_readlane_b32 s56, v251, 38
	v_readlane_b32 s57, v251, 39
	s_and_b64 vcc, exec, s[6:7]
	v_readlane_b32 s53, v251, 35
	v_lshl_add_u64 v[88:89], s[56:57], 0, v[168:169]
	v_lshl_add_u64 v[88:89], v[88:89], 0, v[188:189]
	v_readlane_b32 s54, v251, 36
	v_readlane_b32 s55, v251, 37
	v_readlane_b32 s58, v251, 40
	v_readlane_b32 s59, v251, 41
	v_readlane_b32 s60, v251, 42
	v_readlane_b32 s61, v251, 43
	v_readlane_b32 s62, v251, 44
	v_readlane_b32 s63, v251, 45
	v_readlane_b32 s64, v251, 46
	v_readlane_b32 s65, v251, 47
	v_readlane_b32 s66, v251, 48
	v_readlane_b32 s67, v251, 49
	global_store_dwordx4 v[88:89], v[84:87], off
	global_store_dwordx4 v[88:89], v[80:83], off offset:16
	s_cbranch_vccnz .LBB0_880
	v_readlane_b32 s52, v250, 51
	v_readlane_b32 s10, v250, 40
	v_lshlrev_b64 v[90:91], 5, v[162:163]
	v_readlane_b32 s54, v250, 53
	v_readlane_b32 s55, v250, 54
	v_readlane_b32 s11, v250, 41
	v_mov_b32_e32 v165, v189
	v_lshl_add_u64 v[98:99], v[90:91], 1, s[54:55]
	s_nop 2
	global_load_dwordx4 v[90:93], v188, s[10:11] offset:16
	global_load_dwordx4 v[94:97], v188, s[10:11]
	v_readlane_b32 s53, v250, 52
	v_readlane_b32 s56, v250, 55
	v_readlane_b32 s57, v250, 56
	v_readlane_b32 s58, v250, 57
	v_readlane_b32 s59, v250, 58
	v_readlane_b32 s60, v250, 59
	v_readlane_b32 s61, v250, 60
	v_readlane_b32 s62, v250, 61
	v_readlane_b32 s63, v250, 62
	v_readlane_b32 s64, v250, 63
	v_readlane_b32 s65, v249, 0
	v_readlane_b32 s66, v249, 1
	v_readlane_b32 s67, v249, 2
	s_waitcnt vmcnt(1)
	v_pk_mul_f32 v[92:93], v[82:83], v[92:93]
	s_waitcnt vmcnt(0)
	v_pk_mul_f32 v[96:97], v[86:87], v[96:97]
	v_pk_mul_f32 v[94:95], v[84:85], v[94:95]
	v_pk_mul_f32 v[90:91], v[80:81], v[90:91]
	v_cvt_pk_bf16_f32 v94, v94, v95
	v_cvt_pk_bf16_f32 v95, v96, v97
	v_cvt_pk_bf16_f32 v97, v92, v93
	v_mul_f32_e32 v92, v85, v85
	v_fmac_f32_e32 v92, v84, v84
	v_fmac_f32_e32 v92, v86, v86
	v_fmac_f32_e32 v92, v87, v87
	v_fmac_f32_e32 v92, v80, v80
	v_cvt_pk_bf16_f32 v96, v90, v91
	v_lshl_add_u64 v[90:91], v[98:99], 0, v[164:165]
	v_fmac_f32_e32 v92, v81, v81
	global_store_dwordx4 v[90:91], v[94:97], off
	v_fmac_f32_e32 v92, v82, v82
	global_store_dwordx4 v[88:89], v[76:79], off offset:128
	global_store_dwordx4 v[88:89], v[72:75], off offset:144
	v_fmac_f32_e32 v92, v83, v83
	global_load_dwordx4 v[80:83], v144, s[10:11] offset:16
	global_load_dwordx4 v[84:87], v144, s[10:11]
	s_waitcnt vmcnt(1)
	v_pk_mul_f32 v[80:81], v[72:73], v[80:81]
	s_waitcnt vmcnt(0)
	v_pk_mul_f32 v[86:87], v[78:79], v[86:87]
	v_pk_mul_f32 v[84:85], v[76:77], v[84:85]
	v_pk_mul_f32 v[82:83], v[74:75], v[82:83]
	v_cvt_pk_bf16_f32 v84, v84, v85
	v_cvt_pk_bf16_f32 v85, v86, v87
	v_cvt_pk_bf16_f32 v86, v80, v81
	v_mul_f32_e32 v80, v77, v77
	v_fmac_f32_e32 v80, v76, v76
	v_fmac_f32_e32 v80, v78, v78
	v_fmac_f32_e32 v80, v79, v79
	v_fmac_f32_e32 v80, v72, v72
	v_fmac_f32_e32 v80, v73, v73
	v_cvt_pk_bf16_f32 v87, v82, v83
	v_fmac_f32_e32 v80, v74, v74
	v_lshl_add_u64 v[90:91], v[90:91], 0, v[254:255]
	global_store_dwordx4 v[90:91], v[84:87], off
	v_fmac_f32_e32 v80, v75, v75
	global_store_dwordx4 v[88:89], v[68:71], off offset:256
	global_store_dwordx4 v[88:89], v[64:67], off offset:272
	v_add_f32_e32 v92, v92, v80
	global_load_dwordx4 v[80:83], v136, s[10:11] offset:16
	global_load_dwordx4 v[84:87], v136, s[10:11]
	s_waitcnt vmcnt(1)
	v_pk_mul_f32 v[80:81], v[64:65], v[80:81]
	s_waitcnt vmcnt(0)
	v_pk_mul_f32 v[86:87], v[70:71], v[86:87]
	v_pk_mul_f32 v[84:85], v[68:69], v[84:85]
	v_pk_mul_f32 v[82:83], v[66:67], v[82:83]
	v_cvt_pk_bf16_f32 v84, v84, v85
	v_cvt_pk_bf16_f32 v85, v86, v87
	v_cvt_pk_bf16_f32 v86, v80, v81
	v_mul_f32_e32 v80, v69, v69
	v_fmac_f32_e32 v80, v68, v68
	v_fmac_f32_e32 v80, v70, v70
	v_fmac_f32_e32 v80, v71, v71
	v_fmac_f32_e32 v80, v64, v64
	v_fmac_f32_e32 v80, v65, v65
	v_cvt_pk_bf16_f32 v87, v82, v83
	v_fmac_f32_e32 v80, v66, v66
	v_lshl_add_u64 v[90:91], v[90:91], 0, v[254:255]
	global_store_dwordx4 v[90:91], v[84:87], off
	v_fmac_f32_e32 v80, v67, v67
	global_store_dwordx4 v[88:89], v[60:63], off offset:384
	global_store_dwordx4 v[88:89], v[56:59], off offset:400
	v_add_f32_e32 v92, v92, v80
	global_load_dwordx4 v[80:83], v128, s[10:11] offset:16
	global_load_dwordx4 v[84:87], v128, s[10:11]
	s_waitcnt vmcnt(1)
	v_pk_mul_f32 v[80:81], v[56:57], v[80:81]
	s_waitcnt vmcnt(0)
	v_pk_mul_f32 v[86:87], v[62:63], v[86:87]
	v_pk_mul_f32 v[84:85], v[60:61], v[84:85]
	v_pk_mul_f32 v[82:83], v[58:59], v[82:83]
	v_cvt_pk_bf16_f32 v84, v84, v85
	v_cvt_pk_bf16_f32 v85, v86, v87
	v_cvt_pk_bf16_f32 v86, v80, v81
	v_mul_f32_e32 v80, v61, v61
	v_fmac_f32_e32 v80, v60, v60
	v_fmac_f32_e32 v80, v62, v62
	v_fmac_f32_e32 v80, v63, v63
	v_fmac_f32_e32 v80, v56, v56
	v_fmac_f32_e32 v80, v57, v57
	v_fmac_f32_e32 v80, v58, v58
	v_fmac_f32_e32 v80, v59, v59
	v_add_f32_e32 v80, v92, v80
	ds_bpermute_b32 v81, v230, v80
	v_cvt_pk_bf16_f32 v87, v82, v83
	v_lshl_add_u64 v[90:91], v[90:91], 0, v[254:255]
	global_store_dwordx4 v[90:91], v[84:87], off
	s_waitcnt lgkmcnt(0)
	v_add_f32_e32 v80, v80, v81
	ds_bpermute_b32 v81, v191, v80
	s_and_saveexec_b64 s[10:11], s[4:5]
	s_cbranch_execz .LBB0_873
	v_lshl_add_u64 v[82:83], v[162:163], 2, s[70:71]
	s_waitcnt lgkmcnt(0)
	v_add_f32_e32 v80, v80, v81
	global_atomic_add_f32 v[82:83], v80, off

; template <int EPI> ...
;     ...
;         for (int i = 0; i < 4; ++i) {
;             const int m = mt * 128 + wr * 64 + i * 16 + fr;
;             float rsc = 1.f;
;             if (EPI != 2 && rs_in) rsc = rsqrtf(rs_in[m] * (1.f / DM) + 1e-6f);
;             float sq = 0.f;
; #pragma unroll
;             for (int jp = 0; jp < 4; ++jp) {
;                 const int n0 = nt * 256 + wc * 128 + 32 * jp + 8 * fq;
;                 f32x4 v0 = acc[i][2 * jp] * rsc, v1 = acc[i][2 * jp + 1] * rsc;
;                 if (EPI == 0) {
;                     u32x4 o4; o4[0] = pk2(v0[0], v0[1]); o4[1] = pk2(v0[2], v0[3]); o4[2] = pk2(v1[0], v1[1]); o4[3] = pk2(v1[2], v1[3]);
;                     *(u32x4*)(outb + (size_t)m * Nn + n0) = o4;
;                     if (n0 >= C_BA && n0 < C_BA + 12) *(f32x4*)(side + (size_t)m * 12 + (n0 - C_BA)) = v0;
;                     if (n0 + 4 >= C_BA && n0 + 4 < C_BA + 12) *(f32x4*)(side + (size_t)m * 12 + (n0 + 4 - C_BA)) = v1;
;                 } else if (EPI == 1) {
; #pragma unroll
;                     for (int e = 0; e < 4; ++e) { const float r0 = fmaxf(v0[e], 0.f), r1 = fmaxf(v1[e], 0.f); v0[e] = r0 * r0; v1[e] = r1 * r1; }
;                     u32x4 o4; o4[0] = pk2(v0[0], v0[1]); o4[1] = pk2(v0[2], v0[3]); o4[2] = pk2(v1[0], v1[1]); o4[3] = pk2(v1[2], v1[3]);
;                     *(u32x4*)(outb + (size_t)m * Nn + n0) = o4;
;                 } else {
;                     *(f32x4*)(xout + (size_t)m * Nn + n0) = v0;
;                     *(f32x4*)(xout + (size_t)m * Nn + n0 + 4) = v1;
;                     if (hb) {
;                         const f32x4 g0 = *(const f32x4*)(gn + n0), g1 = *(const f32x4*)(gn + n0 + 4);
;                         u32x4 o4; o4[0] = pk2(v0[0] * g0[0], v0[1] * g0[1]); o4[1] = pk2(v0[2] * g0[2], v0[3] * g0[3]);
;                         o4[2] = pk2(v1[0] * g1[0], v1[1] * g1[1]); o4[3] = pk2(v1[2] * g1[2], v1[3] * g1[3]);
;                         *(u32x4*)(hb + (size_t)m * Nn + n0) = o4;
;                         sq += v0[0] * v0[0] + v0[1] * v0[1] + v0[2] * v0[2] + v0[3] * v0[3] + v1[0] * v1[0] + v1[1] * v1[1] + v1[2] * v1[2] + v1[3] * v1[3];
;                     }
;                 }
;             }
;             if (EPI == 2 && hb) {
;                 sq += __shfl_xor(sq, 16); sq += __shfl_xor(sq, 32);
;                 if (fq == 0) atomicAdd(ssq_out + m, sq);
;             }
.LBB0_875:
	v_readlane_b32 s52, v251, 34
	v_readlane_b32 s56, v251, 38
	v_readlane_b32 s57, v251, 39
	s_and_b64 vcc, exec, s[6:7]
	v_readlane_b32 s53, v251, 35
	v_lshl_add_u64 v[56:57], s[56:57], 0, v[160:161]
	v_lshl_add_u64 v[56:57], v[56:57], 0, v[188:189]
	v_readlane_b32 s54, v251, 36
	v_readlane_b32 s55, v251, 37
	v_readlane_b32 s58, v251, 40
	v_readlane_b32 s59, v251, 41
	v_readlane_b32 s60, v251, 42
	v_readlane_b32 s61, v251, 43
	v_readlane_b32 s62, v251, 44
	v_readlane_b32 s63, v251, 45
	v_readlane_b32 s64, v251, 46
	v_readlane_b32 s65, v251, 47
	v_readlane_b32 s66, v251, 48
	v_readlane_b32 s67, v251, 49
	global_store_dwordx4 v[56:57], v[52:55], off
	global_store_dwordx4 v[56:57], v[48:51], off offset:16
	s_cbranch_vccnz .LBB0_881
	v_readlane_b32 s6, v250, 40
	v_readlane_b32 s7, v250, 41
	s_nop 4
	global_load_dwordx4 v[58:61], v188, s[6:7]
	global_load_dwordx4 v[62:65], v188, s[6:7] offset:16
	v_readlane_b32 s52, v250, 51
	v_lshlrev_b64 v[66:67], 5, v[158:159]
	v_readlane_b32 s54, v250, 53
	v_readlane_b32 s55, v250, 54
	v_mov_b32_e32 v165, v189
	v_mul_f32_e32 v68, v45, v45
	v_lshl_add_u64 v[66:67], v[66:67], 1, s[54:55]
	v_lshl_add_u64 v[66:67], v[66:67], 0, v[164:165]
	v_mul_f32_e32 v69, v37, v37
	v_fmac_f32_e32 v68, v44, v44
	v_mul_f32_e32 v70, v29, v29
	v_fmac_f32_e32 v69, v36, v36
	v_fmac_f32_e32 v68, v46, v46
	v_fmac_f32_e32 v70, v28, v28
	v_fmac_f32_e32 v69, v38, v38
	v_fmac_f32_e32 v68, v47, v47
	v_fmac_f32_e32 v70, v30, v30
	v_fmac_f32_e32 v69, v39, v39
	v_fmac_f32_e32 v68, v40, v40
	v_fmac_f32_e32 v70, v31, v31
	v_fmac_f32_e32 v69, v32, v32
	v_fmac_f32_e32 v68, v41, v41
	v_fmac_f32_e32 v70, v24, v24
	v_fmac_f32_e32 v69, v33, v33
	v_fmac_f32_e32 v68, v42, v42
	v_fmac_f32_e32 v70, v25, v25
	v_fmac_f32_e32 v69, v34, v34
	v_fmac_f32_e32 v68, v43, v43
	v_fmac_f32_e32 v70, v26, v26
	v_fmac_f32_e32 v69, v35, v35
	v_fmac_f32_e32 v70, v27, v27
	v_readlane_b32 s53, v250, 52
	v_readlane_b32 s56, v250, 55
	v_readlane_b32 s57, v250, 56
	v_readlane_b32 s58, v250, 57
	v_readlane_b32 s59, v250, 58
	v_readlane_b32 s60, v250, 59
	v_readlane_b32 s61, v250, 60
	v_readlane_b32 s62, v250, 61
	v_readlane_b32 s63, v250, 62
	v_readlane_b32 s64, v250, 63
	v_readlane_b32 s65, v249, 0
	v_readlane_b32 s66, v249, 1
	v_readlane_b32 s67, v249, 2
	s_waitcnt vmcnt(1)
	v_pk_mul_f32 v[60:61], v[54:55], v[60:61]
	v_pk_mul_f32 v[58:59], v[52:53], v[58:59]
	s_waitcnt vmcnt(0)
	v_pk_mul_f32 v[64:65], v[50:51], v[64:65]
	v_pk_mul_f32 v[62:63], v[48:49], v[62:63]
	v_cvt_pk_bf16_f32 v58, v58, v59
	v_cvt_pk_bf16_f32 v59, v60, v61
	v_cvt_pk_bf16_f32 v60, v62, v63
	v_cvt_pk_bf16_f32 v61, v64, v65
	global_store_dwordx4 v[66:67], v[58:61], off
	global_store_dwordx4 v[56:57], v[44:47], off offset:128
	global_store_dwordx4 v[56:57], v[40:43], off offset:144
	global_load_dwordx4 v[58:61], v144, s[6:7]
	s_nop 0
	global_load_dwordx4 v[62:65], v144, s[6:7] offset:16
	v_mul_f32_e32 v53, v53, v53
	v_fmac_f32_e32 v53, v52, v52
	v_fmac_f32_e32 v53, v54, v54
	v_fmac_f32_e32 v53, v55, v55
	v_fmac_f32_e32 v53, v48, v48
	v_fmac_f32_e32 v53, v49, v49
	v_fmac_f32_e32 v53, v50, v50
	v_fmac_f32_e32 v53, v51, v51
	v_add_f32_e32 v48, v53, v68
	v_add_f32_e32 v48, v48, v69
	v_add_f32_e32 v48, v48, v70
	ds_bpermute_b32 v49, v230, v48
	s_waitcnt lgkmcnt(0)
	v_add_f32_e32 v48, v48, v49
	ds_bpermute_b32 v49, v191, v48
	s_waitcnt vmcnt(1)
	v_pk_mul_f32 v[60:61], v[46:47], v[60:61]
	v_pk_mul_f32 v[58:59], v[44:45], v[58:59]
	s_waitcnt vmcnt(0)
	v_pk_mul_f32 v[64:65], v[42:43], v[64:65]
	v_pk_mul_f32 v[62:63], v[40:41], v[62:63]
	v_cvt_pk_bf16_f32 v58, v58, v59
	v_cvt_pk_bf16_f32 v59, v60, v61
	v_cvt_pk_bf16_f32 v60, v62, v63
	v_cvt_pk_bf16_f32 v61, v64, v65
	v_lshl_add_u64 v[66:67], v[66:67], 0, v[254:255]
	global_store_dwordx4 v[66:67], v[58:61], off
	global_store_dwordx4 v[56:57], v[36:39], off offset:256
	global_store_dwordx4 v[56:57], v[32:35], off offset:272
	global_load_dwordx4 v[58:61], v136, s[6:7]
	s_nop 0
	global_load_dwordx4 v[62:65], v136, s[6:7] offset:16
	s_waitcnt vmcnt(1)
	v_pk_mul_f32 v[60:61], v[38:39], v[60:61]
	v_pk_mul_f32 v[58:59], v[36:37], v[58:59]
	s_waitcnt vmcnt(0)
	v_pk_mul_f32 v[64:65], v[34:35], v[64:65]
	v_pk_mul_f32 v[62:63], v[32:33], v[62:63]
	v_cvt_pk_bf16_f32 v58, v58, v59
	v_cvt_pk_bf16_f32 v59, v60, v61
	v_cvt_pk_bf16_f32 v60, v62, v63
	v_cvt_pk_bf16_f32 v61, v64, v65
	v_lshl_add_u64 v[66:67], v[66:67], 0, v[254:255]
	global_store_dwordx4 v[66:67], v[58:61], off
	global_store_dwordx4 v[56:57], v[28:31], off offset:384
	global_store_dwordx4 v[56:57], v[24:27], off offset:400
	global_load_dwordx4 v[58:61], v128, s[6:7]
	s_nop 0
	global_load_dwordx4 v[62:65], v128, s[6:7] offset:16
	s_waitcnt vmcnt(1)
	v_pk_mul_f32 v[52:53], v[30:31], v[60:61]
	v_pk_mul_f32 v[50:51], v[28:29], v[58:59]
	s_waitcnt vmcnt(0)
	v_pk_mul_f32 v[54:55], v[26:27], v[64:65]
	v_pk_mul_f32 v[58:59], v[24:25], v[62:63]
	v_cvt_pk_bf16_f32 v50, v50, v51
	v_cvt_pk_bf16_f32 v51, v52, v53
	v_cvt_pk_bf16_f32 v52, v58, v59
	v_cvt_pk_bf16_f32 v53, v54, v55
	v_lshl_add_u64 v[66:67], v[66:67], 0, v[254:255]
	global_store_dwordx4 v[66:67], v[50:53], off
	s_and_saveexec_b64 s[6:7], s[4:5]
	s_cbranch_execz .LBB0_878
	v_lshl_add_u64 v[50:51], v[158:159], 2, s[70:71]
	s_waitcnt lgkmcnt(0)
	v_add_f32_e32 v48, v48, v49
	global_atomic_add_f32 v[50:51], v48, off
